# plus: drop IEEE-canonicalizing v_max before relu in indexer scoring (bit-identical for non-sNaN), 256B-align K-loop heads
# speedup vs baseline: 1.0232x; 1.0062x over previous
; template <class Epi, class Sched, bool ALIGN_EPI = false, bool SP2 = false>
; __device__ __forceinline__ void gemm_phase(PG8_LAS unsigned char* lds, const Gemm g, const Sched& S, const Epi& E) {
;     ...
;         const bool has_next = S.next(ui + 1, nxt);
;         const char* nA = has_next ? (const char*)g.A + (size_t)nxt.pm * tstep : cA; const char* nB = has_next ? (const char*)g.Bt + (size_t)nxt.pn * tstep : cB;
;         for (int t = 0; t < nt; t += 2) {
;             const bool last = (t == nt - 2);
;             const char* a1 = cA + (size_t)(t + 1) * kstep;
;             const char* a2 = last ? nA : cA + (size_t)(t + 2) * kstep; const char* b2 = last ? nB : cB + (size_t)(t + 2) * kstep;
;             const char* a3 = a2 + kstep; const char* b3 = b2 + kstep;
;     ...
; #pragma unroll
;         for (int a = 0; a < 2; ++a)
; #pragma unroll
;             for (int b = 0; b < 2; ++b)
; #pragma unroll
;                 for (int m = 0; m < 4; ++m)
; #pragma unroll
;                     for (int n = 0; n < 2; ++n) acc[a][b][m][n] = (f32x4){0.f, 0.f, 0.f, 0.f};
.LBB0_212:
	s_ashr_i32 s31, s30, 31
	s_lshl_b64 s[14:15], s[30:31], 20
	s_add_u32 s34, s57, s14
	s_addc_u32 s35, s58, s15
	s_and_b64 s[14:15], s[8:9], exec
	s_cselect_b32 s16, s35, s13
	s_cselect_b32 s17, s34, s12
	s_ashr_i32 s29, s28, 31
	s_lshl_b64 s[14:15], s[28:29], 20
	s_add_u32 s36, s59, s14
	s_addc_u32 s37, s60, s15
	s_and_b64 s[14:15], s[8:9], exec
	s_cselect_b32 s29, s37, s11
	s_cselect_b32 s31, s36, s10
	s_add_u32 s38, s10, 0x100
	s_addc_u32 s39, s11, 0
	s_add_u32 s10, s12, 0x80080
	v_mov_b32_e32 v2, 0
	s_addc_u32 s11, s13, 0
	s_mov_b32 s40, -2
	v_mov_b32_e32 v3, v2
	v_mov_b32_e32 v4, v2
	v_mov_b32_e32 v5, v2
	v_mov_b32_e32 v6, v2
	v_mov_b32_e32 v7, v2
	v_mov_b32_e32 v8, v2
	v_mov_b32_e32 v9, v2
	v_mov_b32_e32 v26, v2
	v_mov_b32_e32 v27, v2
	v_mov_b32_e32 v28, v2
	v_mov_b32_e32 v29, v2
	v_mov_b32_e32 v30, v2
	v_mov_b32_e32 v31, v2
	v_mov_b32_e32 v32, v2
	v_mov_b32_e32 v33, v2
	v_mov_b32_e32 v42, v2
	v_mov_b32_e32 v43, v2
	v_mov_b32_e32 v44, v2
	v_mov_b32_e32 v45, v2
	v_mov_b32_e32 v46, v2
	v_mov_b32_e32 v47, v2
	v_mov_b32_e32 v48, v2
	v_mov_b32_e32 v49, v2
	v_mov_b32_e32 v58, v2
	v_mov_b32_e32 v59, v2
	v_mov_b32_e32 v60, v2
	v_mov_b32_e32 v61, v2
	v_mov_b32_e32 v62, v2
	v_mov_b32_e32 v63, v2
	v_mov_b32_e32 v64, v2
	v_mov_b32_e32 v65, v2
	v_mov_b32_e32 v10, v2
	v_mov_b32_e32 v11, v2
	v_mov_b32_e32 v12, v2
	v_mov_b32_e32 v13, v2
	v_mov_b32_e32 v14, v2
	v_mov_b32_e32 v15, v2
	v_mov_b32_e32 v16, v2
	v_mov_b32_e32 v17, v2
	v_mov_b32_e32 v34, v2
	v_mov_b32_e32 v35, v2
	v_mov_b32_e32 v36, v2
	v_mov_b32_e32 v37, v2
	v_mov_b32_e32 v38, v2
	v_mov_b32_e32 v39, v2
	v_mov_b32_e32 v40, v2
	v_mov_b32_e32 v41, v2
	v_mov_b32_e32 v50, v2
	v_mov_b32_e32 v51, v2
	v_mov_b32_e32 v52, v2
	v_mov_b32_e32 v53, v2
	v_mov_b32_e32 v54, v2
	v_mov_b32_e32 v55, v2
	v_mov_b32_e32 v56, v2
	v_mov_b32_e32 v57, v2
	v_mov_b32_e32 v66, v2
	v_mov_b32_e32 v67, v2
	v_mov_b32_e32 v68, v2
	v_mov_b32_e32 v69, v2
	v_mov_b32_e32 v70, v2
	v_mov_b32_e32 v71, v2
	v_mov_b32_e32 v72, v2
	v_mov_b32_e32 v73, v2
	v_mov_b32_e32 v74, v2
	v_mov_b32_e32 v75, v2
	v_mov_b32_e32 v76, v2
	v_mov_b32_e32 v77, v2
	v_mov_b32_e32 v78, v2
	v_mov_b32_e32 v79, v2
	v_mov_b32_e32 v80, v2
	v_mov_b32_e32 v81, v2
	v_mov_b32_e32 v90, v2
	v_mov_b32_e32 v91, v2
	v_mov_b32_e32 v92, v2
	v_mov_b32_e32 v93, v2
	v_mov_b32_e32 v94, v2
	v_mov_b32_e32 v95, v2
	v_mov_b32_e32 v96, v2
	v_mov_b32_e32 v97, v2
	v_mov_b32_e32 v106, v2
	v_mov_b32_e32 v107, v2
	v_mov_b32_e32 v108, v2
	v_mov_b32_e32 v109, v2
	v_mov_b32_e32 v110, v2
	v_mov_b32_e32 v111, v2
	v_mov_b32_e32 v112, v2
	v_mov_b32_e32 v113, v2
	v_mov_b32_e32 v122, v2
	v_mov_b32_e32 v123, v2
	v_mov_b32_e32 v124, v2
	v_mov_b32_e32 v125, v2
	v_mov_b32_e32 v126, v2
	v_mov_b32_e32 v127, v2
	v_mov_b32_e32 v128, v2
	v_mov_b32_e32 v129, v2
	v_mov_b32_e32 v82, v2
	v_mov_b32_e32 v83, v2
	v_mov_b32_e32 v84, v2
	v_mov_b32_e32 v85, v2
	v_mov_b32_e32 v86, v2
	v_mov_b32_e32 v87, v2
	v_mov_b32_e32 v88, v2
	v_mov_b32_e32 v89, v2
	v_mov_b32_e32 v98, v2
	v_mov_b32_e32 v99, v2
	v_mov_b32_e32 v100, v2
	v_mov_b32_e32 v101, v2
	v_mov_b32_e32 v102, v2
	v_mov_b32_e32 v103, v2
	v_mov_b32_e32 v104, v2
	v_mov_b32_e32 v105, v2
	v_mov_b32_e32 v114, v2
	v_mov_b32_e32 v115, v2
	v_mov_b32_e32 v116, v2
	v_mov_b32_e32 v117, v2
	v_mov_b32_e32 v118, v2
	v_mov_b32_e32 v119, v2
	v_mov_b32_e32 v120, v2
	v_mov_b32_e32 v121, v2
	v_mov_b32_e32 v130, v2
	v_mov_b32_e32 v131, v2
	v_mov_b32_e32 v132, v2
	v_mov_b32_e32 v133, v2
	v_mov_b32_e32 v134, v2
	v_mov_b32_e32 v135, v2
	v_mov_b32_e32 v136, v2
	v_mov_b32_e32 v137, v2
	s_mov_b64 s[46:47], 0x80
	s_waitcnt vmcnt(0)
	.p2align 8

; #define LAS __attribute__((address_space(3)))
; __device__ __forceinline__ void att_unit(LAS unsigned char* lds, const bf16* P, const bf16* AKV, const bf16* IKC, bf16* ACAT, const float* aqg, const float* ssq_ak, const float* ssq_ik, int b, int qg, int tid) {
;     ...
;     const int lane = tid & 63, w = __builtin_amdgcn_readfirstlane(tid >> 6), fr = lane & 15, fq = lane >> 4;
;     LAS unsigned char* IK = lds;
;     LAS unsigned char* Vst = lds + w * 9216;
;     LAS int* list0 = (LAS int*)(lds + 73728 + w * 6144);
;     const int L = 64 * ((qg >> 2) + 1);
;     const bf16* AKVb = AKV + (size_t)(b * SEQ) * 256;
;     const bf16* IKb = IKC + (size_t)(b * SEQ) * 128;
;     const GAS f32x4* sak = (const GAS f32x4*)ssq_ak + b * SEQ;
;     const size_t tok0 = (size_t)(b * SEQ + 16 * qg + 2 * w);
;     int cnt;
;     if (L <= 256) {
;         cnt = L;
; #pragma unroll
;         for (int r = 0; r < 4; ++r) { const int i = 64 * r + lane; const int kx = i < L ? i : 0; const f32x4 q4 = sak[kx]; const float rk = rsqrtf(((q4.x + q4.y) + (q4.z + q4.w)) * (1.f / 128.f) + EPS);
;             list0[i] = kx; ((LAS float*)list0)[256 + i] = rk; list0[512 + i] = kx; ((LAS float*)list0)[768 + i] = rk;
;             const int tp = ((i >> 5) * 4 + (i & 3)) * 8 + ((i >> 2) & 7); ((LAS unsigned*)list0)[1024 + tp] = (unsigned)kx * 512u; ((LAS unsigned*)list0)[1280 + tp] = (unsigned)kx * 512u; }
;     } else {
;         cnt = 256;
;         typedef float f32x2 __attribute__((ext_vector_type(2)));
;         const GAS f32x2* sik = (const GAS f32x2*)ssq_ik + b * SEQ;
;         bf16x8 Qi[2][2]; float wv[2][4];
; #pragma unroll
;         for (int q = 0; q < 2; ++q) {
; #pragma unroll
;             for (int kk = 0; kk < 2; ++kk) Qi[q][kk] = *(const GAS bf16x8*)(P + (tok0 + q) * NP + C_IQ + fr * 64 + 32 * kk + 8 * fq);
;             const u32x2 ww = *(const GAS u32x2*)(IKC + (tok0 + q) * 128 + 64 + 4 * fq); wv[q][0] = bflo(ww.x); wv[q][1] = bfhi(ww.x); wv[q][2] = bflo(ww.y); wv[q][3] = bfhi(ww.y);
;         }
;         unsigned uk[2][32];
;         const int ntile = (L + 255) >> 8;
;         const int skey = tid >> 3, spart = tid & 7;
;         const bf16* sb = IKb + (size_t)skey * 128 + spart * 8;
;         u32x4 ikr[4]; f32x2 rik[4];
; #pragma unroll
;         for (int i = 0; i < 4; ++i) { ikr[i] = *(const GAS u32x4*)(sb + (size_t)(64 * i) * 128); rik[i] = sik[64 * i + lane]; }
; #pragma unroll
.LBB0_593:
	v_readlane_b32 s0, v254, 13
	v_readlane_b32 s70, v254, 19
	v_readlane_b32 s2, v254, 9
	v_readlane_b32 s76, v254, 11
	v_readlane_b32 s8, v254, 5
	v_readlane_b32 s6, v254, 7
	v_readlane_b32 s4, v254, 3
	v_readlane_b32 s1, v254, 14
	v_readlane_b32 s71, v254, 20
	v_readlane_b32 s3, v254, 10
	v_readlane_b32 s77, v254, 12
	s_waitcnt vmcnt(0)
	v_mov_b32_e32 v18, v220
	v_readlane_b32 s9, v254, 6
	v_readlane_b32 s7, v254, 8
	v_readlane_b32 s5, v254, 4
	s_mov_b32 s11, 0x8c00
	v_writelane_b32 v254, s8, 43
	v_mov_b64_e32 v[154:155], s[4:5]
	v_readfirstlane_b32 s4, v18
	s_ashr_i32 s74, s4, 6
	v_writelane_b32 v254, s9, 44
	s_mul_i32 s4, s74, 0x1800
	s_lshl_b32 s5, s26, 4
	s_add_i32 s33, s4, 0
	s_and_b32 s4, s5, 0xffffffc0
	v_readlane_b32 s9, v254, 38
	s_add_i32 s33, s33, 0x12000
	s_add_i32 s81, s4, 64
	s_lshl_b32 s8, s9, 4
	s_add_u32 s72, s6, s8
	s_addc_u32 s73, s7, 0
	s_lshl_b32 s6, s74, 1
	s_add_i32 s6, s6, s9
	s_add_i32 s5, s6, s5
	s_ashr_i32 s6, s5, 31
	v_and_b32_e32 v124, 63, v18
	v_and_b32_e32 v125, 15, v18
	v_bfe_u32 v126, v18, 4, 2
	v_writelane_b32 v254, s5, 45
	s_cmpk_gt_i32 s81, 0x100
	s_movk_i32 s10, 0x4000
	v_mov_b32_e32 v6, s81
	v_mov_b32_e32 v156, s5
	v_writelane_b32 v254, s6, 46
	v_mov_b32_e32 v157, s6
	s_cselect_b64 s[6:7], -1, 0
	v_lshlrev_b32_e32 v50, 7, v125
	v_lshlrev_b32_e32 v52, 3, v124
	v_lshlrev_b32_e32 v2, 3, v126
	v_and_b32_e32 v51, 48, v18
	s_and_saveexec_b64 s[8:9], s[6:7]
	s_xor_b64 s[82:83], exec, s[8:9]
	s_cbranch_execz .LBB0_1007
	v_mov_b64_e32 v[20:21], s[2:3]
	v_readlane_b32 s2, v254, 41
	v_mov_b64_e32 v[2:3], s[0:1]
	v_readlane_b32 s3, v254, 42
	v_mov_b32_e32 v51, v1
	v_lshlrev_b32_e32 v4, 4, v126
	v_lshl_add_u64 v[22:23], v[2:3], 0, s[2:3]
	v_readlane_b32 s2, v254, 45
	v_mov_b32_e32 v5, v1
	v_lshlrev_b64 v[24:25], 8, v[156:157]
	v_mov_b32_e32 v2, s2
	v_mad_i64_i32 v[2:3], s[2:3], v2, s11, v[154:155]
	v_lshl_add_u64 v[2:3], v[2:3], 0, v[50:51]
	v_lshl_add_u64 v[2:3], v[2:3], 0, v[4:5]
	s_mov_b64 s[2:3], 0x6200
	v_add_co_u32_e32 v6, vcc, 0x6000, v2
	v_lshl_add_u64 v[4:5], v[2:3], 0, s[2:3]
	s_nop 0
	v_addc_co_u32_e32 v7, vcc, 0, v3, vcc
	global_load_dwordx4 v[14:17], v[6:7], off offset:512
	global_load_dwordx4 v[10:13], v[4:5], off offset:64
	v_lshl_add_u64 v[4:5], s[0:1], 0, v[24:25]
	v_or_b32_e32 v24, 0x100, v24
	s_mov_b64 s[2:3], 0xee00
	v_lshl_add_u64 v[24:25], s[0:1], 0, v[24:25]
	v_readlane_b32 s0, v253, 34
	v_lshlrev_b32_e32 v0, 3, v126
	v_lshl_add_u64 v[6:7], v[2:3], 0, s[2:3]
	v_add_co_u32_e32 v2, vcc, 0xe000, v2
	v_readlane_b32 s1, v253, 35
	v_readlane_b32 s0, v254, 38
	v_ashrrev_i32_e32 v32, 3, v18
	v_lshl_add_u64 v[4:5], v[4:5], 0, v[0:1]
	v_addc_co_u32_e32 v3, vcc, 0, v3, vcc
	v_lshl_add_u64 v[24:25], v[24:25], 0, v[0:1]
	s_mov_b32 s3, s1
	s_lshl_b32 s2, s0, 3
	v_ashrrev_i32_e32 v33, 31, v32
	global_load_dwordx2 v[40:41], v[4:5], off offset:128
	s_nop 0
	global_load_dwordx4 v[2:5], v[2:3], off offset:3584
	s_nop 0
	global_load_dwordx4 v[6:9], v[6:7], off offset:64
	v_lshlrev_b32_e32 v19, 4, v18
	global_load_dwordx2 v[38:39], v[24:25], off offset:128
	v_lshl_add_u64 v[24:25], v[20:21], 0, s[2:3]
	v_lshlrev_b64 v[20:21], 8, v[32:33]
	v_lshl_add_u64 v[20:21], v[22:23], 0, v[20:21]
	v_and_b32_e32 v54, 0x70, v19
	v_mov_b32_e32 v55, v1
	v_lshl_add_u64 v[66:67], v[20:21], 0, v[54:55]
	v_mov_b32_e32 v53, v1
	v_writelane_b32 v253, s0, 34
	v_lshl_add_u64 v[88:89], v[24:25], 0, v[52:53]
	v_add_co_u32_e32 v24, vcc, s10, v66
	v_writelane_b32 v253, s1, 35
	s_nop 0
	v_addc_co_u32_e32 v25, vcc, 0, v67, vcc
	s_mov_b32 s0, 0x8000
	v_add_co_u32_e32 v28, vcc, s0, v66
	s_mov_b32 s0, 0xc000
	s_nop 0
	v_addc_co_u32_e32 v29, vcc, 0, v67, vcc
	v_add_co_u32_e32 v36, vcc, s0, v66
	global_load_dwordx4 v[20:23], v[66:67], off
	s_nop 0
	v_addc_co_u32_e32 v37, vcc, 0, v67, vcc
	global_load_dwordx2 v[42:43], v[88:89], off
	s_nop 0
	global_load_dwordx4 v[24:27], v[24:25], off
	s_nop 0
	global_load_dwordx2 v[44:45], v[88:89], off offset:512
	s_nop 0
	global_load_dwordx4 v[28:31], v[28:29], off
	s_nop 0
	global_load_dwordx2 v[34:35], v[88:89], off offset:1024
	global_load_dwordx4 v[46:49], v[36:37], off
	s_nop 0
	global_load_dwordx2 v[36:37], v[88:89], off offset:1536
	s_movk_i32 s0, 0x90
	v_mul_lo_u32 v32, v32, s0
	v_and_b32_e32 v51, 48, v18
	v_and_b32_e32 v18, 16, v18
	s_mov_b32 s0, 0x10000
	v_add_u32_e32 v19, 0, v54
	v_cmp_eq_u32_e64 s[6:7], 0, v18
	v_add_co_u32_e32 v18, vcc, s0, v66
	v_add_u32_e32 v129, v19, v32
	s_nop 0
	v_addc_co_u32_e32 v19, vcc, 0, v67, vcc
	s_mov_b32 s0, 0x14000
	s_mov_b32 s2, 0x3c800000
	v_mov_b32_e32 v132, s4
	s_mov_b32 s18, 0x800000
	s_waitcnt vmcnt(7)
	ds_write_b128 v129, v[20:23]
	s_waitcnt vmcnt(5)
	ds_write_b128 v129, v[24:27] offset:9216
	s_waitcnt vmcnt(3)
	ds_write_b128 v129, v[28:31] offset:18432
	s_waitcnt vmcnt(1)
	ds_write_b128 v129, v[46:49] offset:27648
	v_add_co_u32_e32 v22, vcc, s0, v66
	s_mov_b32 s0, 0x18000
	s_nop 0
	v_addc_co_u32_e32 v23, vcc, 0, v67, vcc
	v_add_co_u32_e32 v26, vcc, s0, v66
	s_mov_b32 s0, 0x1c000
	s_nop 0
	v_addc_co_u32_e32 v27, vcc, 0, v67, vcc
	v_add_co_u32_e32 v30, vcc, s0, v66
	v_mul_u32_u24_e32 v48, 0x90, v125
	s_nop 0
	v_addc_co_u32_e32 v31, vcc, 0, v67, vcc
	v_add3_u32 v131, 0, v51, v48
	s_waitcnt lgkmcnt(0)
	s_barrier
; #define LAS __attribute__((address_space(3)))
; #define GAS __attribute__((address_space(1)))
; __device__ __forceinline__ f32x4 mfma16(bf16x8 a, bf16x8 b, f32x4 c) { return __builtin_amdgcn_mfma_f32_16x16x32_bf16(a, b, c, 0, 0, 0); }
; __device__ __forceinline__ void att_unit(LAS unsigned char* lds, const bf16* P, const bf16* AKV, const bf16* IKC, bf16* ACAT, const float* aqg, const float* ssq_ak, const float* ssq_ik, int b, int qg, int tid) {
;     ...
;                 if (tile + 1 < ntile) {
; #pragma unroll
;                     for (int i = 0; i < 4; ++i) { ikr[i] = *(const GAS u32x4*)(sb + (size_t)(256 * (tile + 1) + 64 * i) * 128); rik[i] = sik[256 * (tile + 1) + 64 * i + lane]; }
;                 }
; #pragma unroll
;                 for (int r4 = 0; r4 < 4; ++r4) {
;                     float pt[2][4];
; #pragma unroll
;                     for (int q4 = 0; q4 < 4; ++q4) {
;                         const LAS unsigned char* kp = IKc + (64 * r4 + 16 * q4 + fr) * 144 + fq * 16;
;                         const bf16x8 K0 = *(const LAS bf16x8*)kp, K1 = *(const LAS bf16x8*)(kp + 64);
; #pragma unroll
;                         for (int q = 0; q < 2; ++q) {
;                             f32x4 a = (f32x4){0.f, 0.f, 0.f, 0.f};
;                             a = mfma16(Qi[q][0], K0, a); a = mfma16(Qi[q][1], K1, a);
;                             pt[q][q4] = fmaxf(a[0], 0.f) * wv[q][0] + fmaxf(a[1], 0.f) * wv[q][1] + fmaxf(a[2], 0.f) * wv[q][2] + fmaxf(a[3], 0.f) * wv[q][3];
;                         }
;                     }
	global_load_dwordx4 v[18:21], v[18:19], off
	s_nop 0
	global_load_dwordx2 v[46:47], v[88:89], off offset:2048
	s_nop 0
	global_load_dwordx4 v[22:25], v[22:23], off
	s_nop 0
	global_load_dwordx2 v[104:105], v[88:89], off offset:2560
	s_nop 0
	global_load_dwordx4 v[26:29], v[26:27], off
	s_nop 0
	global_load_dwordx2 v[100:101], v[88:89], off offset:3072
	s_nop 0
	global_load_dwordx4 v[30:33], v[30:31], off
	s_nop 0
	global_load_dwordx2 v[94:95], v[88:89], off offset:3584
	ds_read_b128 v[54:57], v131
	ds_read_b128 v[60:63], v131 offset:64
	s_waitcnt lgkmcnt(1)
	v_mfma_f32_16x16x32_bf16 v[68:71], v[14:17], v[54:57], 0
	s_mov_b32 s0, 0x358637bd
	v_mfma_f32_16x16x32_bf16 v[54:57], v[2:5], v[54:57], 0
	s_waitcnt lgkmcnt(0)
	v_mfma_f32_16x16x32_bf16 v[68:71], v[10:13], v[60:63], v[68:71]
	v_mfma_f32_16x16x32_bf16 v[54:57], v[6:9], v[60:63], v[54:57]
	ds_read_b128 v[60:63], v131 offset:2304
	ds_read_b128 v[72:75], v131 offset:2368
	s_nop 4
	v_max_f32_e32 v64, 0, v68
	v_max_f32_e32 v65, 0, v69
	v_max_f32_e32 v59, 0, v70
	v_max_f32_e32 v58, 0, v71
	s_waitcnt lgkmcnt(1)
	v_mfma_f32_16x16x32_bf16 v[68:71], v[14:17], v[60:63], 0
	v_max_f32_e32 v54, 0, v54
	s_waitcnt lgkmcnt(0)
	v_mfma_f32_16x16x32_bf16 v[76:79], v[10:13], v[72:75], v[68:71]
	v_max_f32_e32 v55, 0, v55
	v_mfma_f32_16x16x32_bf16 v[60:63], v[2:5], v[60:63], 0
	v_max_f32_e32 v49, 0, v56
	s_nop 2
	s_nop 1
	v_max_f32_e32 v70, 0, v76
	v_max_f32_e32 v71, 0, v77
	v_max_f32_e32 v69, 0, v78
	v_max_f32_e32 v68, 0, v79
	ds_read_b128 v[78:81], v131 offset:4608
	ds_read_b128 v[82:85], v131 offset:4672
	v_mfma_f32_16x16x32_bf16 v[60:63], v[6:9], v[72:75], v[60:63]
	v_max_f32_e32 v48, 0, v57
	s_waitcnt lgkmcnt(1)
	v_mfma_f32_16x16x32_bf16 v[72:75], v[14:17], v[78:81], 0
	s_waitcnt lgkmcnt(0)
	v_mfma_f32_16x16x32_bf16 v[72:75], v[10:13], v[82:85], v[72:75]
	s_nop 0
	s_nop 1
	v_max_f32_e32 v60, 0, v60
	v_mfma_f32_16x16x32_bf16 v[78:81], v[2:5], v[78:81], 0
	v_max_f32_e32 v61, 0, v61
	v_max_f32_e32 v57, 0, v62
	v_max_f32_e32 v56, 0, v63
	v_mfma_f32_16x16x32_bf16 v[80:83], v[6:9], v[82:85], v[78:81]
	v_max_f32_e32 v76, 0, v72
	v_max_f32_e32 v77, 0, v73
	v_max_f32_e32 v73, 0, v74
	v_max_f32_e32 v72, 0, v75
	s_nop 0
	s_nop 2
	v_max_f32_e32 v80, 0, v80
	v_max_f32_e32 v81, 0, v81
	v_max_f32_e32 v63, 0, v82
	v_max_f32_e32 v62, 0, v83
	ds_read_b128 v[82:85], v131 offset:6912
	ds_read_b128 v[96:99], v131 offset:6976
	s_waitcnt lgkmcnt(1)
	v_mfma_f32_16x16x32_bf16 v[90:93], v[14:17], v[82:85], 0
	v_mov_b32_e32 v75, v42
	v_mov_b32_e32 v42, v45
	s_waitcnt lgkmcnt(0)
	v_mfma_f32_16x16x32_bf16 v[90:93], v[10:13], v[96:99], v[90:93]
	v_mfma_f32_16x16x32_bf16 v[82:85], v[2:5], v[82:85], 0
	v_mfma_f32_16x16x32_bf16 v[84:87], v[6:9], v[96:99], v[82:85]
	s_nop 5
	v_max_f32_e32 v78, 0, v90
	ds_read_b128 v[96:99], v131 offset:9216
	ds_read_b128 v[106:109], v131 offset:9280
	v_max_f32_e32 v79, 0, v91
	v_max_f32_e32 v91, 0, v92
	v_max_f32_e32 v90, 0, v93
	v_max_f32_e32 v84, 0, v84
	s_waitcnt lgkmcnt(1)
	v_mfma_f32_16x16x32_bf16 v[110:113], v[14:17], v[96:99], 0
	v_max_f32_e32 v85, 0, v85
	v_max_f32_e32 v83, 0, v86
	v_mfma_f32_16x16x32_bf16 v[96:99], v[2:5], v[96:99], 0
	v_max_f32_e32 v82, 0, v87
	v_mbcnt_hi_u32_b32 v53, -1, v221
	v_and_b32_e32 v74, 64, v53
	s_waitcnt lgkmcnt(0)
	v_mfma_f32_16x16x32_bf16 v[110:113], v[10:13], v[106:109], v[110:113]
	v_xor_b32_e32 v127, 16, v53
	v_add_u32_e32 v128, 64, v74
	v_cmp_lt_i32_e32 vcc, v127, v128
	v_mfma_f32_16x16x32_bf16 v[96:99], v[6:9], v[106:109], v[96:99]
	ds_read_b128 v[106:109], v131 offset:11520
	ds_read_b128 v[114:117], v131 offset:11584
	v_cndmask_b32_e32 v74, v53, v127, vcc
	v_lshlrev_b32_e32 v130, 2, v74
	s_waitcnt lgkmcnt(1)
	v_mfma_f32_16x16x32_bf16 v[118:121], v[14:17], v[106:109], 0
	v_max_f32_e32 v110, 0, v110
	v_max_f32_e32 v111, 0, v111
	v_max_f32_e32 v103, 0, v112
	v_mfma_f32_16x16x32_bf16 v[106:109], v[2:5], v[106:109], 0
	v_max_f32_e32 v102, 0, v113
	v_max_f32_e32 v96, 0, v96
	s_waitcnt lgkmcnt(0)
	v_mfma_f32_16x16x32_bf16 v[118:121], v[10:13], v[114:117], v[118:121]
	v_max_f32_e32 v97, 0, v97
	v_max_f32_e32 v87, 0, v98
	v_mfma_f32_16x16x32_bf16 v[106:109], v[6:9], v[114:117], v[106:109]
	ds_read_b128 v[114:117], v131 offset:13824
	ds_read_b128 v[134:137], v131 offset:13888
	v_max_f32_e32 v86, 0, v99
	s_nop 1
	v_max_f32_e32 v118, 0, v118
	v_max_f32_e32 v119, 0, v119
	v_max_f32_e32 v113, 0, v120
	v_max_f32_e32 v112, 0, v121
	s_waitcnt lgkmcnt(1)
	v_mfma_f32_16x16x32_bf16 v[120:123], v[14:17], v[114:117], 0
	v_max_f32_e32 v106, 0, v106
	v_mfma_f32_16x16x32_bf16 v[114:117], v[2:5], v[114:117], 0
	v_max_f32_e32 v107, 0, v107
	s_waitcnt lgkmcnt(0)
	v_mfma_f32_16x16x32_bf16 v[120:123], v[10:13], v[134:137], v[120:123]
	v_max_f32_e32 v99, 0, v108
	v_max_f32_e32 v98, 0, v109
	v_mfma_f32_16x16x32_bf16 v[114:117], v[6:9], v[134:137], v[114:117]
	ds_read_b128 v[134:137], v131 offset:16128
	ds_read_b128 v[138:141], v131 offset:16192
	s_nop 1
	s_nop 0
	v_max_f32_e32 v146, 0, v120
	s_waitcnt lgkmcnt(1)
	v_mfma_f32_16x16x32_bf16 v[142:145], v[14:17], v[134:137], 0
	v_max_f32_e32 v147, 0, v121
	v_max_f32_e32 v121, 0, v122
	v_max_f32_e32 v120, 0, v123
	s_waitcnt lgkmcnt(0)
	v_mfma_f32_16x16x32_bf16 v[142:145], v[10:13], v[138:141], v[142:145]
	v_max_f32_e32 v114, 0, v114
	v_max_f32_e32 v115, 0, v115
	v_mfma_f32_16x16x32_bf16 v[134:137], v[2:5], v[134:137], 0
	v_max_f32_e32 v109, 0, v116
	v_max_f32_e32 v108, 0, v117
	v_mfma_f32_16x16x32_bf16 v[134:137], v[6:9], v[138:141], v[134:137]
	s_nop 1
	v_max_f32_e32 v148, 0, v142
	v_max_f32_e32 v149, 0, v143
	v_max_f32_e32 v151, 0, v144
	v_max_f32_e32 v150, 0, v145
	s_nop 0
	s_nop 0
	v_max_f32_e32 v122, 0, v134
	v_max_f32_e32 v123, 0, v135
	v_max_f32_e32 v117, 0, v136
	v_max_f32_e32 v116, 0, v137
	ds_read_b128 v[134:137], v131 offset:18432
	ds_read_b128 v[138:141], v131 offset:18496
	s_waitcnt lgkmcnt(1)
; __device__ __forceinline__ void att_unit(LAS unsigned char* lds, const bf16* P, const bf16* AKV, const bf16* IKC, bf16* ACAT, const float* aqg, const float* ssq_ak, const float* ssq_ik, int b, int qg, int tid) {
;     ...
;                             pt[q][q4] = fmaxf(a[0], 0.f) * wv[q][0] + fmaxf(a[1], 0.f) * wv[q][1] + fmaxf(a[2], 0.f) * wv[q][2] + fmaxf(a[3], 0.f) * wv[q][3];
;                         }
;                     }
;                     const int rr = 4 * tile + r4;
;                     const float rscale = rsqrtf((rc[r4].x + rc[r4].y) * (1.f / 64.f) + EPS);
;                     const bool live = 64 * rr + lane < L;
; #pragma unroll
;                     for (int q = 0; q < 2; ++q) {
;                         float hx; const float A = half_sum32(pt[q][0], pt[q][2], hx), B = half_sum32(pt[q][1], pt[q][3], hx);
;                         const bool odd = fq & 1;
;                         const float send = odd ? A : B, keep = odd ? B : A;
;                         const float sc = live ? (keep + __shfl_xor(send, 16)) * rscale : -INFINITY;
;                         const unsigned bts = __float_as_uint(sc);
;                         uk[q][rr] = bts ^ ((unsigned)((int)bts >> 31) | 0x80000000u);
	v_mfma_f32_16x16x32_bf16 v[142:145], v[14:17], v[134:137], 0
	v_mov_b32_e32 v74, v44
	v_pk_add_f32 v[44:45], v[74:75], v[42:43]
	v_and_b32_e32 v75, 0xffff0000, v40
	s_waitcnt lgkmcnt(0)
	v_mfma_f32_16x16x32_bf16 v[142:145], v[10:13], v[138:141], v[142:145]
	v_lshlrev_b32_e32 v74, 16, v40
	v_mul_f32_e32 v40, v65, v75
	v_pk_fma_f32 v[64:65], v[64:65], v[74:75], v[40:41] op_sel_hi:[1,1,0]
	v_mul_f32_e32 v40, v71, v75
	v_pk_fma_f32 v[70:71], v[70:71], v[74:75], v[40:41] op_sel_hi:[1,1,0]
	v_mul_f32_e32 v40, v77, v75
	v_mov_b64_e32 v[42:43], s[0:1]
	v_pk_fma_f32 v[76:77], v[76:77], v[74:75], v[40:41] op_sel_hi:[1,1,0]
	v_mul_f32_e32 v40, v79, v75
	v_pk_fma_f32 v[92:93], v[44:45], s[2:3], v[42:43] op_sel_hi:[1,0,0]
	v_max_f32_e32 v44, 0, v142
	v_max_f32_e32 v45, 0, v143
	v_pk_fma_f32 v[142:143], v[78:79], v[74:75], v[40:41] op_sel_hi:[1,1,0]
	v_mul_f32_e32 v40, v111, v75
	v_pk_fma_f32 v[110:111], v[110:111], v[74:75], v[40:41] op_sel_hi:[1,1,0]
	v_mul_f32_e32 v40, v119, v75
	v_pk_fma_f32 v[118:119], v[118:119], v[74:75], v[40:41] op_sel_hi:[1,1,0]
	v_mul_f32_e32 v40, v147, v75
	v_pk_fma_f32 v[146:147], v[146:147], v[74:75], v[40:41] op_sel_hi:[1,1,0]
	v_mul_f32_e32 v40, v149, v75
	v_pk_fma_f32 v[148:149], v[148:149], v[74:75], v[40:41] op_sel_hi:[1,1,0]
	v_mul_f32_e32 v40, v45, v75
	v_pk_fma_f32 v[44:45], v[44:45], v[74:75], v[40:41] op_sel_hi:[1,1,0]
	v_max_f32_e32 v153, 0, v144
	v_lshlrev_b32_e32 v79, 16, v41
	v_max_f32_e32 v152, 0, v145
	v_mul_f32_e32 v40, v59, v79
	v_and_b32_e32 v78, 0xffff0000, v41
	v_pk_add_f32 v[40:41], v[40:41], v[64:65] op_sel_hi:[0,1]
	v_pk_fma_f32 v[40:41], v[58:59], v[78:79], v[40:41]
	v_mul_f32_e32 v58, v69, v79
	v_pk_add_f32 v[58:59], v[58:59], v[70:71] op_sel_hi:[0,1]
	v_pk_fma_f32 v[58:59], v[68:69], v[78:79], v[58:59]
	v_mul_f32_e32 v64, v73, v79
	v_mul_f32_e32 v68, v91, v79
	v_pk_add_f32 v[64:65], v[64:65], v[76:77] op_sel_hi:[0,1]
	v_pk_add_f32 v[68:69], v[68:69], v[142:143] op_sel_hi:[0,1]
	v_pk_fma_f32 v[64:65], v[72:73], v[78:79], v[64:65]
	v_pk_fma_f32 v[68:69], v[90:91], v[78:79], v[68:69]
	v_mul_f32_e32 v70, v103, v79
	v_mul_f32_e32 v72, v113, v79
	v_mul_f32_e32 v76, v121, v79
	v_mul_f32_e32 v90, v151, v79
	v_pk_add_f32 v[70:71], v[70:71], v[110:111] op_sel_hi:[0,1]
	v_pk_add_f32 v[72:73], v[72:73], v[118:119] op_sel_hi:[0,1]
	v_pk_add_f32 v[76:77], v[76:77], v[146:147] op_sel_hi:[0,1]
	v_pk_add_f32 v[90:91], v[90:91], v[148:149] op_sel_hi:[0,1]
	v_permlane32_swap_b32_e32 v40, v64
	v_permlane32_swap_b32_e32 v58, v68
	v_pk_fma_f32 v[70:71], v[102:103], v[78:79], v[70:71]
	v_pk_fma_f32 v[72:73], v[112:113], v[78:79], v[72:73]
	v_pk_fma_f32 v[76:77], v[120:121], v[78:79], v[76:77]
	v_pk_fma_f32 v[90:91], v[150:151], v[78:79], v[90:91]
	v_mfma_f32_16x16x32_bf16 v[110:113], v[2:5], v[134:137], 0
	v_permlane32_swap_b32_e32 v70, v76
	v_permlane32_swap_b32_e32 v72, v90
	v_mov_b32_e32 v73, v58
	v_mov_b32_e32 v91, v68
	v_mov_b32_e32 v71, v40
	v_mov_b32_e32 v77, v64
	v_pk_add_f32 v[68:69], v[72:73], v[90:91]
	v_pk_add_f32 v[70:71], v[70:71], v[76:77]
	v_and_b32_e32 v77, 0xffff0000, v38
	v_cndmask_b32_e64 v40, v71, v69, s[6:7]
	v_lshlrev_b32_e32 v76, 16, v38
	v_mul_f32_e32 v38, v55, v77
	ds_bpermute_b32 v73, v130, v40
	v_cndmask_b32_e64 v40, v70, v68, s[6:7]
	v_mfma_f32_16x16x32_bf16 v[110:113], v[6:9], v[138:141], v[110:113]
	v_fma_f32 v54, v54, v76, v38
	v_fma_f32 v55, v55, v77, v38
	v_mul_f32_e32 v38, v61, v77
	ds_bpermute_b32 v72, v130, v40
	v_mul_f32_e32 v40, v153, v79
	v_pk_fma_f32 v[58:59], v[60:61], v[76:77], v[38:39] op_sel_hi:[1,1,0]
	v_mul_f32_e32 v38, v81, v77
	v_pk_add_f32 v[40:41], v[40:41], v[44:45] op_sel_hi:[0,1]
	v_pk_fma_f32 v[60:61], v[80:81], v[76:77], v[38:39] op_sel_hi:[1,1,0]
	v_mul_f32_e32 v38, v85, v77
	v_pk_fma_f32 v[40:41], v[152:153], v[78:79], v[40:41]
	v_pk_fma_f32 v[64:65], v[84:85], v[76:77], v[38:39] op_sel_hi:[1,1,0]
	v_mul_f32_e32 v38, v97, v77
	v_pk_fma_f32 v[84:85], v[96:97], v[76:77], v[38:39] op_sel_hi:[1,1,0]
	v_mul_f32_e32 v38, v107, v77
	v_max_f32_e32 v44, 0, v110
	v_pk_fma_f32 v[90:91], v[106:107], v[76:77], v[38:39] op_sel_hi:[1,1,0]
	v_mul_f32_e32 v38, v115, v77
	v_max_f32_e32 v45, 0, v111
	v_pk_fma_f32 v[96:97], v[114:115], v[76:77], v[38:39] op_sel_hi:[1,1,0]
	v_mul_f32_e32 v38, v123, v77
	v_pk_fma_f32 v[102:103], v[122:123], v[76:77], v[38:39] op_sel_hi:[1,1,0]
	v_mul_f32_e32 v38, v45, v77
	v_pk_fma_f32 v[44:45], v[44:45], v[76:77], v[38:39] op_sel_hi:[1,1,0]
	v_max_f32_e32 v107, 0, v112
	v_lshlrev_b32_e32 v81, 16, v39
	v_max_f32_e32 v106, 0, v113
	v_mul_f32_e32 v38, v49, v81
	v_and_b32_e32 v80, 0xffff0000, v39
	v_pk_add_f32 v[38:39], v[38:39], v[54:55] op_sel_hi:[0,1]
	v_pk_fma_f32 v[38:39], v[48:49], v[80:81], v[38:39]
	v_mul_f32_e32 v48, v57, v81
	v_mul_f32_e32 v54, v63, v81
	v_pk_add_f32 v[48:49], v[48:49], v[58:59] op_sel_hi:[0,1]
	v_pk_add_f32 v[54:55], v[54:55], v[60:61] op_sel_hi:[0,1]
	v_pk_fma_f32 v[48:49], v[56:57], v[80:81], v[48:49]
	v_pk_fma_f32 v[56:57], v[62:63], v[80:81], v[54:55]
	v_mul_f32_e32 v54, v83, v81
	v_pk_add_f32 v[54:55], v[54:55], v[64:65] op_sel_hi:[0,1]
	v_mul_f32_e32 v58, v87, v81
	v_mul_f32_e32 v60, v99, v81
	v_mul_f32_e32 v62, v109, v81
	v_mul_f32_e32 v64, v117, v81
	v_pk_fma_f32 v[54:55], v[82:83], v[80:81], v[54:55]
	v_pk_add_f32 v[58:59], v[58:59], v[84:85] op_sel_hi:[0,1]
	v_pk_add_f32 v[60:61], v[60:61], v[90:91] op_sel_hi:[0,1]
	v_pk_add_f32 v[62:63], v[62:63], v[96:97] op_sel_hi:[0,1]
	v_pk_add_f32 v[64:65], v[64:65], v[102:103] op_sel_hi:[0,1]
	v_permlane32_swap_b32_e32 v38, v56
	v_permlane32_swap_b32_e32 v48, v54
	v_pk_fma_f32 v[58:59], v[86:87], v[80:81], v[58:59]
	v_pk_fma_f32 v[60:61], v[98:99], v[80:81], v[60:61]
	v_pk_fma_f32 v[62:63], v[108:109], v[80:81], v[62:63]
	v_pk_fma_f32 v[64:65], v[116:117], v[80:81], v[64:65]
	s_nop 0
	v_permlane32_swap_b32_e32 v58, v62
	v_permlane32_swap_b32_e32 v60, v64
	v_mov_b32_e32 v61, v48
	v_mov_b32_e32 v65, v54
	v_mov_b32_e32 v59, v38
	v_mov_b32_e32 v63, v56
	v_pk_add_f32 v[54:55], v[60:61], v[64:65]
	v_pk_add_f32 v[58:59], v[58:59], v[62:63]
	ds_read_b128 v[60:63], v131 offset:20736
	ds_read_b128 v[82:85], v131 offset:20800
	s_waitcnt lgkmcnt(1)
; #define LAS __attribute__((address_space(3)))
; __device__ __forceinline__ f32x4 mfma16(bf16x8 a, bf16x8 b, f32x4 c) { return __builtin_amdgcn_mfma_f32_16x16x32_bf16(a, b, c, 0, 0, 0); }
; __device__ __forceinline__ void att_unit(LAS unsigned char* lds, const bf16* P, const bf16* AKV, const bf16* IKC, bf16* ACAT, const float* aqg, const float* ssq_ak, const float* ssq_ik, int b, int qg, int tid) {
;     ...
;                 for (int r4 = 0; r4 < 4; ++r4) {
;                     float pt[2][4];
; #pragma unroll
;                     for (int q4 = 0; q4 < 4; ++q4) {
;                         const LAS unsigned char* kp = IKc + (64 * r4 + 16 * q4 + fr) * 144 + fq * 16;
;                         const bf16x8 K0 = *(const LAS bf16x8*)kp, K1 = *(const LAS bf16x8*)(kp + 64);
; #pragma unroll
;                         for (int q = 0; q < 2; ++q) {
;                             f32x4 a = (f32x4){0.f, 0.f, 0.f, 0.f};
;                             a = mfma16(Qi[q][0], K0, a); a = mfma16(Qi[q][1], K1, a);
;                             pt[q][q4] = fmaxf(a[0], 0.f) * wv[q][0] + fmaxf(a[1], 0.f) * wv[q][1] + fmaxf(a[2], 0.f) * wv[q][2] + fmaxf(a[3], 0.f) * wv[q][3];
;                         }
;                     }
;                     const int rr = 4 * tile + r4;
;                     const float rscale = rsqrtf((rc[r4].x + rc[r4].y) * (1.f / 64.f) + EPS);
;                     const bool live = 64 * rr + lane < L;
; #pragma unroll
;                     for (int q = 0; q < 2; ++q) {
;                         float hx; const float A = half_sum32(pt[q][0], pt[q][2], hx), B = half_sum32(pt[q][1], pt[q][3], hx);
;                         const bool odd = fq & 1;
;                         const float send = odd ? A : B, keep = odd ? B : A;
;                         const float sc = live ? (keep + __shfl_xor(send, 16)) * rscale : -INFINITY;
;                         const unsigned bts = __float_as_uint(sc);
;                         uk[q][rr] = bts ^ ((unsigned)((int)bts >> 31) | 0x80000000u);
	v_mfma_f32_16x16x32_bf16 v[96:99], v[14:17], v[60:63], 0
	v_cndmask_b32_e64 v38, v59, v55, s[6:7]
	ds_bpermute_b32 v57, v130, v38
	v_cndmask_b32_e64 v38, v58, v54, s[6:7]
	s_waitcnt lgkmcnt(1)
	v_mfma_f32_16x16x32_bf16 v[96:99], v[10:13], v[82:85], v[96:99]
	ds_bpermute_b32 v56, v130, v38
	v_mul_f32_e32 v38, v107, v81
	v_pk_add_f32 v[38:39], v[38:39], v[44:45] op_sel_hi:[0,1]
	v_mfma_f32_16x16x32_bf16 v[60:63], v[2:5], v[60:63], 0
	v_fma_f32 v38, v106, v80, v38
	v_fma_f32 v39, v107, v81, v39
	s_mov_b32 s0, 0x800000
	s_nop 0
	v_max_f32_e32 v44, 0, v96
	v_max_f32_e32 v45, 0, v97
	v_mfma_f32_16x16x32_bf16 v[60:63], v[6:9], v[82:85], v[60:63]
	v_mul_f32_e32 v48, v45, v75
	v_pk_fma_f32 v[44:45], v[44:45], v[74:75], v[48:49] op_sel_hi:[1,1,0]
	v_max_f32_e32 v49, 0, v98
	v_mul_f32_e32 v64, v49, v79
	v_max_f32_e32 v48, 0, v99
	v_pk_add_f32 v[44:45], v[64:65], v[44:45] op_sel_hi:[0,1]
	v_pk_fma_f32 v[44:45], v[48:49], v[78:79], v[44:45]
	s_nop 0
	v_max_f32_e32 v48, 0, v60
	v_max_f32_e32 v49, 0, v61
	v_mul_f32_e32 v60, v49, v77
	v_pk_fma_f32 v[48:49], v[48:49], v[76:77], v[60:61] op_sel_hi:[1,1,0]
	v_max_f32_e32 v61, 0, v62
	v_mul_f32_e32 v62, v61, v81
	v_max_f32_e32 v60, 0, v63
	v_pk_add_f32 v[48:49], v[62:63], v[48:49] op_sel_hi:[0,1]
	v_pk_fma_f32 v[48:49], v[60:61], v[80:81], v[48:49]
	ds_read_b128 v[60:63], v131 offset:23040
	ds_read_b128 v[96:99], v131 offset:23104
	s_waitcnt lgkmcnt(1)
	v_mfma_f32_16x16x32_bf16 v[82:85], v[14:17], v[60:63], 0
	v_cmp_gt_f32_e64 s[8:9], s0, v92
	v_cmp_gt_f32_e64 s[10:11], s0, v93
	v_mfma_f32_16x16x32_bf16 v[60:63], v[2:5], v[60:63], 0
	s_waitcnt lgkmcnt(0)
	v_mfma_f32_16x16x32_bf16 v[82:85], v[10:13], v[96:99], v[82:85]
	v_mfma_f32_16x16x32_bf16 v[60:63], v[6:9], v[96:99], v[60:63]
	ds_read_b128 v[96:99], v131 offset:25344
	ds_read_b128 v[106:109], v131 offset:25408
	s_nop 4
	v_max_f32_e32 v64, 0, v82
	v_max_f32_e32 v65, 0, v83
	v_mul_f32_e32 v82, v65, v75
	s_waitcnt lgkmcnt(1)
	v_mfma_f32_16x16x32_bf16 v[110:113], v[14:17], v[96:99], 0
	v_fma_f32 v64, v64, v74, v82
	v_fma_f32 v65, v65, v75, v82
	v_max_f32_e32 v83, 0, v84
	v_max_f32_e32 v82, 0, v85
	v_mul_f32_e32 v84, v83, v79
	v_max_f32_e32 v60, 0, v60
	v_pk_add_f32 v[64:65], v[84:85], v[64:65] op_sel_hi:[0,1]
	v_max_f32_e32 v61, 0, v61
	s_waitcnt lgkmcnt(0)
	v_mfma_f32_16x16x32_bf16 v[110:113], v[10:13], v[106:109], v[110:113]
	v_fma_f32 v84, v82, v78, v64
	v_fma_f32 v85, v83, v79, v65
	v_mul_f32_e32 v64, v61, v77
	v_pk_fma_f32 v[60:61], v[60:61], v[76:77], v[64:65] op_sel_hi:[1,1,0]
	v_max_f32_e32 v65, 0, v62
	v_mfma_f32_16x16x32_bf16 v[96:99], v[2:5], v[96:99], 0
	v_mul_f32_e32 v62, v65, v81
	v_max_f32_e32 v64, 0, v63
	v_pk_add_f32 v[60:61], v[62:63], v[60:61] op_sel_hi:[0,1]
	v_pk_fma_f32 v[62:63], v[64:65], v[80:81], v[60:61]
	v_max_f32_e32 v60, 0, v110
	v_max_f32_e32 v61, 0, v111
	v_mfma_f32_16x16x32_bf16 v[96:99], v[6:9], v[106:109], v[96:99]
	v_mul_f32_e32 v64, v61, v75
	v_pk_fma_f32 v[60:61], v[60:61], v[74:75], v[64:65] op_sel_hi:[1,1,0]
	v_max_f32_e32 v65, 0, v112
	v_mul_f32_e32 v82, v65, v79
	v_max_f32_e32 v64, 0, v113
	v_pk_add_f32 v[60:61], v[82:83], v[60:61] op_sel_hi:[0,1]
	v_pk_fma_f32 v[82:83], v[64:65], v[78:79], v[60:61]
	s_nop 0
	v_max_f32_e32 v60, 0, v96
	v_max_f32_e32 v61, 0, v97
	v_mul_f32_e32 v64, v61, v77
	v_pk_fma_f32 v[60:61], v[60:61], v[76:77], v[64:65] op_sel_hi:[1,1,0]
	v_max_f32_e32 v65, 0, v98
	v_max_f32_e32 v64, 0, v99
	ds_read_b128 v[96:99], v131 offset:27648
	ds_read_b128 v[106:109], v131 offset:27712
	s_waitcnt lgkmcnt(1)
	v_mfma_f32_16x16x32_bf16 v[110:113], v[14:17], v[96:99], 0
	v_mul_f32_e32 v86, v65, v81
	v_pk_add_f32 v[60:61], v[86:87], v[60:61] op_sel_hi:[0,1]
	s_waitcnt lgkmcnt(0)
	v_mfma_f32_16x16x32_bf16 v[110:113], v[10:13], v[106:109], v[110:113]
	v_fma_f32 v60, v64, v80, v60
	v_fma_f32 v61, v65, v81, v61
	v_permlane32_swap_b32_e32 v38, v62
	v_mfma_f32_16x16x32_bf16 v[96:99], v[2:5], v[96:99], 0
	v_permlane32_swap_b32_e32 v48, v60
	s_nop 2
	v_max_f32_e32 v64, 0, v110
	v_max_f32_e32 v65, 0, v111
	v_mfma_f32_16x16x32_bf16 v[96:99], v[6:9], v[106:109], v[96:99]
	v_mul_f32_e32 v86, v65, v75
	v_pk_fma_f32 v[64:65], v[64:65], v[74:75], v[86:87] op_sel_hi:[1,1,0]
	v_max_f32_e32 v87, 0, v112
	v_mul_f32_e32 v90, v87, v79
	v_max_f32_e32 v86, 0, v113
	v_pk_add_f32 v[64:65], v[90:91], v[64:65] op_sel_hi:[0,1]
	v_pk_fma_f32 v[86:87], v[86:87], v[78:79], v[64:65]
	s_nop 0
	v_max_f32_e32 v64, 0, v96
	v_max_f32_e32 v65, 0, v97
	v_mul_f32_e32 v90, v65, v77
	v_pk_fma_f32 v[64:65], v[64:65], v[76:77], v[90:91] op_sel_hi:[1,1,0]
	v_max_f32_e32 v91, 0, v98
	v_mul_f32_e32 v96, v91, v81
	v_max_f32_e32 v90, 0, v99
	v_pk_add_f32 v[64:65], v[96:97], v[64:65] op_sel_hi:[0,1]
	ds_read_b128 v[96:99], v131 offset:29952
	ds_read_b128 v[106:109], v131 offset:30016
	s_waitcnt lgkmcnt(1)
	v_mfma_f32_16x16x32_bf16 v[110:113], v[14:17], v[96:99], 0
	v_pk_fma_f32 v[64:65], v[90:91], v[80:81], v[64:65]
	v_permlane32_swap_b32_e32 v40, v84
	s_waitcnt lgkmcnt(0)
	v_mfma_f32_16x16x32_bf16 v[110:113], v[10:13], v[106:109], v[110:113]
	v_mov_b32_e32 v65, v38
	v_permlane32_swap_b32_e32 v44, v82
	v_mfma_f32_16x16x32_bf16 v[96:99], v[2:5], v[96:99], 0
	v_mov_b32_e32 v87, v40
	s_nop 3
	v_max_f32_e32 v90, 0, v110
	v_max_f32_e32 v91, 0, v111
	v_mul_f32_e32 v102, v91, v75
	v_pk_fma_f32 v[90:91], v[90:91], v[74:75], v[102:103] op_sel_hi:[1,1,0]
	v_max_f32_e32 v103, 0, v112
	v_mul_f32_e32 v110, v103, v79
	v_max_f32_e32 v102, 0, v113
	v_pk_add_f32 v[90:91], v[110:111], v[90:91] op_sel_hi:[0,1]
	v_mfma_f32_16x16x32_bf16 v[96:99], v[6:9], v[106:109], v[96:99]
	ds_read_b128 v[106:109], v131 offset:32256
	ds_read_b128 v[110:113], v131 offset:32320
	v_pk_fma_f32 v[90:91], v[102:103], v[78:79], v[90:91]
	s_waitcnt lgkmcnt(1)
; __device__ __forceinline__ void att_unit(LAS unsigned char* lds, const bf16* P, const bf16* AKV, const bf16* IKC, bf16* ACAT, const float* aqg, const float* ssq_ak, const float* ssq_ik, int b, int qg, int tid) {
;     ...
;                 if (tile + 1 < ntile) {
; #pragma unroll
;                     for (int i = 0; i < 4; ++i) { ikr[i] = *(const GAS u32x4*)(sb + (size_t)(256 * (tile + 1) + 64 * i) * 128); rik[i] = sik[256 * (tile + 1) + 64 * i + lane]; }
;                 }
; #pragma unroll
;                 for (int r4 = 0; r4 < 4; ++r4) {
;                     float pt[2][4];
; #pragma unroll
;                     for (int q4 = 0; q4 < 4; ++q4) {
;                         const LAS unsigned char* kp = IKc + (64 * r4 + 16 * q4 + fr) * 144 + fq * 16;
;                         const bf16x8 K0 = *(const LAS bf16x8*)kp, K1 = *(const LAS bf16x8*)(kp + 64);
; #pragma unroll
;                         for (int q = 0; q < 2; ++q) {
;                             f32x4 a = (f32x4){0.f, 0.f, 0.f, 0.f};
;                             a = mfma16(Qi[q][0], K0, a); a = mfma16(Qi[q][1], K1, a);
;                             pt[q][q4] = fmaxf(a[0], 0.f) * wv[q][0] + fmaxf(a[1], 0.f) * wv[q][1] + fmaxf(a[2], 0.f) * wv[q][2] + fmaxf(a[3], 0.f) * wv[q][3];
;                         }
;                     }
;                     const int rr = 4 * tile + r4;
;                     const float rscale = rsqrtf((rc[r4].x + rc[r4].y) * (1.f / 64.f) + EPS);
;                     const bool live = 64 * rr + lane < L;
; #pragma unroll
;                     for (int q = 0; q < 2; ++q) {
;                         float hx; const float A = half_sum32(pt[q][0], pt[q][2], hx), B = half_sum32(pt[q][1], pt[q][3], hx);
;                         const bool odd = fq & 1;
;                         const float send = odd ? A : B, keep = odd ? B : A;
;                         const float sc = live ? (keep + __shfl_xor(send, 16)) * rscale : -INFINITY;
;                         const unsigned bts = __float_as_uint(sc);
;                         uk[q][rr] = bts ^ ((unsigned)((int)bts >> 31) | 0x80000000u);
;                     }
;                 }
;                 if (tile + 1 < ntile) {
; #pragma unroll
;                     for (int i = 0; i < 4; ++i) *(LAS u32x4*)(IK + ((tile + 1) & 1) * 36864 + (skey + 64 * i) * 144 + spart * 16) = ikr[i];
;                 }
;                 __syncthreads();
	v_mfma_f32_16x16x32_bf16 v[114:117], v[14:17], v[106:109], 0
	s_nop 1
	s_nop 0
	v_max_f32_e32 v96, 0, v96
	s_waitcnt lgkmcnt(0)
	v_mfma_f32_16x16x32_bf16 v[114:117], v[10:13], v[110:113], v[114:117]
	v_max_f32_e32 v97, 0, v97
	v_mul_f32_e32 v102, v97, v77
	v_mfma_f32_16x16x32_bf16 v[106:109], v[2:5], v[106:109], 0
	v_fma_f32 v96, v96, v76, v102
	v_fma_f32 v97, v97, v77, v102
	v_max_f32_e32 v103, 0, v98
	v_max_f32_e32 v102, 0, v99
	v_mul_f32_e32 v98, v103, v81
	v_pk_add_f32 v[96:97], v[98:99], v[96:97] op_sel_hi:[0,1]
	v_max_f32_e32 v98, 0, v114
	v_max_f32_e32 v99, 0, v115
	v_mfma_f32_16x16x32_bf16 v[106:109], v[6:9], v[110:113], v[106:109]
	v_fma_f32 v96, v102, v80, v96
	v_fma_f32 v97, v103, v81, v97
	v_mul_f32_e32 v102, v99, v75
	v_pk_fma_f32 v[98:99], v[98:99], v[74:75], v[102:103] op_sel_hi:[1,1,0]
	v_max_f32_e32 v103, 0, v116
	v_mul_f32_e32 v114, v103, v79
	v_max_f32_e32 v102, 0, v117
	v_pk_add_f32 v[98:99], v[114:115], v[98:99] op_sel_hi:[0,1]
	v_pk_fma_f32 v[98:99], v[102:103], v[78:79], v[98:99]
	v_max_f32_e32 v102, 0, v106
	v_max_f32_e32 v103, 0, v107
	v_mul_f32_e32 v106, v103, v77
	v_pk_fma_f32 v[102:103], v[102:103], v[76:77], v[106:107] op_sel_hi:[1,1,0]
	v_max_f32_e32 v107, 0, v108
	v_mul_f32_e32 v108, v107, v81
	v_max_f32_e32 v106, 0, v109
	v_pk_add_f32 v[102:103], v[108:109], v[102:103] op_sel_hi:[0,1]
	v_pk_fma_f32 v[102:103], v[106:107], v[80:81], v[102:103]
	ds_read_b128 v[106:109], v131 offset:34560
	ds_read_b128 v[110:113], v131 offset:34624
	s_waitcnt lgkmcnt(1)
	v_mfma_f32_16x16x32_bf16 v[114:117], v[14:17], v[106:109], 0
	v_permlane32_swap_b32_e32 v64, v102
	v_mov_b32_e32 v97, v48
	s_waitcnt lgkmcnt(0)
	v_mfma_f32_16x16x32_bf16 v[114:117], v[10:13], v[110:113], v[114:117]
	v_mov_b32_e32 v103, v62
	v_pk_add_f32 v[64:65], v[64:65], v[102:103]
	v_permlane32_swap_b32_e32 v86, v98
	v_mfma_f32_16x16x32_bf16 v[106:109], v[2:5], v[106:109], 0
	s_nop 3
	v_max_f32_e32 v114, 0, v114
	v_mfma_f32_16x16x32_bf16 v[106:109], v[6:9], v[110:113], v[106:109]
	v_max_f32_e32 v115, 0, v115
	v_mul_f32_e32 v118, v115, v75
	v_pk_fma_f32 v[114:115], v[114:115], v[74:75], v[118:119] op_sel_hi:[1,1,0]
	v_max_f32_e32 v119, 0, v116
	v_max_f32_e32 v118, 0, v117
	s_nop 0
	s_nop 1
	v_max_f32_e32 v106, 0, v106
	v_max_f32_e32 v107, 0, v107
	v_mul_f32_e32 v110, v107, v77
	v_pk_fma_f32 v[106:107], v[106:107], v[76:77], v[110:111] op_sel_hi:[1,1,0]
	v_max_f32_e32 v111, 0, v108
	v_mul_f32_e32 v108, v111, v81
	v_max_f32_e32 v110, 0, v109
	v_pk_add_f32 v[106:107], v[108:109], v[106:107] op_sel_hi:[0,1]
	v_mul_f32_e32 v116, v119, v79
	v_pk_fma_f32 v[108:109], v[110:111], v[80:81], v[106:107]
	v_pk_add_f32 v[114:115], v[116:117], v[114:115] op_sel_hi:[0,1]
	s_nop 0
	v_permlane32_swap_b32_e32 v96, v108
	s_waitcnt vmcnt(8)
	v_mov_b32_e32 v106, v36
	v_mov_b32_e32 v107, v34
	v_mov_b32_e32 v34, v37
	v_mov_b32_e32 v109, v60
	v_pk_fma_f32 v[114:115], v[118:119], v[78:79], v[114:115]
	v_pk_add_f32 v[34:35], v[106:107], v[34:35]
	v_pk_add_f32 v[60:61], v[96:97], v[108:109]
	v_permlane32_swap_b32_e32 v90, v114
	v_pk_fma_f32 v[106:107], v[34:35], s[2:3], v[42:43] op_sel_hi:[1,0,0]
	v_cndmask_b32_e64 v34, v65, v61, s[6:7]
	v_mov_b32_e32 v91, v44
	v_mov_b32_e32 v115, v82
	v_mov_b32_e32 v99, v84
	ds_bpermute_b32 v63, v130, v34
	v_cndmask_b32_e64 v34, v64, v60, s[6:7]
	v_pk_add_f32 v[82:83], v[90:91], v[114:115]
	v_pk_add_f32 v[86:87], v[86:87], v[98:99]
	ds_bpermute_b32 v62, v130, v34
	v_cndmask_b32_e64 v34, v87, v83, s[6:7]
	ds_bpermute_b32 v85, v130, v34
	v_cndmask_b32_e64 v34, v86, v82, s[6:7]
	ds_bpermute_b32 v84, v130, v34
	v_cmp_gt_f32_e64 s[12:13], s0, v106
	v_cmp_gt_f32_e64 s[14:15], s0, v107
	s_movk_i32 s0, 0x1c0
	v_cmp_lt_u32_e64 s[0:1], s0, v132
	s_waitcnt vmcnt(0)
	v_mov_b64_e32 v[90:91], v[94:95]
	v_mov_b64_e32 v[96:97], v[100:101]
	v_mov_b64_e32 v[98:99], v[104:105]
	v_mov_b64_e32 v[102:103], v[46:47]
	ds_write_b128 v129, v[18:21] offset:36864
	ds_write_b128 v129, v[22:25] offset:46080
	ds_write_b128 v129, v[26:29] offset:55296
	ds_write_b128 v129, v[30:33] offset:64512
	s_waitcnt lgkmcnt(0)
	s_barrier
	s_and_saveexec_b64 s[2:3], s[0:1]
	s_cbranch_execz .LBB0_596
	v_add_co_u32_e32 v18, vcc, 0x20000, v66
	s_nop 1
	v_addc_co_u32_e32 v19, vcc, 0, v67, vcc
	v_add_co_u32_e32 v34, vcc, 0x1000, v88
	global_load_dwordx4 v[18:21], v[18:19], off
	s_nop 0
	v_addc_co_u32_e32 v35, vcc, 0, v89, vcc
	v_add_co_u32_e32 v22, vcc, 0x24000, v66
	s_nop 1
	v_addc_co_u32_e32 v23, vcc, 0, v67, vcc
	v_add_co_u32_e32 v26, vcc, 0x28000, v66
	s_nop 1
	v_addc_co_u32_e32 v27, vcc, 0, v67, vcc
	v_add_co_u32_e32 v30, vcc, 0x2c000, v66
	global_load_dwordx4 v[22:25], v[22:23], off
	s_nop 0
	global_load_dwordx4 v[26:29], v[26:27], off
	v_addc_co_u32_e32 v31, vcc, 0, v67, vcc
	global_load_dwordx4 v[30:33], v[30:31], off
	s_nop 0
	global_load_dwordx2 v[102:103], v[34:35], off
	global_load_dwordx2 v[98:99], v[34:35], off offset:512
	global_load_dwordx2 v[96:97], v[34:35], off offset:1024
	global_load_dwordx2 v[90:91], v[34:35], off offset:1536
; #define LAS __attribute__((address_space(3)))
; __device__ __forceinline__ f32x4 mfma16(bf16x8 a, bf16x8 b, f32x4 c) { return __builtin_amdgcn_mfma_f32_16x16x32_bf16(a, b, c, 0, 0, 0); }
; __device__ __forceinline__ void att_unit(LAS unsigned char* lds, const bf16* P, const bf16* AKV, const bf16* IKC, bf16* ACAT, const float* aqg, const float* ssq_ak, const float* ssq_ik, int b, int qg, int tid) {
;     ...
;                 for (int r4 = 0; r4 < 4; ++r4) {
;                     float pt[2][4];
; #pragma unroll
;                     for (int q4 = 0; q4 < 4; ++q4) {
;                         const LAS unsigned char* kp = IKc + (64 * r4 + 16 * q4 + fr) * 144 + fq * 16;
;                         const bf16x8 K0 = *(const LAS bf16x8*)kp, K1 = *(const LAS bf16x8*)(kp + 64);
; #pragma unroll
;                         for (int q = 0; q < 2; ++q) {
;                             f32x4 a = (f32x4){0.f, 0.f, 0.f, 0.f};
;                             a = mfma16(Qi[q][0], K0, a); a = mfma16(Qi[q][1], K1, a);
;                             pt[q][q4] = fmaxf(a[0], 0.f) * wv[q][0] + fmaxf(a[1], 0.f) * wv[q][1] + fmaxf(a[2], 0.f) * wv[q][2] + fmaxf(a[3], 0.f) * wv[q][3];
;                         }
;                     }
;                     const int rr = 4 * tile + r4;
;                     const float rscale = rsqrtf((rc[r4].x + rc[r4].y) * (1.f / 64.f) + EPS);
;                     const bool live = 64 * rr + lane < L;
; #pragma unroll
;                     for (int q = 0; q < 2; ++q) {
;                         float hx; const float A = half_sum32(pt[q][0], pt[q][2], hx), B = half_sum32(pt[q][1], pt[q][3], hx);
;                         const bool odd = fq & 1;
;                         const float send = odd ? A : B, keep = odd ? B : A;
;                         const float sc = live ? (keep + __shfl_xor(send, 16)) * rscale : -INFINITY;
;                         const unsigned bts = __float_as_uint(sc);
;                         uk[q][rr] = bts ^ ((unsigned)((int)bts >> 31) | 0x80000000u);
.LBB0_596:
	s_or_b64 exec, exec, s[2:3]
	ds_read_b128 v[34:37], v131 offset:36864
	ds_read_b128 v[38:41], v131 offset:36928
	ds_read_b128 v[112:115], v131 offset:39168
	ds_read_b128 v[116:119], v131 offset:39232
	ds_read_b128 v[120:123], v131 offset:41472
	v_add_f32_e32 v46, v46, v47
	s_waitcnt lgkmcnt(4)
	v_mfma_f32_16x16x32_bf16 v[42:45], v[14:17], v[34:37], 0
	v_fmamk_f32 v46, v46, 0x3c800000, v222
	v_mul_f32_e32 v47, 0x4b800000, v46
	v_cmp_gt_f32_e32 vcc, s18, v46
	s_waitcnt lgkmcnt(3)
	v_mfma_f32_16x16x32_bf16 v[42:45], v[10:13], v[38:41], v[42:45]
	v_cndmask_b32_e32 v46, v46, v47, vcc
	v_mfma_f32_16x16x32_bf16 v[34:37], v[2:5], v[34:37], 0
	v_mfma_f32_16x16x32_bf16 v[34:37], v[6:9], v[38:41], v[34:37]
	s_nop 4
	v_max_f32_e32 v42, v42, v42
	v_max_f32_e32 v43, v43, v43
	v_max_f32_e32 v44, v44, v44
	v_max_f32_e32 v48, 0, v45
	v_max_f32_e32 v49, 0, v42
	v_max_f32_e32 v108, 0, v43
	v_max_f32_e32 v109, 0, v44
	s_waitcnt lgkmcnt(2)
	v_mfma_f32_16x16x32_bf16 v[42:45], v[14:17], v[112:115], 0
	v_mul_f32_e32 v108, v108, v75
	v_fmac_f32_e32 v108, v49, v74
	v_fmac_f32_e32 v108, v109, v79
	s_waitcnt lgkmcnt(1)
	v_mfma_f32_16x16x32_bf16 v[42:45], v[10:13], v[116:119], v[42:45]
	v_fmac_f32_e32 v108, v48, v78
	v_rsq_f32_e32 v109, v46
	s_nop 0
	v_mul_f32_e32 v111, 0x45800000, v109
	s_nop 2
	s_nop 0
	v_max_f32_e32 v38, 0, v43
	v_mul_f32_e32 v110, v38, v75
	v_mfma_f32_16x16x32_bf16 v[38:41], v[2:5], v[112:115], 0
	v_max_f32_e32 v42, 0, v42
	v_fmac_f32_e32 v110, v42, v74
	v_mfma_f32_16x16x32_bf16 v[38:41], v[6:9], v[116:119], v[38:41]
	ds_read_b128 v[114:117], v131 offset:41536
	v_max_f32_e32 v42, 0, v44
	s_waitcnt lgkmcnt(1)
	v_mfma_f32_16x16x32_bf16 v[134:137], v[14:17], v[120:123], 0
	v_fmac_f32_e32 v110, v42, v79
	v_max_f32_e32 v42, 0, v45
	s_waitcnt lgkmcnt(0)
	v_mfma_f32_16x16x32_bf16 v[134:137], v[10:13], v[114:117], v[134:137]
	v_fmac_f32_e32 v110, v42, v78
	v_cndmask_b32_e32 v109, v109, v111, vcc
	v_or_b32_e32 v111, 0x100, v124
	v_cmp_gt_u32_e32 vcc, s81, v111
	s_nop 3
	v_max_f32_e32 v48, 0, v134
	v_max_f32_e32 v42, 0, v135
	v_mul_f32_e32 v112, v42, v75
	v_mfma_f32_16x16x32_bf16 v[42:45], v[2:5], v[120:123], 0
	ds_read_b128 v[118:121], v131 offset:43776
	v_fmac_f32_e32 v112, v48, v74
	v_mfma_f32_16x16x32_bf16 v[42:45], v[6:9], v[114:117], v[42:45]
	ds_read_b128 v[114:117], v131 offset:43840
	v_max_f32_e32 v48, 0, v136
	v_fmac_f32_e32 v112, v48, v79
	s_waitcnt lgkmcnt(1)
	v_mfma_f32_16x16x32_bf16 v[138:141], v[14:17], v[118:121], 0
	v_max_f32_e32 v48, 0, v137
	v_fmac_f32_e32 v112, v48, v78
	s_waitcnt lgkmcnt(0)
	v_mfma_f32_16x16x32_bf16 v[134:137], v[10:13], v[114:117], v[138:141]
	v_permlane32_swap_b32_e32 v108, v112
	v_mfma_f32_16x16x32_bf16 v[118:121], v[2:5], v[118:121], 0
	s_nop 0
	s_nop 0
	v_mov_b32_e32 v140, 0xff800000
	s_nop 3
	v_max_f32_e32 v49, 0, v135
	v_max_f32_e32 v48, 0, v134
	v_mul_f32_e32 v113, v49, v75
	v_fmac_f32_e32 v113, v48, v74
	v_max_f32_e32 v48, 0, v136
	v_fmac_f32_e32 v113, v48, v79
	v_max_f32_e32 v48, v137, v137
	v_max_f32_e32 v46, 0, v48
	v_fmac_f32_e32 v113, v46, v78
	v_mfma_f32_16x16x32_bf16 v[46:49], v[6:9], v[114:117], v[118:121]
	s_nop 0
	v_permlane32_swap_b32_e32 v110, v113
	v_mov_b32_e32 v115, 0xff800000
	s_and_saveexec_b64 s[2:3], vcc
	s_cbranch_execz .LBB0_598
	v_add_f32_e32 v110, v110, v113
	v_add_f32_e32 v108, v108, v112
	v_cndmask_b32_e64 v112, v108, v110, s[6:7]
	ds_bpermute_b32 v112, v130, v112
	v_cndmask_b32_e64 v108, v110, v108, s[6:7]
	s_waitcnt lgkmcnt(0)
	v_add_f32_e32 v108, v108, v112
	v_mul_f32_e32 v140, v109, v108
.LBB0_598:
	s_or_b64 exec, exec, s[2:3]
	v_max_f32_e32 v108, 0, v34
	v_max_f32_e32 v34, 0, v35
	v_mul_f32_e32 v34, v34, v77
	v_fmac_f32_e32 v34, v108, v76
	v_max_f32_e32 v35, 0, v36
	v_fmac_f32_e32 v34, v35, v81
	v_max_f32_e32 v35, 0, v37
	v_fmac_f32_e32 v34, v35, v80
	v_max_f32_e32 v36, 0, v38
	v_max_f32_e32 v35, 0, v39
	v_mul_f32_e32 v35, v35, v77
	v_fmac_f32_e32 v35, v36, v76
	v_max_f32_e32 v36, 0, v40
	v_fmac_f32_e32 v35, v36, v81
	v_max_f32_e32 v36, 0, v41
	v_fmac_f32_e32 v35, v36, v80
	v_max_f32_e32 v37, 0, v42
	v_max_f32_e32 v36, 0, v43
	v_mul_f32_e32 v36, v36, v77
	v_fmac_f32_e32 v36, v37, v76
	v_max_f32_e32 v37, 0, v44
	v_fmac_f32_e32 v36, v37, v81
	v_max_f32_e32 v37, 0, v45
	v_fmac_f32_e32 v36, v37, v80
	v_max_f32_e32 v38, 0, v46
	v_max_f32_e32 v37, 0, v47
	v_mul_f32_e32 v37, v37, v77
	v_fmac_f32_e32 v37, v38, v76
	v_max_f32_e32 v38, 0, v48
	v_fmac_f32_e32 v37, v38, v81
	v_max_f32_e32 v38, 0, v49
	v_fmac_f32_e32 v37, v38, v80
	v_permlane32_swap_b32_e32 v34, v36
	s_nop 0
	v_permlane32_swap_b32_e32 v35, v37
	s_and_saveexec_b64 s[2:3], vcc
	s_cbranch_execz .LBB0_600
	v_add_f32_e32 v35, v35, v37
	v_add_f32_e32 v34, v34, v36
	v_cndmask_b32_e64 v36, v34, v35, s[6:7]
	ds_bpermute_b32 v36, v130, v36
	v_cndmask_b32_e64 v34, v35, v34, s[6:7]
	s_waitcnt lgkmcnt(0)
	v_add_f32_e32 v34, v34, v36
	v_mul_f32_e32 v115, v109, v34
; #define LAS __attribute__((address_space(3)))
; __device__ __forceinline__ f32x4 mfma16(bf16x8 a, bf16x8 b, f32x4 c) { return __builtin_amdgcn_mfma_f32_16x16x32_bf16(a, b, c, 0, 0, 0); }
; __device__ __forceinline__ void att_unit(LAS unsigned char* lds, const bf16* P, const bf16* AKV, const bf16* IKC, bf16* ACAT, const float* aqg, const float* ssq_ak, const float* ssq_ik, int b, int qg, int tid) {
;     ...
;                 for (int r4 = 0; r4 < 4; ++r4) {
;                     float pt[2][4];
; #pragma unroll
;                     for (int q4 = 0; q4 < 4; ++q4) {
;                         const LAS unsigned char* kp = IKc + (64 * r4 + 16 * q4 + fr) * 144 + fq * 16;
;                         const bf16x8 K0 = *(const LAS bf16x8*)kp, K1 = *(const LAS bf16x8*)(kp + 64);
; #pragma unroll
;                         for (int q = 0; q < 2; ++q) {
;                             f32x4 a = (f32x4){0.f, 0.f, 0.f, 0.f};
;                             a = mfma16(Qi[q][0], K0, a); a = mfma16(Qi[q][1], K1, a);
;                             pt[q][q4] = fmaxf(a[0], 0.f) * wv[q][0] + fmaxf(a[1], 0.f) * wv[q][1] + fmaxf(a[2], 0.f) * wv[q][2] + fmaxf(a[3], 0.f) * wv[q][3];
;                         }
;                     }
;                     const int rr = 4 * tile + r4;
;                     const float rscale = rsqrtf((rc[r4].x + rc[r4].y) * (1.f / 64.f) + EPS);
;                     const bool live = 64 * rr + lane < L;
; #pragma unroll
;                     for (int q = 0; q < 2; ++q) {
;                         float hx; const float A = half_sum32(pt[q][0], pt[q][2], hx), B = half_sum32(pt[q][1], pt[q][3], hx);
;                         const bool odd = fq & 1;
;                         const float send = odd ? A : B, keep = odd ? B : A;
;                         const float sc = live ? (keep + __shfl_xor(send, 16)) * rscale : -INFINITY;
;                         const unsigned bts = __float_as_uint(sc);
;                         uk[q][rr] = bts ^ ((unsigned)((int)bts >> 31) | 0x80000000u);
.LBB0_600:
	s_or_b64 exec, exec, s[2:3]
	ds_read_b128 v[34:37], v131 offset:46080
	ds_read_b128 v[38:41], v131 offset:46144
	ds_read_b128 v[46:49], v131 offset:48384
	ds_read_b128 v[116:119], v131 offset:48448
	v_add_f32_e32 v104, v104, v105
	v_fmamk_f32 v104, v104, 0x3c800000, v222
	s_waitcnt lgkmcnt(3)
	v_mfma_f32_16x16x32_bf16 v[42:45], v[14:17], v[34:37], 0
	v_mul_f32_e32 v105, 0x4b800000, v104
	v_cmp_gt_f32_e32 vcc, s18, v104
	v_mov_b32_e32 v141, 0xff800000
	s_waitcnt lgkmcnt(2)
	v_mfma_f32_16x16x32_bf16 v[42:45], v[10:13], v[38:41], v[42:45]
	v_cndmask_b32_e32 v104, v104, v105, vcc
	v_rsq_f32_e32 v104, v104
	v_mfma_f32_16x16x32_bf16 v[34:37], v[2:5], v[34:37], 0
	v_mfma_f32_16x16x32_bf16 v[34:37], v[6:9], v[38:41], v[34:37]
	s_nop 3
	v_max_f32_e32 v42, v42, v42
	v_max_f32_e32 v43, v43, v43
	v_max_f32_e32 v44, v44, v44
	v_max_f32_e32 v109, 0, v45
	v_max_f32_e32 v110, 0, v42
	v_max_f32_e32 v108, 0, v43
	v_max_f32_e32 v112, 0, v44
	s_waitcnt lgkmcnt(1)
	v_mfma_f32_16x16x32_bf16 v[42:45], v[14:17], v[46:49], 0
	v_mul_f32_e32 v108, v108, v75
	v_fmac_f32_e32 v108, v110, v74
	v_fmac_f32_e32 v108, v112, v79
	s_waitcnt lgkmcnt(0)
	v_mfma_f32_16x16x32_bf16 v[42:45], v[10:13], v[116:119], v[42:45]
	v_fmac_f32_e32 v108, v109, v78
	s_nop 5
	s_nop 0
	v_max_f32_e32 v38, 0, v43
	v_mul_f32_e32 v109, v38, v75
	v_mfma_f32_16x16x32_bf16 v[38:41], v[2:5], v[46:49], 0
	ds_read_b128 v[46:49], v131 offset:50688
	v_max_f32_e32 v42, 0, v42
	v_mfma_f32_16x16x32_bf16 v[38:41], v[6:9], v[116:119], v[38:41]
	ds_read_b128 v[116:119], v131 offset:50752
	v_fmac_f32_e32 v109, v42, v74
	s_waitcnt lgkmcnt(1)
	v_mfma_f32_16x16x32_bf16 v[120:123], v[14:17], v[46:49], 0
	v_max_f32_e32 v42, 0, v44
	v_fmac_f32_e32 v109, v42, v79
	s_waitcnt lgkmcnt(0)
	v_mfma_f32_16x16x32_bf16 v[120:123], v[10:13], v[116:119], v[120:123]
	v_max_f32_e32 v42, 0, v45
	v_fmac_f32_e32 v109, v42, v78
	s_nop 5
	v_max_f32_e32 v112, 0, v120
	v_max_f32_e32 v42, 0, v121
	v_mul_f32_e32 v110, v42, v75
	v_mfma_f32_16x16x32_bf16 v[42:45], v[2:5], v[46:49], 0
	ds_read_b128 v[46:49], v131 offset:52992
	v_fmac_f32_e32 v110, v112, v74
	v_mfma_f32_16x16x32_bf16 v[42:45], v[6:9], v[116:119], v[42:45]
	ds_read_b128 v[116:119], v131 offset:53056
	v_max_f32_e32 v112, 0, v122
	v_fmac_f32_e32 v110, v112, v79
	s_waitcnt lgkmcnt(1)
	v_mfma_f32_16x16x32_bf16 v[134:137], v[14:17], v[46:49], 0
	v_max_f32_e32 v112, 0, v123
	v_fmac_f32_e32 v110, v112, v78
	s_waitcnt lgkmcnt(0)
	v_mfma_f32_16x16x32_bf16 v[120:123], v[10:13], v[116:119], v[134:137]
	v_permlane32_swap_b32_e32 v108, v110
	v_mfma_f32_16x16x32_bf16 v[46:49], v[2:5], v[46:49], 0
	v_mfma_f32_16x16x32_bf16 v[46:49], v[6:9], v[116:119], v[46:49]
	s_nop 4
	v_max_f32_e32 v113, 0, v121
	v_max_f32_e32 v112, 0, v120
	v_mul_f32_e32 v113, v113, v75
	v_fmac_f32_e32 v113, v112, v74
	v_max_f32_e32 v112, 0, v122
	v_fmac_f32_e32 v113, v112, v79
	v_max_f32_e32 v105, 0, v123
	v_fmac_f32_e32 v113, v105, v78
	v_mul_f32_e32 v105, 0x45800000, v104
	v_or_b32_e32 v112, 0x140, v124
	v_cndmask_b32_e32 v104, v104, v105, vcc
	v_cmp_gt_u32_e32 vcc, s81, v112
	v_permlane32_swap_b32_e32 v109, v113
	v_mov_b32_e32 v116, 0xff800000
	s_and_saveexec_b64 s[2:3], vcc
	s_cbranch_execz .LBB0_602
	v_add_f32_e32 v105, v109, v113
	v_add_f32_e32 v108, v108, v110
	v_cndmask_b32_e64 v109, v108, v105, s[6:7]
	ds_bpermute_b32 v109, v130, v109
	v_cndmask_b32_e64 v105, v105, v108, s[6:7]
	s_waitcnt lgkmcnt(0)
	v_add_f32_e32 v105, v105, v109
	v_mul_f32_e32 v141, v104, v105
.LBB0_602:
	s_or_b64 exec, exec, s[2:3]
	v_max_f32_e32 v105, 0, v34
	v_max_f32_e32 v34, 0, v35
	v_mul_f32_e32 v34, v34, v77
	v_fmac_f32_e32 v34, v105, v76
	v_max_f32_e32 v35, 0, v36
	v_fmac_f32_e32 v34, v35, v81
	v_max_f32_e32 v35, 0, v37
	v_fmac_f32_e32 v34, v35, v80
	v_max_f32_e32 v36, 0, v38
	v_max_f32_e32 v35, 0, v39
	v_mul_f32_e32 v35, v35, v77
	v_fmac_f32_e32 v35, v36, v76
	v_max_f32_e32 v36, 0, v40
	v_fmac_f32_e32 v35, v36, v81
	v_max_f32_e32 v36, 0, v41
	v_fmac_f32_e32 v35, v36, v80
	v_max_f32_e32 v37, 0, v42
	v_max_f32_e32 v36, 0, v43
	v_mul_f32_e32 v36, v36, v77
	v_fmac_f32_e32 v36, v37, v76
	v_max_f32_e32 v37, 0, v44
	v_fmac_f32_e32 v36, v37, v81
	v_max_f32_e32 v37, 0, v45
	v_fmac_f32_e32 v36, v37, v80
	v_max_f32_e32 v38, 0, v46
	v_max_f32_e32 v37, 0, v47
	v_mul_f32_e32 v37, v37, v77
	v_fmac_f32_e32 v37, v38, v76
	v_max_f32_e32 v38, 0, v48
	v_fmac_f32_e32 v37, v38, v81
	v_max_f32_e32 v38, 0, v49
	v_fmac_f32_e32 v37, v38, v80
	v_permlane32_swap_b32_e32 v34, v36
	s_nop 0
	v_permlane32_swap_b32_e32 v35, v37
	s_and_saveexec_b64 s[2:3], vcc
	s_cbranch_execz .LBB0_604
	v_add_f32_e32 v35, v35, v37
	v_add_f32_e32 v34, v34, v36
	v_cndmask_b32_e64 v36, v34, v35, s[6:7]
	ds_bpermute_b32 v36, v130, v36
	v_cndmask_b32_e64 v34, v35, v34, s[6:7]
	s_waitcnt lgkmcnt(0)
	v_add_f32_e32 v34, v34, v36
	v_mul_f32_e32 v116, v104, v34
; #define LAS __attribute__((address_space(3)))
; __device__ __forceinline__ f32x4 mfma16(bf16x8 a, bf16x8 b, f32x4 c) { return __builtin_amdgcn_mfma_f32_16x16x32_bf16(a, b, c, 0, 0, 0); }
; __device__ __forceinline__ void att_unit(LAS unsigned char* lds, const bf16* P, const bf16* AKV, const bf16* IKC, bf16* ACAT, const float* aqg, const float* ssq_ak, const float* ssq_ik, int b, int qg, int tid) {
;     ...
;                 for (int r4 = 0; r4 < 4; ++r4) {
;                     float pt[2][4];
; #pragma unroll
;                     for (int q4 = 0; q4 < 4; ++q4) {
;                         const LAS unsigned char* kp = IKc + (64 * r4 + 16 * q4 + fr) * 144 + fq * 16;
;                         const bf16x8 K0 = *(const LAS bf16x8*)kp, K1 = *(const LAS bf16x8*)(kp + 64);
; #pragma unroll
;                         for (int q = 0; q < 2; ++q) {
;                             f32x4 a = (f32x4){0.f, 0.f, 0.f, 0.f};
;                             a = mfma16(Qi[q][0], K0, a); a = mfma16(Qi[q][1], K1, a);
;                             pt[q][q4] = fmaxf(a[0], 0.f) * wv[q][0] + fmaxf(a[1], 0.f) * wv[q][1] + fmaxf(a[2], 0.f) * wv[q][2] + fmaxf(a[3], 0.f) * wv[q][3];
;                         }
;                     }
;                     const int rr = 4 * tile + r4;
;                     const float rscale = rsqrtf((rc[r4].x + rc[r4].y) * (1.f / 64.f) + EPS);
;                     const bool live = 64 * rr + lane < L;
; #pragma unroll
;                     for (int q = 0; q < 2; ++q) {
;                         float hx; const float A = half_sum32(pt[q][0], pt[q][2], hx), B = half_sum32(pt[q][1], pt[q][3], hx);
;                         const bool odd = fq & 1;
;                         const float send = odd ? A : B, keep = odd ? B : A;
;                         const float sc = live ? (keep + __shfl_xor(send, 16)) * rscale : -INFINITY;
;                         const unsigned bts = __float_as_uint(sc);
;                         uk[q][rr] = bts ^ ((unsigned)((int)bts >> 31) | 0x80000000u);
.LBB0_604:
	s_or_b64 exec, exec, s[2:3]
	ds_read_b128 v[34:37], v131 offset:55296
	ds_read_b128 v[38:41], v131 offset:55360
	ds_read_b128 v[46:49], v131 offset:57600
	ds_read_b128 v[118:121], v131 offset:57664
	v_add_f32_e32 v100, v100, v101
	v_fmamk_f32 v100, v100, 0x3c800000, v222
	s_waitcnt lgkmcnt(3)
	v_mfma_f32_16x16x32_bf16 v[42:45], v[14:17], v[34:37], 0
	v_mul_f32_e32 v101, 0x4b800000, v100
	v_cmp_gt_f32_e32 vcc, s18, v100
	v_or_b32_e32 v113, 0x180, v124
	s_waitcnt lgkmcnt(2)
	v_mfma_f32_16x16x32_bf16 v[42:45], v[10:13], v[38:41], v[42:45]
	v_cndmask_b32_e32 v100, v100, v101, vcc
	v_rsq_f32_e32 v100, v100
	v_mov_b32_e32 v146, 0xff800000
	v_mfma_f32_16x16x32_bf16 v[34:37], v[2:5], v[34:37], 0
	v_mfma_f32_16x16x32_bf16 v[34:37], v[6:9], v[38:41], v[34:37]
	s_nop 2
	v_max_f32_e32 v42, v42, v42
	v_max_f32_e32 v43, v43, v43
	v_max_f32_e32 v44, v44, v44
	v_max_f32_e32 v105, 0, v45
	v_max_f32_e32 v108, 0, v42
	v_max_f32_e32 v104, 0, v43
	v_max_f32_e32 v109, 0, v44
	s_waitcnt lgkmcnt(1)
	v_mfma_f32_16x16x32_bf16 v[42:45], v[14:17], v[46:49], 0
	v_mul_f32_e32 v104, v104, v75
	v_fmac_f32_e32 v104, v108, v74
	v_fmac_f32_e32 v104, v109, v79
	s_waitcnt lgkmcnt(0)
	v_mfma_f32_16x16x32_bf16 v[42:45], v[10:13], v[118:121], v[42:45]
	v_fmac_f32_e32 v104, v105, v78
	s_nop 5
	s_nop 0
	v_max_f32_e32 v38, 0, v43
	v_mul_f32_e32 v105, v38, v75
	v_mfma_f32_16x16x32_bf16 v[38:41], v[2:5], v[46:49], 0
	ds_read_b128 v[46:49], v131 offset:59904
	v_max_f32_e32 v42, 0, v42
	v_mfma_f32_16x16x32_bf16 v[38:41], v[6:9], v[118:121], v[38:41]
	ds_read_b128 v[118:121], v131 offset:59968
	v_fmac_f32_e32 v105, v42, v74
	s_waitcnt lgkmcnt(1)
	v_mfma_f32_16x16x32_bf16 v[134:137], v[14:17], v[46:49], 0
	v_max_f32_e32 v42, 0, v44
	v_fmac_f32_e32 v105, v42, v79
	s_waitcnt lgkmcnt(0)
	v_mfma_f32_16x16x32_bf16 v[134:137], v[10:13], v[118:121], v[134:137]
	v_max_f32_e32 v42, 0, v45
	v_fmac_f32_e32 v105, v42, v78
	s_nop 5
	v_max_f32_e32 v109, 0, v134
	v_max_f32_e32 v42, 0, v135
	v_mul_f32_e32 v108, v42, v75
	v_mfma_f32_16x16x32_bf16 v[42:45], v[2:5], v[46:49], 0
	ds_read_b128 v[46:49], v131 offset:62208
	v_fmac_f32_e32 v108, v109, v74
	v_mfma_f32_16x16x32_bf16 v[42:45], v[6:9], v[118:121], v[42:45]
	ds_read_b128 v[118:121], v131 offset:62272
	v_max_f32_e32 v109, 0, v136
	v_fmac_f32_e32 v108, v109, v79
	s_waitcnt lgkmcnt(1)
	v_mfma_f32_16x16x32_bf16 v[142:145], v[14:17], v[46:49], 0
	v_max_f32_e32 v109, 0, v137
	v_fmac_f32_e32 v108, v109, v78
	s_waitcnt lgkmcnt(0)
	v_mfma_f32_16x16x32_bf16 v[134:137], v[10:13], v[118:121], v[142:145]
	v_permlane32_swap_b32_e32 v104, v108
	v_mfma_f32_16x16x32_bf16 v[46:49], v[2:5], v[46:49], 0
	v_mfma_f32_16x16x32_bf16 v[46:49], v[6:9], v[118:121], v[46:49]
	s_nop 4
	v_max_f32_e32 v110, 0, v134
	v_max_f32_e32 v109, 0, v135
	v_mul_f32_e32 v109, v109, v75
	v_fmac_f32_e32 v109, v110, v74
	v_max_f32_e32 v110, 0, v136
	v_fmac_f32_e32 v109, v110, v79
	v_max_f32_e32 v101, 0, v137
	v_fmac_f32_e32 v109, v101, v78
	v_mul_f32_e32 v101, 0x45800000, v100
	v_cndmask_b32_e32 v100, v100, v101, vcc
	v_cmp_gt_u32_e32 vcc, s81, v113
	v_permlane32_swap_b32_e32 v105, v109
	v_mov_b32_e32 v121, 0xff800000
	s_and_saveexec_b64 s[2:3], vcc
	s_cbranch_execz .LBB0_606
	v_add_f32_e32 v101, v105, v109
	v_add_f32_e32 v104, v104, v108
	v_cndmask_b32_e64 v105, v104, v101, s[6:7]
	ds_bpermute_b32 v105, v130, v105
	v_cndmask_b32_e64 v101, v101, v104, s[6:7]
	s_waitcnt lgkmcnt(0)
	v_add_f32_e32 v101, v101, v105
	v_mul_f32_e32 v146, v100, v101
.LBB0_606:
	s_or_b64 exec, exec, s[2:3]
	v_max_f32_e32 v101, 0, v34
	v_max_f32_e32 v34, 0, v35
	v_mul_f32_e32 v34, v34, v77
	v_fmac_f32_e32 v34, v101, v76
	v_max_f32_e32 v35, 0, v36
	v_fmac_f32_e32 v34, v35, v81
	v_max_f32_e32 v35, 0, v37
	v_fmac_f32_e32 v34, v35, v80
	v_max_f32_e32 v36, 0, v38
	v_max_f32_e32 v35, 0, v39
	v_mul_f32_e32 v35, v35, v77
	v_fmac_f32_e32 v35, v36, v76
	v_max_f32_e32 v36, 0, v40
	v_fmac_f32_e32 v35, v36, v81
	v_max_f32_e32 v36, 0, v41
	v_fmac_f32_e32 v35, v36, v80
	v_max_f32_e32 v37, 0, v42
	v_max_f32_e32 v36, 0, v43
	v_mul_f32_e32 v36, v36, v77
	v_fmac_f32_e32 v36, v37, v76
	v_max_f32_e32 v37, 0, v44
	v_fmac_f32_e32 v36, v37, v81
	v_max_f32_e32 v37, 0, v45
	v_fmac_f32_e32 v36, v37, v80
	v_max_f32_e32 v38, 0, v46
	v_max_f32_e32 v37, 0, v47
	v_mul_f32_e32 v37, v37, v77
	v_fmac_f32_e32 v37, v38, v76
	v_max_f32_e32 v38, 0, v48
	v_fmac_f32_e32 v37, v38, v81
	v_max_f32_e32 v38, 0, v49
	v_fmac_f32_e32 v37, v38, v80
	v_permlane32_swap_b32_e32 v34, v36
	s_nop 0
	v_permlane32_swap_b32_e32 v35, v37
	s_and_saveexec_b64 s[2:3], vcc
	s_cbranch_execz .LBB0_608
	v_add_f32_e32 v35, v35, v37
	v_add_f32_e32 v34, v34, v36
	v_cndmask_b32_e64 v36, v34, v35, s[6:7]
	ds_bpermute_b32 v36, v130, v36
	v_cndmask_b32_e64 v34, v35, v34, s[6:7]
	s_waitcnt lgkmcnt(0)
	v_add_f32_e32 v34, v34, v36
	v_mul_f32_e32 v121, v100, v34
; #define LAS __attribute__((address_space(3)))
; __device__ __forceinline__ f32x4 mfma16(bf16x8 a, bf16x8 b, f32x4 c) { return __builtin_amdgcn_mfma_f32_16x16x32_bf16(a, b, c, 0, 0, 0); }
; __device__ __forceinline__ void att_unit(LAS unsigned char* lds, const bf16* P, const bf16* AKV, const bf16* IKC, bf16* ACAT, const float* aqg, const float* ssq_ak, const float* ssq_ik, int b, int qg, int tid) {
;     ...
;                 for (int r4 = 0; r4 < 4; ++r4) {
;                     float pt[2][4];
; #pragma unroll
;                     for (int q4 = 0; q4 < 4; ++q4) {
;                         const LAS unsigned char* kp = IKc + (64 * r4 + 16 * q4 + fr) * 144 + fq * 16;
;                         const bf16x8 K0 = *(const LAS bf16x8*)kp, K1 = *(const LAS bf16x8*)(kp + 64);
; #pragma unroll
;                         for (int q = 0; q < 2; ++q) {
;                             f32x4 a = (f32x4){0.f, 0.f, 0.f, 0.f};
;                             a = mfma16(Qi[q][0], K0, a); a = mfma16(Qi[q][1], K1, a);
;                             pt[q][q4] = fmaxf(a[0], 0.f) * wv[q][0] + fmaxf(a[1], 0.f) * wv[q][1] + fmaxf(a[2], 0.f) * wv[q][2] + fmaxf(a[3], 0.f) * wv[q][3];
;                         }
;                     }
;                     const int rr = 4 * tile + r4;
;                     const float rscale = rsqrtf((rc[r4].x + rc[r4].y) * (1.f / 64.f) + EPS);
;                     const bool live = 64 * rr + lane < L;
; #pragma unroll
;                     for (int q = 0; q < 2; ++q) {
;                         float hx; const float A = half_sum32(pt[q][0], pt[q][2], hx), B = half_sum32(pt[q][1], pt[q][3], hx);
;                         const bool odd = fq & 1;
;                         const float send = odd ? A : B, keep = odd ? B : A;
;                         const float sc = live ? (keep + __shfl_xor(send, 16)) * rscale : -INFINITY;
;                         const unsigned bts = __float_as_uint(sc);
;                         uk[q][rr] = bts ^ ((unsigned)((int)bts >> 31) | 0x80000000u);
;                     }
.LBB0_608:
	s_or_b64 exec, exec, s[2:3]
	ds_read_b128 v[34:37], v131 offset:64512
	ds_read_b128 v[38:41], v131 offset:64576
	v_add_u32_e32 v152, 0x9000, v131
	ds_read_b128 v[46:49], v152 offset:29952
	ds_read_b128 v[134:137], v152 offset:30016
	v_add_f32_e32 v94, v94, v95
	s_waitcnt lgkmcnt(3)
	v_mfma_f32_16x16x32_bf16 v[42:45], v[14:17], v[34:37], 0
	v_fmamk_f32 v94, v94, 0x3c800000, v222
	v_mul_f32_e32 v95, 0x4b800000, v94
	v_cmp_gt_f32_e32 vcc, s18, v94
	s_waitcnt lgkmcnt(2)
	v_mfma_f32_16x16x32_bf16 v[42:45], v[10:13], v[38:41], v[42:45]
	v_or_b32_e32 v114, 0x1c0, v124
	v_cndmask_b32_e32 v94, v94, v95, vcc
	v_rsq_f32_e32 v94, v94
	v_mfma_f32_16x16x32_bf16 v[34:37], v[2:5], v[34:37], 0
	v_mov_b32_e32 v122, 0xff800000
	s_nop 2
	v_max_f32_e32 v43, 0, v43
	v_mfma_f32_16x16x32_bf16 v[34:37], v[6:9], v[38:41], v[34:37]
	v_max_f32_e32 v42, 0, v42
	v_mul_f32_e32 v100, v43, v75
	s_waitcnt lgkmcnt(1)
	v_mfma_f32_16x16x32_bf16 v[38:41], v[14:17], v[46:49], 0
	v_max_f32_e32 v44, 0, v44
	v_fmac_f32_e32 v100, v42, v74
	v_fmac_f32_e32 v100, v44, v79
	v_max_f32_e32 v42, 0, v45
	v_fmac_f32_e32 v100, v42, v78
	s_waitcnt lgkmcnt(0)
	v_mfma_f32_16x16x32_bf16 v[40:43], v[10:13], v[134:137], v[38:41]
	s_nop 7
	v_max_f32_e32 v44, 0, v40
	v_max_f32_e32 v38, 0, v41
	v_mul_f32_e32 v101, v38, v75
	v_mfma_f32_16x16x32_bf16 v[38:41], v[2:5], v[46:49], 0
	v_fmac_f32_e32 v101, v44, v74
	ds_read_b128 v[44:47], v152 offset:32256
	v_mfma_f32_16x16x32_bf16 v[38:41], v[6:9], v[134:137], v[38:41]
	ds_read_b128 v[134:137], v152 offset:32320
	v_max_f32_e32 v42, 0, v42
	v_fmac_f32_e32 v101, v42, v79
	s_waitcnt lgkmcnt(1)
	v_mfma_f32_16x16x32_bf16 v[142:145], v[14:17], v[44:47], 0
	v_max_f32_e32 v42, 0, v43
	v_fmac_f32_e32 v101, v42, v78
	s_waitcnt lgkmcnt(0)
	v_mfma_f32_16x16x32_bf16 v[142:145], v[10:13], v[134:137], v[142:145]
	s_nop 7
	v_max_f32_e32 v48, 0, v142
	v_max_f32_e32 v42, 0, v143
	v_mul_f32_e32 v104, v42, v75
	v_mfma_f32_16x16x32_bf16 v[42:45], v[2:5], v[44:47], 0
	v_fmac_f32_e32 v104, v48, v74
	ds_read_b128 v[46:49], v152 offset:34560
	v_mfma_f32_16x16x32_bf16 v[42:45], v[6:9], v[134:137], v[42:45]
	ds_read_b128 v[134:137], v152 offset:34624
	v_max_f32_e32 v105, 0, v144
	v_fmac_f32_e32 v104, v105, v79
	s_waitcnt lgkmcnt(1)
	v_mfma_f32_16x16x32_bf16 v[148:151], v[14:17], v[46:49], 0
	v_max_f32_e32 v105, 0, v145
	v_fmac_f32_e32 v104, v105, v78
	s_waitcnt lgkmcnt(0)
	v_mfma_f32_16x16x32_bf16 v[142:145], v[10:13], v[134:137], v[148:151]
	v_permlane32_swap_b32_e32 v100, v104
	v_mfma_f32_16x16x32_bf16 v[46:49], v[2:5], v[46:49], 0
	s_nop 0
	s_nop 0
	v_mov_b32_e32 v150, 0xff800000
	s_nop 3
	v_max_f32_e32 v108, 0, v142
	v_max_f32_e32 v105, 0, v143
	v_mul_f32_e32 v105, v105, v75
	v_fmac_f32_e32 v105, v108, v74
	v_max_f32_e32 v108, 0, v144
	v_fmac_f32_e32 v105, v108, v79
	v_mfma_f32_16x16x32_bf16 v[46:49], v[6:9], v[134:137], v[46:49]
	v_max_f32_e32 v95, 0, v145
	v_fmac_f32_e32 v105, v95, v78
	v_mul_f32_e32 v95, 0x45800000, v94
	v_cndmask_b32_e32 v94, v94, v95, vcc
	v_cmp_gt_u32_e32 vcc, s81, v114
	v_permlane32_swap_b32_e32 v101, v105
	s_and_saveexec_b64 s[2:3], vcc
	s_cbranch_execz .LBB0_610
	v_add_f32_e32 v95, v101, v105
	v_add_f32_e32 v100, v100, v104
	v_cndmask_b32_e64 v101, v100, v95, s[6:7]
	ds_bpermute_b32 v101, v130, v101
	v_cndmask_b32_e64 v95, v95, v100, s[6:7]
	s_waitcnt lgkmcnt(0)
	v_add_f32_e32 v95, v95, v101
	v_mul_f32_e32 v150, v94, v95
.LBB0_610:
	s_or_b64 exec, exec, s[2:3]
	v_max_f32_e32 v95, 0, v34
	v_max_f32_e32 v34, 0, v35
	v_mul_f32_e32 v34, v34, v77
	v_fmac_f32_e32 v34, v95, v76
	v_max_f32_e32 v35, 0, v36
	v_fmac_f32_e32 v34, v35, v81
	v_max_f32_e32 v35, 0, v37
	v_fmac_f32_e32 v34, v35, v80
	v_max_f32_e32 v36, 0, v38
	v_max_f32_e32 v35, 0, v39
	v_mul_f32_e32 v35, v35, v77
	v_fmac_f32_e32 v35, v36, v76
	v_max_f32_e32 v36, 0, v40
	v_fmac_f32_e32 v35, v36, v81
	v_max_f32_e32 v36, 0, v41
	v_fmac_f32_e32 v35, v36, v80
	v_max_f32_e32 v37, 0, v42
	v_max_f32_e32 v36, 0, v43
	v_mul_f32_e32 v36, v36, v77
	v_fmac_f32_e32 v36, v37, v76
	v_max_f32_e32 v37, 0, v44
	v_fmac_f32_e32 v36, v37, v81
	v_max_f32_e32 v37, 0, v45
	v_fmac_f32_e32 v36, v37, v80
	v_max_f32_e32 v38, 0, v46
	v_max_f32_e32 v37, 0, v47
	v_mul_f32_e32 v37, v37, v77
	v_fmac_f32_e32 v37, v38, v76
	v_max_f32_e32 v38, 0, v48
	v_fmac_f32_e32 v37, v38, v81
	v_max_f32_e32 v38, 0, v49
	v_fmac_f32_e32 v37, v38, v80
	v_permlane32_swap_b32_e32 v34, v36
	s_nop 0
	v_permlane32_swap_b32_e32 v35, v37
	s_and_saveexec_b64 s[2:3], vcc
	s_cbranch_execz .LBB0_612
	v_add_f32_e32 v35, v35, v37
	v_add_f32_e32 v34, v34, v36
	v_cndmask_b32_e64 v36, v34, v35, s[6:7]
	ds_bpermute_b32 v36, v130, v36
	v_cndmask_b32_e64 v34, v35, v34, s[6:7]
	s_waitcnt lgkmcnt(0)
	v_add_f32_e32 v34, v34, v36
	v_mul_f32_e32 v122, v94, v34

; #define LAS __attribute__((address_space(3)))
; __device__ __forceinline__ f32x4 mfma16(bf16x8 a, bf16x8 b, f32x4 c) { return __builtin_amdgcn_mfma_f32_16x16x32_bf16(a, b, c, 0, 0, 0); }
; __device__ __forceinline__ void att_unit(LAS unsigned char* lds, const bf16* P, const bf16* AKV, const bf16* IKC, bf16* ACAT, const float* aqg, const float* ssq_ak, const float* ssq_ik, int b, int qg, int tid) {
;     ...
;                 for (int r4 = 0; r4 < 4; ++r4) {
;                     float pt[2][4];
; #pragma unroll
;                     for (int q4 = 0; q4 < 4; ++q4) {
;                         const LAS unsigned char* kp = IKc + (64 * r4 + 16 * q4 + fr) * 144 + fq * 16;
;                         const bf16x8 K0 = *(const LAS bf16x8*)kp, K1 = *(const LAS bf16x8*)(kp + 64);
; #pragma unroll
;                         for (int q = 0; q < 2; ++q) {
;                             f32x4 a = (f32x4){0.f, 0.f, 0.f, 0.f};
;                             a = mfma16(Qi[q][0], K0, a); a = mfma16(Qi[q][1], K1, a);
;                             pt[q][q4] = fmaxf(a[0], 0.f) * wv[q][0] + fmaxf(a[1], 0.f) * wv[q][1] + fmaxf(a[2], 0.f) * wv[q][2] + fmaxf(a[3], 0.f) * wv[q][3];
;                         }
;                     }
;                     const int rr = 4 * tile + r4;
;                     const float rscale = rsqrtf((rc[r4].x + rc[r4].y) * (1.f / 64.f) + EPS);
;                     const bool live = 64 * rr + lane < L;
; #pragma unroll
;                     for (int q = 0; q < 2; ++q) {
;                         float hx; const float A = half_sum32(pt[q][0], pt[q][2], hx), B = half_sum32(pt[q][1], pt[q][3], hx);
;                         const bool odd = fq & 1;
;                         const float send = odd ? A : B, keep = odd ? B : A;
;                         const float sc = live ? (keep + __shfl_xor(send, 16)) * rscale : -INFINITY;
;                         const unsigned bts = __float_as_uint(sc);
;                         uk[q][rr] = bts ^ ((unsigned)((int)bts >> 31) | 0x80000000u);
;                     }
.LBB0_617:
	s_or_b64 exec, exec, s[4:5]
	ds_read_b128 v[34:37], v131
	ds_read_b128 v[38:41], v131 offset:64
	ds_read_b128 v[46:49], v131 offset:2304
	ds_read_b128 v[134:137], v131 offset:2368
	v_add_f32_e32 v102, v102, v103
	v_fmamk_f32 v102, v102, 0x3c800000, v222
	s_waitcnt lgkmcnt(3)
	v_mfma_f32_16x16x32_bf16 v[42:45], v[14:17], v[34:37], 0
	v_mul_f32_e32 v103, 0x4b800000, v102
	v_cmp_gt_f32_e32 vcc, s18, v102
	s_waitcnt lgkmcnt(2)
	v_mfma_f32_16x16x32_bf16 v[42:45], v[10:13], v[38:41], v[42:45]
	v_cndmask_b32_e32 v102, v102, v103, vcc
	v_rsq_f32_e32 v102, v102
	v_mfma_f32_16x16x32_bf16 v[34:37], v[2:5], v[34:37], 0
	v_mfma_f32_16x16x32_bf16 v[34:37], v[6:9], v[38:41], v[34:37]
	s_nop 3
	v_max_f32_e32 v42, v42, v42
	v_max_f32_e32 v43, v43, v43
	v_max_f32_e32 v44, v44, v44
	v_max_f32_e32 v117, 0, v45
	v_max_f32_e32 v118, 0, v42
	v_max_f32_e32 v110, 0, v43
	v_max_f32_e32 v119, 0, v44
	s_waitcnt lgkmcnt(1)
	v_mfma_f32_16x16x32_bf16 v[42:45], v[14:17], v[46:49], 0
	v_mul_f32_e32 v110, v110, v75
	v_fmac_f32_e32 v110, v118, v74
	v_fmac_f32_e32 v110, v119, v79
	s_waitcnt lgkmcnt(0)
	v_mfma_f32_16x16x32_bf16 v[42:45], v[10:13], v[134:137], v[42:45]
	v_fmac_f32_e32 v110, v117, v78
	s_nop 5
	s_nop 0
	v_max_f32_e32 v38, 0, v43
	v_mul_f32_e32 v118, v38, v75
	v_mfma_f32_16x16x32_bf16 v[38:41], v[2:5], v[46:49], 0
	ds_read_b128 v[46:49], v131 offset:4608
	v_max_f32_e32 v42, 0, v42
	v_mfma_f32_16x16x32_bf16 v[38:41], v[6:9], v[134:137], v[38:41]
	ds_read_b128 v[134:137], v131 offset:4672
	v_fmac_f32_e32 v118, v42, v74
	s_waitcnt lgkmcnt(1)
	v_mfma_f32_16x16x32_bf16 v[142:145], v[14:17], v[46:49], 0
	v_max_f32_e32 v42, 0, v44
	v_fmac_f32_e32 v118, v42, v79
	s_waitcnt lgkmcnt(0)
	v_mfma_f32_16x16x32_bf16 v[142:145], v[10:13], v[134:137], v[142:145]
	v_max_f32_e32 v42, 0, v45
	v_fmac_f32_e32 v118, v42, v78
	s_nop 5
	v_max_f32_e32 v117, 0, v142
	v_max_f32_e32 v42, 0, v143
	v_mul_f32_e32 v119, v42, v75
	v_mfma_f32_16x16x32_bf16 v[42:45], v[2:5], v[46:49], 0
	ds_read_b128 v[46:49], v131 offset:6912
	v_fmac_f32_e32 v119, v117, v74
	v_mfma_f32_16x16x32_bf16 v[42:45], v[6:9], v[134:137], v[42:45]
	ds_read_b128 v[134:137], v131 offset:6976
	v_max_f32_e32 v117, 0, v144
	v_fmac_f32_e32 v119, v117, v79
	s_waitcnt lgkmcnt(1)
	v_mfma_f32_16x16x32_bf16 v[158:161], v[14:17], v[46:49], 0
	v_max_f32_e32 v117, 0, v145
	v_fmac_f32_e32 v119, v117, v78
	s_waitcnt lgkmcnt(0)
	v_mfma_f32_16x16x32_bf16 v[142:145], v[10:13], v[134:137], v[158:161]
	v_permlane32_swap_b32_e32 v110, v119
	v_mfma_f32_16x16x32_bf16 v[46:49], v[2:5], v[46:49], 0
	v_mfma_f32_16x16x32_bf16 v[46:49], v[6:9], v[134:137], v[46:49]
	s_nop 4
	v_max_f32_e32 v120, 0, v143
	v_max_f32_e32 v117, 0, v142
	v_mul_f32_e32 v120, v120, v75
	v_fmac_f32_e32 v120, v117, v74
	v_max_f32_e32 v117, 0, v144
	v_fmac_f32_e32 v120, v117, v79
	v_max_f32_e32 v103, 0, v145
	v_fmac_f32_e32 v120, v103, v78
	v_mul_f32_e32 v103, 0x45800000, v102
	v_cndmask_b32_e32 v117, v102, v103, vcc
	v_or_b32_e32 v102, 0x200, v124
	v_cmp_gt_u32_e32 vcc, s81, v102
	v_permlane32_swap_b32_e32 v118, v120
	v_mov_b32_e32 v103, 0xff800000
	v_mov_b32_e32 v102, 0xff800000
	s_and_saveexec_b64 s[4:5], vcc
	s_cbranch_execz .LBB0_619
	v_add_f32_e32 v102, v118, v120
	v_add_f32_e32 v110, v110, v119
	v_cndmask_b32_e64 v118, v110, v102, s[6:7]
	ds_bpermute_b32 v118, v130, v118
	v_cndmask_b32_e64 v102, v102, v110, s[6:7]
	s_waitcnt lgkmcnt(0)
	v_add_f32_e32 v102, v102, v118
	v_mul_f32_e32 v102, v117, v102
.LBB0_619:
	s_or_b64 exec, exec, s[4:5]
	v_max_f32_e32 v110, 0, v34
	v_max_f32_e32 v34, 0, v35
	v_mul_f32_e32 v34, v34, v77
	v_fmac_f32_e32 v34, v110, v76
	v_max_f32_e32 v35, 0, v36
	v_fmac_f32_e32 v34, v35, v81
	v_max_f32_e32 v35, 0, v37
	v_fmac_f32_e32 v34, v35, v80
	v_max_f32_e32 v36, 0, v38
	v_max_f32_e32 v35, 0, v39
	v_mul_f32_e32 v35, v35, v77
	v_fmac_f32_e32 v35, v36, v76
	v_max_f32_e32 v36, 0, v40
	v_fmac_f32_e32 v35, v36, v81
	v_max_f32_e32 v36, 0, v41
	v_fmac_f32_e32 v35, v36, v80
	v_max_f32_e32 v37, 0, v42
	v_max_f32_e32 v36, 0, v43
	v_mul_f32_e32 v36, v36, v77
	v_fmac_f32_e32 v36, v37, v76
	v_max_f32_e32 v37, 0, v44
	v_fmac_f32_e32 v36, v37, v81
	v_max_f32_e32 v37, 0, v45
	v_fmac_f32_e32 v36, v37, v80
	v_max_f32_e32 v38, 0, v46
	v_max_f32_e32 v37, 0, v47
	v_mul_f32_e32 v37, v37, v77
	v_fmac_f32_e32 v37, v38, v76
	v_max_f32_e32 v38, 0, v48
	v_fmac_f32_e32 v37, v38, v81
	v_max_f32_e32 v38, 0, v49
	v_fmac_f32_e32 v37, v38, v80
	v_permlane32_swap_b32_e32 v34, v36
	s_nop 0
	v_permlane32_swap_b32_e32 v35, v37
	s_and_saveexec_b64 s[4:5], vcc
	s_cbranch_execz .LBB0_621
	v_add_f32_e32 v35, v35, v37
	v_add_f32_e32 v34, v34, v36
	v_cndmask_b32_e64 v36, v34, v35, s[6:7]
	ds_bpermute_b32 v36, v130, v36
	v_cndmask_b32_e64 v34, v35, v34, s[6:7]
	s_waitcnt lgkmcnt(0)
	v_add_f32_e32 v34, v34, v36
	v_mul_f32_e32 v103, v117, v34
; #define LAS __attribute__((address_space(3)))
; __device__ __forceinline__ f32x4 mfma16(bf16x8 a, bf16x8 b, f32x4 c) { return __builtin_amdgcn_mfma_f32_16x16x32_bf16(a, b, c, 0, 0, 0); }
; __device__ __forceinline__ void att_unit(LAS unsigned char* lds, const bf16* P, const bf16* AKV, const bf16* IKC, bf16* ACAT, const float* aqg, const float* ssq_ak, const float* ssq_ik, int b, int qg, int tid) {
;     ...
;                 for (int r4 = 0; r4 < 4; ++r4) {
;                     float pt[2][4];
; #pragma unroll
;                     for (int q4 = 0; q4 < 4; ++q4) {
;                         const LAS unsigned char* kp = IKc + (64 * r4 + 16 * q4 + fr) * 144 + fq * 16;
;                         const bf16x8 K0 = *(const LAS bf16x8*)kp, K1 = *(const LAS bf16x8*)(kp + 64);
; #pragma unroll
;                         for (int q = 0; q < 2; ++q) {
;                             f32x4 a = (f32x4){0.f, 0.f, 0.f, 0.f};
;                             a = mfma16(Qi[q][0], K0, a); a = mfma16(Qi[q][1], K1, a);
;                             pt[q][q4] = fmaxf(a[0], 0.f) * wv[q][0] + fmaxf(a[1], 0.f) * wv[q][1] + fmaxf(a[2], 0.f) * wv[q][2] + fmaxf(a[3], 0.f) * wv[q][3];
;                         }
;                     }
;                     const int rr = 4 * tile + r4;
;                     const float rscale = rsqrtf((rc[r4].x + rc[r4].y) * (1.f / 64.f) + EPS);
;                     const bool live = 64 * rr + lane < L;
; #pragma unroll
;                     for (int q = 0; q < 2; ++q) {
;                         float hx; const float A = half_sum32(pt[q][0], pt[q][2], hx), B = half_sum32(pt[q][1], pt[q][3], hx);
;                         const bool odd = fq & 1;
;                         const float send = odd ? A : B, keep = odd ? B : A;
;                         const float sc = live ? (keep + __shfl_xor(send, 16)) * rscale : -INFINITY;
;                         const unsigned bts = __float_as_uint(sc);
;                         uk[q][rr] = bts ^ ((unsigned)((int)bts >> 31) | 0x80000000u);
;                     }
.LBB0_621:
	s_or_b64 exec, exec, s[4:5]
	ds_read_b128 v[34:37], v131 offset:9216
	ds_read_b128 v[38:41], v131 offset:9280
	ds_read_b128 v[46:49], v131 offset:11520
	ds_read_b128 v[134:137], v131 offset:11584
	v_add_f32_e32 v98, v98, v99
	v_fmamk_f32 v98, v98, 0x3c800000, v222
	s_waitcnt lgkmcnt(3)
	v_mfma_f32_16x16x32_bf16 v[42:45], v[14:17], v[34:37], 0
	v_mul_f32_e32 v99, 0x4b800000, v98
	v_cmp_gt_f32_e32 vcc, s18, v98
	s_waitcnt lgkmcnt(2)
	v_mfma_f32_16x16x32_bf16 v[42:45], v[10:13], v[38:41], v[42:45]
	v_cndmask_b32_e32 v98, v98, v99, vcc
	v_rsq_f32_e32 v98, v98
	v_mfma_f32_16x16x32_bf16 v[34:37], v[2:5], v[34:37], 0
	v_mfma_f32_16x16x32_bf16 v[34:37], v[6:9], v[38:41], v[34:37]
	s_nop 3
	v_max_f32_e32 v42, v42, v42
	v_max_f32_e32 v43, v43, v43
	v_max_f32_e32 v44, v44, v44
	v_max_f32_e32 v117, 0, v45
	v_max_f32_e32 v118, 0, v42
	v_max_f32_e32 v110, 0, v43
	v_max_f32_e32 v119, 0, v44
	s_waitcnt lgkmcnt(1)
	v_mfma_f32_16x16x32_bf16 v[42:45], v[14:17], v[46:49], 0
	v_mul_f32_e32 v110, v110, v75
	v_fmac_f32_e32 v110, v118, v74
	v_fmac_f32_e32 v110, v119, v79
	s_waitcnt lgkmcnt(0)
	v_mfma_f32_16x16x32_bf16 v[42:45], v[10:13], v[134:137], v[42:45]
	v_fmac_f32_e32 v110, v117, v78
	s_nop 5
	s_nop 0
	v_max_f32_e32 v38, 0, v43
	v_mul_f32_e32 v118, v38, v75
	v_mfma_f32_16x16x32_bf16 v[38:41], v[2:5], v[46:49], 0
	ds_read_b128 v[46:49], v131 offset:13824
	v_max_f32_e32 v42, 0, v42
	v_mfma_f32_16x16x32_bf16 v[38:41], v[6:9], v[134:137], v[38:41]
	ds_read_b128 v[134:137], v131 offset:13888
	v_fmac_f32_e32 v118, v42, v74
	s_waitcnt lgkmcnt(1)
	v_mfma_f32_16x16x32_bf16 v[142:145], v[14:17], v[46:49], 0
	v_max_f32_e32 v42, 0, v44
	v_fmac_f32_e32 v118, v42, v79
	s_waitcnt lgkmcnt(0)
	v_mfma_f32_16x16x32_bf16 v[142:145], v[10:13], v[134:137], v[142:145]
	v_max_f32_e32 v42, 0, v45
	v_fmac_f32_e32 v118, v42, v78
	s_nop 5
	v_max_f32_e32 v117, 0, v142
	v_max_f32_e32 v42, 0, v143
	v_mul_f32_e32 v119, v42, v75
	v_mfma_f32_16x16x32_bf16 v[42:45], v[2:5], v[46:49], 0
	ds_read_b128 v[46:49], v131 offset:16128
	v_fmac_f32_e32 v119, v117, v74
	v_mfma_f32_16x16x32_bf16 v[42:45], v[6:9], v[134:137], v[42:45]
	ds_read_b128 v[134:137], v131 offset:16192
	v_max_f32_e32 v117, 0, v144
	v_fmac_f32_e32 v119, v117, v79
	s_waitcnt lgkmcnt(1)
	v_mfma_f32_16x16x32_bf16 v[158:161], v[14:17], v[46:49], 0
	v_max_f32_e32 v117, 0, v145
	v_fmac_f32_e32 v119, v117, v78
	s_waitcnt lgkmcnt(0)
	v_mfma_f32_16x16x32_bf16 v[142:145], v[10:13], v[134:137], v[158:161]
	v_permlane32_swap_b32_e32 v110, v119
	v_mfma_f32_16x16x32_bf16 v[46:49], v[2:5], v[46:49], 0
	v_mfma_f32_16x16x32_bf16 v[46:49], v[6:9], v[134:137], v[46:49]
	s_nop 4
	v_max_f32_e32 v120, 0, v143
	v_max_f32_e32 v117, 0, v142
	v_mul_f32_e32 v120, v120, v75
	v_fmac_f32_e32 v120, v117, v74
	v_max_f32_e32 v117, 0, v144
	v_fmac_f32_e32 v120, v117, v79
	v_max_f32_e32 v99, 0, v145
	v_fmac_f32_e32 v120, v99, v78
	v_mul_f32_e32 v99, 0x45800000, v98
	v_cndmask_b32_e32 v117, v98, v99, vcc
	v_or_b32_e32 v98, 0x240, v124
	v_cmp_gt_u32_e32 vcc, s81, v98
	v_permlane32_swap_b32_e32 v118, v120
	v_mov_b32_e32 v99, 0xff800000
	v_mov_b32_e32 v98, 0xff800000
	s_and_saveexec_b64 s[4:5], vcc
	s_cbranch_execz .LBB0_623
	v_add_f32_e32 v98, v118, v120
	v_add_f32_e32 v110, v110, v119
	v_cndmask_b32_e64 v118, v110, v98, s[6:7]
	ds_bpermute_b32 v118, v130, v118
	v_cndmask_b32_e64 v98, v98, v110, s[6:7]
	s_waitcnt lgkmcnt(0)
	v_add_f32_e32 v98, v98, v118
	v_mul_f32_e32 v98, v117, v98
.LBB0_623:
	s_or_b64 exec, exec, s[4:5]
	v_max_f32_e32 v110, 0, v34
	v_max_f32_e32 v34, 0, v35
	v_mul_f32_e32 v34, v34, v77
	v_fmac_f32_e32 v34, v110, v76
	v_max_f32_e32 v35, 0, v36
	v_fmac_f32_e32 v34, v35, v81
	v_max_f32_e32 v35, 0, v37
	v_fmac_f32_e32 v34, v35, v80
	v_max_f32_e32 v36, 0, v38
	v_max_f32_e32 v35, 0, v39
	v_mul_f32_e32 v35, v35, v77
	v_fmac_f32_e32 v35, v36, v76
	v_max_f32_e32 v36, 0, v40
	v_fmac_f32_e32 v35, v36, v81
	v_max_f32_e32 v36, 0, v41
	v_fmac_f32_e32 v35, v36, v80
	v_max_f32_e32 v37, 0, v42
	v_max_f32_e32 v36, 0, v43
	v_mul_f32_e32 v36, v36, v77
	v_fmac_f32_e32 v36, v37, v76
	v_max_f32_e32 v37, 0, v44
	v_fmac_f32_e32 v36, v37, v81
	v_max_f32_e32 v37, 0, v45
	v_fmac_f32_e32 v36, v37, v80
	v_max_f32_e32 v38, 0, v46
	v_max_f32_e32 v37, 0, v47
	v_mul_f32_e32 v37, v37, v77
	v_fmac_f32_e32 v37, v38, v76
	v_max_f32_e32 v38, 0, v48
	v_fmac_f32_e32 v37, v38, v81
	v_max_f32_e32 v38, 0, v49
	v_fmac_f32_e32 v37, v38, v80
	v_permlane32_swap_b32_e32 v34, v36
	s_nop 0
	v_permlane32_swap_b32_e32 v35, v37
	s_and_saveexec_b64 s[4:5], vcc
	s_cbranch_execz .LBB0_625
	v_add_f32_e32 v35, v35, v37
	v_add_f32_e32 v34, v34, v36
	v_cndmask_b32_e64 v36, v34, v35, s[6:7]
	ds_bpermute_b32 v36, v130, v36
	v_cndmask_b32_e64 v34, v35, v34, s[6:7]
	s_waitcnt lgkmcnt(0)
	v_add_f32_e32 v34, v34, v36
	v_mul_f32_e32 v99, v117, v34
; #define LAS __attribute__((address_space(3)))
; __device__ __forceinline__ f32x4 mfma16(bf16x8 a, bf16x8 b, f32x4 c) { return __builtin_amdgcn_mfma_f32_16x16x32_bf16(a, b, c, 0, 0, 0); }
; __device__ __forceinline__ void att_unit(LAS unsigned char* lds, const bf16* P, const bf16* AKV, const bf16* IKC, bf16* ACAT, const float* aqg, const float* ssq_ak, const float* ssq_ik, int b, int qg, int tid) {
;     ...
;                 for (int r4 = 0; r4 < 4; ++r4) {
;                     float pt[2][4];
; #pragma unroll
;                     for (int q4 = 0; q4 < 4; ++q4) {
;                         const LAS unsigned char* kp = IKc + (64 * r4 + 16 * q4 + fr) * 144 + fq * 16;
;                         const bf16x8 K0 = *(const LAS bf16x8*)kp, K1 = *(const LAS bf16x8*)(kp + 64);
; #pragma unroll
;                         for (int q = 0; q < 2; ++q) {
;                             f32x4 a = (f32x4){0.f, 0.f, 0.f, 0.f};
;                             a = mfma16(Qi[q][0], K0, a); a = mfma16(Qi[q][1], K1, a);
;                             pt[q][q4] = fmaxf(a[0], 0.f) * wv[q][0] + fmaxf(a[1], 0.f) * wv[q][1] + fmaxf(a[2], 0.f) * wv[q][2] + fmaxf(a[3], 0.f) * wv[q][3];
;                         }
;                     }
;                     const int rr = 4 * tile + r4;
;                     const float rscale = rsqrtf((rc[r4].x + rc[r4].y) * (1.f / 64.f) + EPS);
;                     const bool live = 64 * rr + lane < L;
; #pragma unroll
;                     for (int q = 0; q < 2; ++q) {
;                         float hx; const float A = half_sum32(pt[q][0], pt[q][2], hx), B = half_sum32(pt[q][1], pt[q][3], hx);
;                         const bool odd = fq & 1;
;                         const float send = odd ? A : B, keep = odd ? B : A;
;                         const float sc = live ? (keep + __shfl_xor(send, 16)) * rscale : -INFINITY;
;                         const unsigned bts = __float_as_uint(sc);
;                         uk[q][rr] = bts ^ ((unsigned)((int)bts >> 31) | 0x80000000u);
;                     }
.LBB0_625:
	s_or_b64 exec, exec, s[4:5]
	ds_read_b128 v[34:37], v131 offset:18432
	ds_read_b128 v[38:41], v131 offset:18496
	ds_read_b128 v[46:49], v131 offset:20736
	ds_read_b128 v[134:137], v131 offset:20800
	v_add_f32_e32 v96, v96, v97
	v_fmamk_f32 v96, v96, 0x3c800000, v222
	s_waitcnt lgkmcnt(3)
	v_mfma_f32_16x16x32_bf16 v[42:45], v[14:17], v[34:37], 0
	v_mul_f32_e32 v97, 0x4b800000, v96
	v_cmp_gt_f32_e32 vcc, s18, v96
	s_waitcnt lgkmcnt(2)
	v_mfma_f32_16x16x32_bf16 v[42:45], v[10:13], v[38:41], v[42:45]
	v_cndmask_b32_e32 v96, v96, v97, vcc
	v_rsq_f32_e32 v96, v96
	v_mfma_f32_16x16x32_bf16 v[34:37], v[2:5], v[34:37], 0
	v_mfma_f32_16x16x32_bf16 v[34:37], v[6:9], v[38:41], v[34:37]
	s_nop 3
	v_max_f32_e32 v42, v42, v42
	v_max_f32_e32 v43, v43, v43
	v_max_f32_e32 v44, v44, v44
	v_max_f32_e32 v117, 0, v45
	v_max_f32_e32 v118, 0, v42
	v_max_f32_e32 v110, 0, v43
	v_max_f32_e32 v119, 0, v44
	s_waitcnt lgkmcnt(1)
	v_mfma_f32_16x16x32_bf16 v[42:45], v[14:17], v[46:49], 0
	v_mul_f32_e32 v110, v110, v75
	v_fmac_f32_e32 v110, v118, v74
	v_fmac_f32_e32 v110, v119, v79
	s_waitcnt lgkmcnt(0)
	v_mfma_f32_16x16x32_bf16 v[42:45], v[10:13], v[134:137], v[42:45]
	v_fmac_f32_e32 v110, v117, v78
	s_nop 5
	s_nop 0
	v_max_f32_e32 v38, 0, v43
	v_mul_f32_e32 v118, v38, v75
	v_mfma_f32_16x16x32_bf16 v[38:41], v[2:5], v[46:49], 0
	ds_read_b128 v[46:49], v131 offset:23040
	v_max_f32_e32 v42, 0, v42
	v_mfma_f32_16x16x32_bf16 v[38:41], v[6:9], v[134:137], v[38:41]
	ds_read_b128 v[134:137], v131 offset:23104
	v_fmac_f32_e32 v118, v42, v74
	s_waitcnt lgkmcnt(1)
	v_mfma_f32_16x16x32_bf16 v[142:145], v[14:17], v[46:49], 0
	v_max_f32_e32 v42, 0, v44
	v_fmac_f32_e32 v118, v42, v79
	s_waitcnt lgkmcnt(0)
	v_mfma_f32_16x16x32_bf16 v[142:145], v[10:13], v[134:137], v[142:145]
	v_max_f32_e32 v42, 0, v45
	v_fmac_f32_e32 v118, v42, v78
	s_nop 5
	v_max_f32_e32 v117, 0, v142
	v_max_f32_e32 v42, 0, v143
	v_mul_f32_e32 v119, v42, v75
	v_mfma_f32_16x16x32_bf16 v[42:45], v[2:5], v[46:49], 0
	ds_read_b128 v[46:49], v131 offset:25344
	v_fmac_f32_e32 v119, v117, v74
	v_mfma_f32_16x16x32_bf16 v[42:45], v[6:9], v[134:137], v[42:45]
	ds_read_b128 v[134:137], v131 offset:25408
	v_max_f32_e32 v117, 0, v144
	v_fmac_f32_e32 v119, v117, v79
	s_waitcnt lgkmcnt(1)
	v_mfma_f32_16x16x32_bf16 v[158:161], v[14:17], v[46:49], 0
	v_max_f32_e32 v117, 0, v145
	v_fmac_f32_e32 v119, v117, v78
	s_waitcnt lgkmcnt(0)
	v_mfma_f32_16x16x32_bf16 v[142:145], v[10:13], v[134:137], v[158:161]
	v_permlane32_swap_b32_e32 v110, v119
	v_mfma_f32_16x16x32_bf16 v[46:49], v[2:5], v[46:49], 0
	v_mfma_f32_16x16x32_bf16 v[46:49], v[6:9], v[134:137], v[46:49]
	s_nop 4
	v_max_f32_e32 v120, 0, v143
	v_max_f32_e32 v117, 0, v142
	v_mul_f32_e32 v120, v120, v75
	v_fmac_f32_e32 v120, v117, v74
	v_max_f32_e32 v117, 0, v144
	v_fmac_f32_e32 v120, v117, v79
	v_max_f32_e32 v97, 0, v145
	v_fmac_f32_e32 v120, v97, v78
	v_mul_f32_e32 v97, 0x45800000, v96
	v_cndmask_b32_e32 v117, v96, v97, vcc
	v_or_b32_e32 v96, 0x280, v124
	v_cmp_gt_u32_e32 vcc, s81, v96
	v_permlane32_swap_b32_e32 v118, v120
	v_mov_b32_e32 v97, 0xff800000
	v_mov_b32_e32 v96, 0xff800000
	s_and_saveexec_b64 s[4:5], vcc
	s_cbranch_execz .LBB0_627
	v_add_f32_e32 v96, v118, v120
	v_add_f32_e32 v110, v110, v119
	v_cndmask_b32_e64 v118, v110, v96, s[6:7]
	ds_bpermute_b32 v118, v130, v118
	v_cndmask_b32_e64 v96, v96, v110, s[6:7]
	s_waitcnt lgkmcnt(0)
	v_add_f32_e32 v96, v96, v118
	v_mul_f32_e32 v96, v117, v96
.LBB0_627:
	s_or_b64 exec, exec, s[4:5]
	v_max_f32_e32 v110, 0, v34
	v_max_f32_e32 v34, 0, v35
	v_mul_f32_e32 v34, v34, v77
	v_fmac_f32_e32 v34, v110, v76
	v_max_f32_e32 v35, 0, v36
	v_fmac_f32_e32 v34, v35, v81
	v_max_f32_e32 v35, 0, v37
	v_fmac_f32_e32 v34, v35, v80
	v_max_f32_e32 v36, 0, v38
	v_max_f32_e32 v35, 0, v39
	v_mul_f32_e32 v35, v35, v77
	v_fmac_f32_e32 v35, v36, v76
	v_max_f32_e32 v36, 0, v40
	v_fmac_f32_e32 v35, v36, v81
	v_max_f32_e32 v36, 0, v41
	v_fmac_f32_e32 v35, v36, v80
	v_max_f32_e32 v37, 0, v42
	v_max_f32_e32 v36, 0, v43
	v_mul_f32_e32 v36, v36, v77
	v_fmac_f32_e32 v36, v37, v76
	v_max_f32_e32 v37, 0, v44
	v_fmac_f32_e32 v36, v37, v81
	v_max_f32_e32 v37, 0, v45
	v_fmac_f32_e32 v36, v37, v80
	v_max_f32_e32 v38, 0, v46
	v_max_f32_e32 v37, 0, v47
	v_mul_f32_e32 v37, v37, v77
	v_fmac_f32_e32 v37, v38, v76
	v_max_f32_e32 v38, 0, v48
	v_fmac_f32_e32 v37, v38, v81
	v_max_f32_e32 v38, 0, v49
	v_fmac_f32_e32 v37, v38, v80
	v_permlane32_swap_b32_e32 v34, v36
	s_nop 0
	v_permlane32_swap_b32_e32 v35, v37
	s_and_saveexec_b64 s[4:5], vcc
	s_cbranch_execz .LBB0_629
	v_add_f32_e32 v35, v35, v37
	v_add_f32_e32 v34, v34, v36
	v_cndmask_b32_e64 v36, v34, v35, s[6:7]
	ds_bpermute_b32 v36, v130, v36
	v_cndmask_b32_e64 v34, v35, v34, s[6:7]
	s_waitcnt lgkmcnt(0)
	v_add_f32_e32 v34, v34, v36
	v_mul_f32_e32 v97, v117, v34
; #define LAS __attribute__((address_space(3)))
; __device__ __forceinline__ f32x4 mfma16(bf16x8 a, bf16x8 b, f32x4 c) { return __builtin_amdgcn_mfma_f32_16x16x32_bf16(a, b, c, 0, 0, 0); }
; __device__ __forceinline__ void att_unit(LAS unsigned char* lds, const bf16* P, const bf16* AKV, const bf16* IKC, bf16* ACAT, const float* aqg, const float* ssq_ak, const float* ssq_ik, int b, int qg, int tid) {
;     ...
;                 for (int r4 = 0; r4 < 4; ++r4) {
;                     float pt[2][4];
; #pragma unroll
;                     for (int q4 = 0; q4 < 4; ++q4) {
;                         const LAS unsigned char* kp = IKc + (64 * r4 + 16 * q4 + fr) * 144 + fq * 16;
;                         const bf16x8 K0 = *(const LAS bf16x8*)kp, K1 = *(const LAS bf16x8*)(kp + 64);
; #pragma unroll
;                         for (int q = 0; q < 2; ++q) {
;                             f32x4 a = (f32x4){0.f, 0.f, 0.f, 0.f};
;                             a = mfma16(Qi[q][0], K0, a); a = mfma16(Qi[q][1], K1, a);
;                             pt[q][q4] = fmaxf(a[0], 0.f) * wv[q][0] + fmaxf(a[1], 0.f) * wv[q][1] + fmaxf(a[2], 0.f) * wv[q][2] + fmaxf(a[3], 0.f) * wv[q][3];
;                         }
;                     }
;                     const int rr = 4 * tile + r4;
;                     const float rscale = rsqrtf((rc[r4].x + rc[r4].y) * (1.f / 64.f) + EPS);
;                     const bool live = 64 * rr + lane < L;
; #pragma unroll
;                     for (int q = 0; q < 2; ++q) {
;                         float hx; const float A = half_sum32(pt[q][0], pt[q][2], hx), B = half_sum32(pt[q][1], pt[q][3], hx);
;                         const bool odd = fq & 1;
;                         const float send = odd ? A : B, keep = odd ? B : A;
;                         const float sc = live ? (keep + __shfl_xor(send, 16)) * rscale : -INFINITY;
;                         const unsigned bts = __float_as_uint(sc);
;                         uk[q][rr] = bts ^ ((unsigned)((int)bts >> 31) | 0x80000000u);
;                     }
.LBB0_629:
	s_or_b64 exec, exec, s[4:5]
	ds_read_b128 v[34:37], v131 offset:27648
	ds_read_b128 v[38:41], v131 offset:27712
	ds_read_b128 v[46:49], v131 offset:29952
	ds_read_b128 v[134:137], v131 offset:30016
	v_add_f32_e32 v90, v90, v91
	v_fmamk_f32 v90, v90, 0x3c800000, v222
	s_waitcnt lgkmcnt(3)
	v_mfma_f32_16x16x32_bf16 v[42:45], v[14:17], v[34:37], 0
	v_mul_f32_e32 v91, 0x4b800000, v90
	v_cmp_gt_f32_e32 vcc, s18, v90
	s_waitcnt lgkmcnt(2)
	v_mfma_f32_16x16x32_bf16 v[42:45], v[10:13], v[38:41], v[42:45]
	v_cndmask_b32_e32 v90, v90, v91, vcc
	v_rsq_f32_e32 v90, v90
	v_mfma_f32_16x16x32_bf16 v[34:37], v[2:5], v[34:37], 0
	v_mfma_f32_16x16x32_bf16 v[34:37], v[6:9], v[38:41], v[34:37]
	s_nop 3
	v_max_f32_e32 v42, v42, v42
	v_max_f32_e32 v43, v43, v43
	v_max_f32_e32 v44, v44, v44
	v_max_f32_e32 v117, 0, v45
	v_max_f32_e32 v118, 0, v42
	v_max_f32_e32 v110, 0, v43
	v_max_f32_e32 v119, 0, v44
	s_waitcnt lgkmcnt(1)
	v_mfma_f32_16x16x32_bf16 v[42:45], v[14:17], v[46:49], 0
	v_mul_f32_e32 v110, v110, v75
	v_fmac_f32_e32 v110, v118, v74
	v_fmac_f32_e32 v110, v119, v79
	s_waitcnt lgkmcnt(0)
	v_mfma_f32_16x16x32_bf16 v[42:45], v[10:13], v[134:137], v[42:45]
	v_fmac_f32_e32 v110, v117, v78
	s_nop 5
	s_nop 0
	v_max_f32_e32 v38, 0, v43
	v_mul_f32_e32 v118, v38, v75
	v_mfma_f32_16x16x32_bf16 v[38:41], v[2:5], v[46:49], 0
	ds_read_b128 v[46:49], v131 offset:32256
	v_max_f32_e32 v42, 0, v42
	v_mfma_f32_16x16x32_bf16 v[38:41], v[6:9], v[134:137], v[38:41]
	ds_read_b128 v[134:137], v131 offset:32320
	v_fmac_f32_e32 v118, v42, v74
	s_waitcnt lgkmcnt(1)
	v_mfma_f32_16x16x32_bf16 v[142:145], v[14:17], v[46:49], 0
	v_max_f32_e32 v42, 0, v44
	v_fmac_f32_e32 v118, v42, v79
	s_waitcnt lgkmcnt(0)
	v_mfma_f32_16x16x32_bf16 v[142:145], v[10:13], v[134:137], v[142:145]
	v_max_f32_e32 v42, 0, v45
	v_fmac_f32_e32 v118, v42, v78
	s_nop 5
	v_max_f32_e32 v117, 0, v142
	v_max_f32_e32 v42, 0, v143
	v_mul_f32_e32 v119, v42, v75
	v_mfma_f32_16x16x32_bf16 v[42:45], v[2:5], v[46:49], 0
	ds_read_b128 v[46:49], v131 offset:34560
	v_fmac_f32_e32 v119, v117, v74
	v_mfma_f32_16x16x32_bf16 v[42:45], v[6:9], v[134:137], v[42:45]
	ds_read_b128 v[134:137], v131 offset:34624
	v_max_f32_e32 v117, 0, v144
	v_fmac_f32_e32 v119, v117, v79
	s_waitcnt lgkmcnt(1)
	v_mfma_f32_16x16x32_bf16 v[158:161], v[14:17], v[46:49], 0
	v_max_f32_e32 v117, 0, v145
	v_fmac_f32_e32 v119, v117, v78
	s_waitcnt lgkmcnt(0)
	v_mfma_f32_16x16x32_bf16 v[142:145], v[10:13], v[134:137], v[158:161]
	v_permlane32_swap_b32_e32 v110, v119
	v_mfma_f32_16x16x32_bf16 v[46:49], v[2:5], v[46:49], 0
	v_mfma_f32_16x16x32_bf16 v[46:49], v[6:9], v[134:137], v[46:49]
	s_nop 4
	v_max_f32_e32 v120, 0, v143
	v_max_f32_e32 v117, 0, v142
	v_mul_f32_e32 v120, v120, v75
	v_fmac_f32_e32 v120, v117, v74
	v_max_f32_e32 v117, 0, v144
	v_fmac_f32_e32 v120, v117, v79
	v_max_f32_e32 v91, 0, v145
	v_fmac_f32_e32 v120, v91, v78
	v_mul_f32_e32 v91, 0x45800000, v90
	v_cndmask_b32_e32 v117, v90, v91, vcc
	v_or_b32_e32 v90, 0x2c0, v124
	v_cmp_gt_u32_e32 vcc, s81, v90
	v_permlane32_swap_b32_e32 v118, v120
	v_mov_b32_e32 v91, 0xff800000
	v_mov_b32_e32 v90, 0xff800000
	s_and_saveexec_b64 s[4:5], vcc
	s_cbranch_execz .LBB0_631
	v_add_f32_e32 v90, v118, v120
	v_add_f32_e32 v110, v110, v119
	v_cndmask_b32_e64 v118, v110, v90, s[6:7]
	ds_bpermute_b32 v118, v130, v118
	v_cndmask_b32_e64 v90, v90, v110, s[6:7]
	s_waitcnt lgkmcnt(0)
	v_add_f32_e32 v90, v90, v118
	v_mul_f32_e32 v90, v117, v90
.LBB0_631:
	s_or_b64 exec, exec, s[4:5]
	v_max_f32_e32 v110, 0, v34
	v_max_f32_e32 v34, 0, v35
	v_mul_f32_e32 v34, v34, v77
	v_fmac_f32_e32 v34, v110, v76
	v_max_f32_e32 v35, 0, v36
	v_fmac_f32_e32 v34, v35, v81
	v_max_f32_e32 v35, 0, v37
	v_fmac_f32_e32 v34, v35, v80
	v_max_f32_e32 v36, 0, v38
	v_max_f32_e32 v35, 0, v39
	v_mul_f32_e32 v35, v35, v77
	v_fmac_f32_e32 v35, v36, v76
	v_max_f32_e32 v36, 0, v40
	v_fmac_f32_e32 v35, v36, v81
	v_max_f32_e32 v36, 0, v41
	v_fmac_f32_e32 v35, v36, v80
	v_max_f32_e32 v37, 0, v42
	v_max_f32_e32 v36, 0, v43
	v_mul_f32_e32 v36, v36, v77
	v_fmac_f32_e32 v36, v37, v76
	v_max_f32_e32 v37, 0, v44
	v_fmac_f32_e32 v36, v37, v81
	v_max_f32_e32 v37, 0, v45
	v_fmac_f32_e32 v36, v37, v80
	v_max_f32_e32 v38, 0, v46
	v_max_f32_e32 v37, 0, v47
	v_mul_f32_e32 v37, v37, v77
	v_fmac_f32_e32 v37, v38, v76
	v_max_f32_e32 v38, 0, v48
	v_fmac_f32_e32 v37, v38, v81
	v_max_f32_e32 v38, 0, v49
	v_fmac_f32_e32 v37, v38, v80
	v_permlane32_swap_b32_e32 v34, v36
	s_nop 0
	v_permlane32_swap_b32_e32 v35, v37
	s_and_saveexec_b64 s[4:5], vcc
	s_cbranch_execz .LBB0_633
	v_add_f32_e32 v35, v35, v37
	v_add_f32_e32 v34, v34, v36
	v_cndmask_b32_e64 v36, v34, v35, s[6:7]
	ds_bpermute_b32 v36, v130, v36
	v_cndmask_b32_e64 v34, v35, v34, s[6:7]
	s_waitcnt lgkmcnt(0)
	v_add_f32_e32 v34, v34, v36
	v_mul_f32_e32 v91, v117, v34

; #define LAS __attribute__((address_space(3)))
; __device__ __forceinline__ f32x4 mfma16(bf16x8 a, bf16x8 b, f32x4 c) { return __builtin_amdgcn_mfma_f32_16x16x32_bf16(a, b, c, 0, 0, 0); }
; __device__ __forceinline__ void att_unit(LAS unsigned char* lds, const bf16* P, const bf16* AKV, const bf16* IKC, bf16* ACAT, const float* aqg, const float* ssq_ak, const float* ssq_ik, int b, int qg, int tid) {
;     ...
;                 for (int r4 = 0; r4 < 4; ++r4) {
;                     float pt[2][4];
; #pragma unroll
;                     for (int q4 = 0; q4 < 4; ++q4) {
;                         const LAS unsigned char* kp = IKc + (64 * r4 + 16 * q4 + fr) * 144 + fq * 16;
;                         const bf16x8 K0 = *(const LAS bf16x8*)kp, K1 = *(const LAS bf16x8*)(kp + 64);
; #pragma unroll
;                         for (int q = 0; q < 2; ++q) {
;                             f32x4 a = (f32x4){0.f, 0.f, 0.f, 0.f};
;                             a = mfma16(Qi[q][0], K0, a); a = mfma16(Qi[q][1], K1, a);
;                             pt[q][q4] = fmaxf(a[0], 0.f) * wv[q][0] + fmaxf(a[1], 0.f) * wv[q][1] + fmaxf(a[2], 0.f) * wv[q][2] + fmaxf(a[3], 0.f) * wv[q][3];
;                         }
;                     }
;                     const int rr = 4 * tile + r4;
;                     const float rscale = rsqrtf((rc[r4].x + rc[r4].y) * (1.f / 64.f) + EPS);
;                     const bool live = 64 * rr + lane < L;
; #pragma unroll
;                     for (int q = 0; q < 2; ++q) {
;                         float hx; const float A = half_sum32(pt[q][0], pt[q][2], hx), B = half_sum32(pt[q][1], pt[q][3], hx);
;                         const bool odd = fq & 1;
;                         const float send = odd ? A : B, keep = odd ? B : A;
;                         const float sc = live ? (keep + __shfl_xor(send, 16)) * rscale : -INFINITY;
;                         const unsigned bts = __float_as_uint(sc);
;                         uk[q][rr] = bts ^ ((unsigned)((int)bts >> 31) | 0x80000000u);
;                     }
.LBB0_639:
	s_or_b64 exec, exec, s[4:5]
	ds_read_b128 v[34:37], v131 offset:36864
	ds_read_b128 v[38:41], v131 offset:36928
	ds_read_b128 v[46:49], v131 offset:39168
	ds_read_b128 v[136:139], v131 offset:39232
	v_add_f32_e32 v102, v102, v103
	v_fmamk_f32 v102, v102, 0x3c800000, v222
	s_waitcnt lgkmcnt(3)
	v_mfma_f32_16x16x32_bf16 v[42:45], v[14:17], v[34:37], 0
	v_mul_f32_e32 v103, 0x4b800000, v102
	v_cmp_gt_f32_e32 vcc, s18, v102
	ds_read_b128 v[162:165], v131 offset:43840
	s_waitcnt lgkmcnt(3)
	v_mfma_f32_16x16x32_bf16 v[42:45], v[10:13], v[38:41], v[42:45]
	v_cndmask_b32_e32 v102, v102, v103, vcc
	v_rsq_f32_e32 v102, v102
	v_mfma_f32_16x16x32_bf16 v[34:37], v[2:5], v[34:37], 0
	v_mfma_f32_16x16x32_bf16 v[34:37], v[6:9], v[38:41], v[34:37]
	s_nop 3
	v_max_f32_e32 v42, v42, v42
	v_max_f32_e32 v43, v43, v43
	v_max_f32_e32 v44, v44, v44
	v_max_f32_e32 v133, 0, v45
	v_max_f32_e32 v134, 0, v42
	v_max_f32_e32 v123, 0, v43
	v_max_f32_e32 v135, 0, v44
	s_waitcnt lgkmcnt(2)
	v_mfma_f32_16x16x32_bf16 v[42:45], v[14:17], v[46:49], 0
	v_mul_f32_e32 v123, v123, v75
	v_fmac_f32_e32 v123, v134, v74
	v_fmac_f32_e32 v123, v135, v79
	s_waitcnt lgkmcnt(1)
	v_mfma_f32_16x16x32_bf16 v[42:45], v[10:13], v[136:139], v[42:45]
	v_fmac_f32_e32 v123, v133, v78
	s_nop 5
	s_nop 0
	v_max_f32_e32 v38, 0, v43
	v_mul_f32_e32 v134, v38, v75
	v_mfma_f32_16x16x32_bf16 v[38:41], v[2:5], v[46:49], 0
	ds_read_b128 v[46:49], v131 offset:41472
	v_max_f32_e32 v42, 0, v42
	v_mfma_f32_16x16x32_bf16 v[38:41], v[6:9], v[136:139], v[38:41]
	ds_read_b128 v[136:139], v131 offset:41536
	v_fmac_f32_e32 v134, v42, v74
	s_waitcnt lgkmcnt(1)
	v_mfma_f32_16x16x32_bf16 v[158:161], v[14:17], v[46:49], 0
	v_max_f32_e32 v42, 0, v44
	v_fmac_f32_e32 v134, v42, v79
	s_waitcnt lgkmcnt(0)
	v_mfma_f32_16x16x32_bf16 v[158:161], v[10:13], v[136:139], v[158:161]
	v_max_f32_e32 v42, 0, v45
	v_fmac_f32_e32 v134, v42, v78
	s_nop 5
	v_max_f32_e32 v133, 0, v158
	v_max_f32_e32 v42, 0, v159
	v_mul_f32_e32 v135, v42, v75
	v_mfma_f32_16x16x32_bf16 v[42:45], v[2:5], v[46:49], 0
	ds_read_b128 v[46:49], v131 offset:43776
	v_fmac_f32_e32 v135, v133, v74
	v_mfma_f32_16x16x32_bf16 v[42:45], v[6:9], v[136:139], v[42:45]
	v_max_f32_e32 v133, 0, v160
	v_fmac_f32_e32 v135, v133, v79
	s_waitcnt lgkmcnt(0)
	v_mfma_f32_16x16x32_bf16 v[136:139], v[14:17], v[46:49], 0
	v_max_f32_e32 v133, 0, v161
	v_fmac_f32_e32 v135, v133, v78
	s_nop 1
	v_permlane32_swap_b32_e32 v123, v135
	v_mfma_f32_16x16x32_bf16 v[136:139], v[10:13], v[162:165], v[136:139]
	v_mfma_f32_16x16x32_bf16 v[46:49], v[2:5], v[46:49], 0
	v_mfma_f32_16x16x32_bf16 v[46:49], v[6:9], v[162:165], v[46:49]
	s_nop 5
	v_max_f32_e32 v133, 0, v136
	v_max_f32_e32 v136, 0, v137
	v_mul_f32_e32 v136, v136, v75
	v_fmac_f32_e32 v136, v133, v74
	v_max_f32_e32 v133, 0, v138
	v_fmac_f32_e32 v136, v133, v79
	v_max_f32_e32 v103, 0, v139
	v_fmac_f32_e32 v136, v103, v78
	v_mul_f32_e32 v103, 0x45800000, v102
	v_cndmask_b32_e32 v133, v102, v103, vcc
	v_or_b32_e32 v102, 0x300, v124
	v_cmp_gt_u32_e32 vcc, s81, v102
	v_permlane32_swap_b32_e32 v134, v136
	v_mov_b32_e32 v103, 0xff800000
	v_mov_b32_e32 v102, 0xff800000
	s_and_saveexec_b64 s[4:5], vcc
	s_cbranch_execz .LBB0_641
	v_add_f32_e32 v102, v134, v136
	v_add_f32_e32 v123, v123, v135
	v_cndmask_b32_e64 v134, v123, v102, s[6:7]
	ds_bpermute_b32 v134, v130, v134
	v_cndmask_b32_e64 v102, v102, v123, s[6:7]
	s_waitcnt lgkmcnt(0)
	v_add_f32_e32 v102, v102, v134
	v_mul_f32_e32 v102, v133, v102
.LBB0_641:
	s_or_b64 exec, exec, s[4:5]
	v_max_f32_e32 v123, 0, v34
	v_max_f32_e32 v34, 0, v35
	v_mul_f32_e32 v34, v34, v77
	v_fmac_f32_e32 v34, v123, v76
	v_max_f32_e32 v35, 0, v36
	v_fmac_f32_e32 v34, v35, v81
	v_max_f32_e32 v35, 0, v37
	v_fmac_f32_e32 v34, v35, v80
	v_max_f32_e32 v36, 0, v38
	v_max_f32_e32 v35, 0, v39
	v_mul_f32_e32 v35, v35, v77
	v_fmac_f32_e32 v35, v36, v76
	v_max_f32_e32 v36, 0, v40
	v_fmac_f32_e32 v35, v36, v81
	v_max_f32_e32 v36, 0, v41
	v_fmac_f32_e32 v35, v36, v80
	v_max_f32_e32 v37, 0, v42
	v_max_f32_e32 v36, 0, v43
	v_mul_f32_e32 v36, v36, v77
	v_fmac_f32_e32 v36, v37, v76
	v_max_f32_e32 v37, 0, v44
	v_fmac_f32_e32 v36, v37, v81
	v_max_f32_e32 v37, 0, v45
	v_fmac_f32_e32 v36, v37, v80
	v_max_f32_e32 v38, 0, v46
	v_max_f32_e32 v37, 0, v47
	v_mul_f32_e32 v37, v37, v77
	v_fmac_f32_e32 v37, v38, v76
	v_max_f32_e32 v38, 0, v48
	v_fmac_f32_e32 v37, v38, v81
	v_max_f32_e32 v38, 0, v49
	v_fmac_f32_e32 v37, v38, v80
	v_permlane32_swap_b32_e32 v34, v36
	s_nop 0
	v_permlane32_swap_b32_e32 v35, v37
	s_and_saveexec_b64 s[4:5], vcc
	s_cbranch_execz .LBB0_643
	v_add_f32_e32 v35, v35, v37
	v_add_f32_e32 v34, v34, v36
	v_cndmask_b32_e64 v36, v34, v35, s[6:7]
	ds_bpermute_b32 v36, v130, v36
	v_cndmask_b32_e64 v34, v35, v34, s[6:7]
	s_waitcnt lgkmcnt(0)
	v_add_f32_e32 v34, v34, v36
	v_mul_f32_e32 v103, v133, v34
; #define LAS __attribute__((address_space(3)))
; __device__ __forceinline__ f32x4 mfma16(bf16x8 a, bf16x8 b, f32x4 c) { return __builtin_amdgcn_mfma_f32_16x16x32_bf16(a, b, c, 0, 0, 0); }
; __device__ __forceinline__ void att_unit(LAS unsigned char* lds, const bf16* P, const bf16* AKV, const bf16* IKC, bf16* ACAT, const float* aqg, const float* ssq_ak, const float* ssq_ik, int b, int qg, int tid) {
;     ...
;                 for (int r4 = 0; r4 < 4; ++r4) {
;                     float pt[2][4];
; #pragma unroll
;                     for (int q4 = 0; q4 < 4; ++q4) {
;                         const LAS unsigned char* kp = IKc + (64 * r4 + 16 * q4 + fr) * 144 + fq * 16;
;                         const bf16x8 K0 = *(const LAS bf16x8*)kp, K1 = *(const LAS bf16x8*)(kp + 64);
; #pragma unroll
;                         for (int q = 0; q < 2; ++q) {
;                             f32x4 a = (f32x4){0.f, 0.f, 0.f, 0.f};
;                             a = mfma16(Qi[q][0], K0, a); a = mfma16(Qi[q][1], K1, a);
;                             pt[q][q4] = fmaxf(a[0], 0.f) * wv[q][0] + fmaxf(a[1], 0.f) * wv[q][1] + fmaxf(a[2], 0.f) * wv[q][2] + fmaxf(a[3], 0.f) * wv[q][3];
;                         }
;                     }
;                     const int rr = 4 * tile + r4;
;                     const float rscale = rsqrtf((rc[r4].x + rc[r4].y) * (1.f / 64.f) + EPS);
;                     const bool live = 64 * rr + lane < L;
; #pragma unroll
;                     for (int q = 0; q < 2; ++q) {
;                         float hx; const float A = half_sum32(pt[q][0], pt[q][2], hx), B = half_sum32(pt[q][1], pt[q][3], hx);
;                         const bool odd = fq & 1;
;                         const float send = odd ? A : B, keep = odd ? B : A;
;                         const float sc = live ? (keep + __shfl_xor(send, 16)) * rscale : -INFINITY;
;                         const unsigned bts = __float_as_uint(sc);
;                         uk[q][rr] = bts ^ ((unsigned)((int)bts >> 31) | 0x80000000u);
;                     }
.LBB0_643:
	s_or_b64 exec, exec, s[4:5]
	ds_read_b128 v[34:37], v131 offset:46080
	ds_read_b128 v[38:41], v131 offset:46144
	ds_read_b128 v[46:49], v131 offset:48384
	ds_read_b128 v[136:139], v131 offset:48448
	v_add_f32_e32 v98, v98, v99
	v_fmamk_f32 v98, v98, 0x3c800000, v222
	s_waitcnt lgkmcnt(3)
	v_mfma_f32_16x16x32_bf16 v[42:45], v[14:17], v[34:37], 0
	v_mul_f32_e32 v99, 0x4b800000, v98
	v_cmp_gt_f32_e32 vcc, s18, v98
	ds_read_b128 v[162:165], v131 offset:53056
	s_waitcnt lgkmcnt(3)
	v_mfma_f32_16x16x32_bf16 v[42:45], v[10:13], v[38:41], v[42:45]
	v_cndmask_b32_e32 v98, v98, v99, vcc
	v_rsq_f32_e32 v98, v98
	v_mfma_f32_16x16x32_bf16 v[34:37], v[2:5], v[34:37], 0
	v_mfma_f32_16x16x32_bf16 v[34:37], v[6:9], v[38:41], v[34:37]
	s_nop 3
	v_max_f32_e32 v42, v42, v42
	v_max_f32_e32 v43, v43, v43
	v_max_f32_e32 v44, v44, v44
	v_max_f32_e32 v133, 0, v45
	v_max_f32_e32 v134, 0, v42
	v_max_f32_e32 v123, 0, v43
	v_max_f32_e32 v135, 0, v44
	s_waitcnt lgkmcnt(2)
	v_mfma_f32_16x16x32_bf16 v[42:45], v[14:17], v[46:49], 0
	v_mul_f32_e32 v123, v123, v75
	v_fmac_f32_e32 v123, v134, v74
	v_fmac_f32_e32 v123, v135, v79
	s_waitcnt lgkmcnt(1)
	v_mfma_f32_16x16x32_bf16 v[42:45], v[10:13], v[136:139], v[42:45]
	v_fmac_f32_e32 v123, v133, v78
	s_nop 5
	s_nop 0
	v_max_f32_e32 v38, 0, v43
	v_mul_f32_e32 v134, v38, v75
	v_mfma_f32_16x16x32_bf16 v[38:41], v[2:5], v[46:49], 0
	ds_read_b128 v[46:49], v131 offset:50688
	v_max_f32_e32 v42, 0, v42
	v_mfma_f32_16x16x32_bf16 v[38:41], v[6:9], v[136:139], v[38:41]
	ds_read_b128 v[136:139], v131 offset:50752
	v_fmac_f32_e32 v134, v42, v74
	s_waitcnt lgkmcnt(1)
	v_mfma_f32_16x16x32_bf16 v[158:161], v[14:17], v[46:49], 0
	v_max_f32_e32 v42, 0, v44
	v_fmac_f32_e32 v134, v42, v79
	s_waitcnt lgkmcnt(0)
	v_mfma_f32_16x16x32_bf16 v[158:161], v[10:13], v[136:139], v[158:161]
	v_max_f32_e32 v42, 0, v45
	v_fmac_f32_e32 v134, v42, v78
	s_nop 5
	v_max_f32_e32 v133, 0, v158
	v_max_f32_e32 v42, 0, v159
	v_mul_f32_e32 v135, v42, v75
	v_mfma_f32_16x16x32_bf16 v[42:45], v[2:5], v[46:49], 0
	ds_read_b128 v[46:49], v131 offset:52992
	v_fmac_f32_e32 v135, v133, v74
	v_mfma_f32_16x16x32_bf16 v[42:45], v[6:9], v[136:139], v[42:45]
	v_max_f32_e32 v133, 0, v160
	v_fmac_f32_e32 v135, v133, v79
	s_waitcnt lgkmcnt(0)
	v_mfma_f32_16x16x32_bf16 v[136:139], v[14:17], v[46:49], 0
	v_max_f32_e32 v133, 0, v161
	v_fmac_f32_e32 v135, v133, v78
	s_nop 1
	v_permlane32_swap_b32_e32 v123, v135
	v_mfma_f32_16x16x32_bf16 v[136:139], v[10:13], v[162:165], v[136:139]
	v_mfma_f32_16x16x32_bf16 v[46:49], v[2:5], v[46:49], 0
	v_mfma_f32_16x16x32_bf16 v[46:49], v[6:9], v[162:165], v[46:49]
	s_nop 5
	v_max_f32_e32 v133, 0, v136
	v_max_f32_e32 v136, 0, v137
	v_mul_f32_e32 v136, v136, v75
	v_fmac_f32_e32 v136, v133, v74
	v_max_f32_e32 v133, 0, v138
	v_fmac_f32_e32 v136, v133, v79
	v_max_f32_e32 v99, 0, v139
	v_fmac_f32_e32 v136, v99, v78
	v_mul_f32_e32 v99, 0x45800000, v98
	v_cndmask_b32_e32 v133, v98, v99, vcc
	v_or_b32_e32 v98, 0x340, v124
	v_cmp_gt_u32_e32 vcc, s81, v98
	v_permlane32_swap_b32_e32 v134, v136
	v_mov_b32_e32 v99, 0xff800000
	v_mov_b32_e32 v98, 0xff800000
	s_and_saveexec_b64 s[4:5], vcc
	s_cbranch_execz .LBB0_645
	v_add_f32_e32 v98, v134, v136
	v_add_f32_e32 v123, v123, v135
	v_cndmask_b32_e64 v134, v123, v98, s[6:7]
	ds_bpermute_b32 v134, v130, v134
	v_cndmask_b32_e64 v98, v98, v123, s[6:7]
	s_waitcnt lgkmcnt(0)
	v_add_f32_e32 v98, v98, v134
	v_mul_f32_e32 v98, v133, v98
.LBB0_645:
	s_or_b64 exec, exec, s[4:5]
	v_max_f32_e32 v123, 0, v34
	v_max_f32_e32 v34, 0, v35
	v_mul_f32_e32 v34, v34, v77
	v_fmac_f32_e32 v34, v123, v76
	v_max_f32_e32 v35, 0, v36
	v_fmac_f32_e32 v34, v35, v81
	v_max_f32_e32 v35, 0, v37
	v_fmac_f32_e32 v34, v35, v80
	v_max_f32_e32 v36, 0, v38
	v_max_f32_e32 v35, 0, v39
	v_mul_f32_e32 v35, v35, v77
	v_fmac_f32_e32 v35, v36, v76
	v_max_f32_e32 v36, 0, v40
	v_fmac_f32_e32 v35, v36, v81
	v_max_f32_e32 v36, 0, v41
	v_fmac_f32_e32 v35, v36, v80
	v_max_f32_e32 v37, 0, v42
	v_max_f32_e32 v36, 0, v43
	v_mul_f32_e32 v36, v36, v77
	v_fmac_f32_e32 v36, v37, v76
	v_max_f32_e32 v37, 0, v44
	v_fmac_f32_e32 v36, v37, v81
	v_max_f32_e32 v37, 0, v45
	v_fmac_f32_e32 v36, v37, v80
	v_max_f32_e32 v38, 0, v46
	v_max_f32_e32 v37, 0, v47
	v_mul_f32_e32 v37, v37, v77
	v_fmac_f32_e32 v37, v38, v76
	v_max_f32_e32 v38, 0, v48
	v_fmac_f32_e32 v37, v38, v81
	v_max_f32_e32 v38, 0, v49
	v_fmac_f32_e32 v37, v38, v80
	v_permlane32_swap_b32_e32 v34, v36
	s_nop 0
	v_permlane32_swap_b32_e32 v35, v37
	s_and_saveexec_b64 s[4:5], vcc
	s_cbranch_execz .LBB0_647
	v_add_f32_e32 v35, v35, v37
	v_add_f32_e32 v34, v34, v36
	v_cndmask_b32_e64 v36, v34, v35, s[6:7]
	ds_bpermute_b32 v36, v130, v36
	v_cndmask_b32_e64 v34, v35, v34, s[6:7]
	s_waitcnt lgkmcnt(0)
	v_add_f32_e32 v34, v34, v36
	v_mul_f32_e32 v99, v133, v34
; #define LAS __attribute__((address_space(3)))
; __device__ __forceinline__ f32x4 mfma16(bf16x8 a, bf16x8 b, f32x4 c) { return __builtin_amdgcn_mfma_f32_16x16x32_bf16(a, b, c, 0, 0, 0); }
; __device__ __forceinline__ void att_unit(LAS unsigned char* lds, const bf16* P, const bf16* AKV, const bf16* IKC, bf16* ACAT, const float* aqg, const float* ssq_ak, const float* ssq_ik, int b, int qg, int tid) {
;     ...
;                 for (int r4 = 0; r4 < 4; ++r4) {
;                     float pt[2][4];
; #pragma unroll
;                     for (int q4 = 0; q4 < 4; ++q4) {
;                         const LAS unsigned char* kp = IKc + (64 * r4 + 16 * q4 + fr) * 144 + fq * 16;
;                         const bf16x8 K0 = *(const LAS bf16x8*)kp, K1 = *(const LAS bf16x8*)(kp + 64);
; #pragma unroll
;                         for (int q = 0; q < 2; ++q) {
;                             f32x4 a = (f32x4){0.f, 0.f, 0.f, 0.f};
;                             a = mfma16(Qi[q][0], K0, a); a = mfma16(Qi[q][1], K1, a);
;                             pt[q][q4] = fmaxf(a[0], 0.f) * wv[q][0] + fmaxf(a[1], 0.f) * wv[q][1] + fmaxf(a[2], 0.f) * wv[q][2] + fmaxf(a[3], 0.f) * wv[q][3];
;                         }
;                     }
;                     const int rr = 4 * tile + r4;
;                     const float rscale = rsqrtf((rc[r4].x + rc[r4].y) * (1.f / 64.f) + EPS);
;                     const bool live = 64 * rr + lane < L;
; #pragma unroll
;                     for (int q = 0; q < 2; ++q) {
;                         float hx; const float A = half_sum32(pt[q][0], pt[q][2], hx), B = half_sum32(pt[q][1], pt[q][3], hx);
;                         const bool odd = fq & 1;
;                         const float send = odd ? A : B, keep = odd ? B : A;
;                         const float sc = live ? (keep + __shfl_xor(send, 16)) * rscale : -INFINITY;
;                         const unsigned bts = __float_as_uint(sc);
;                         uk[q][rr] = bts ^ ((unsigned)((int)bts >> 31) | 0x80000000u);
;                     }
.LBB0_647:
	s_or_b64 exec, exec, s[4:5]
	ds_read_b128 v[34:37], v131 offset:55296
	ds_read_b128 v[38:41], v131 offset:55360
	ds_read_b128 v[46:49], v131 offset:57600
	ds_read_b128 v[136:139], v131 offset:57664
	v_add_f32_e32 v96, v96, v97
	v_fmamk_f32 v96, v96, 0x3c800000, v222
	s_waitcnt lgkmcnt(3)
	v_mfma_f32_16x16x32_bf16 v[42:45], v[14:17], v[34:37], 0
	v_mul_f32_e32 v97, 0x4b800000, v96
	v_cmp_gt_f32_e32 vcc, s18, v96
	ds_read_b128 v[162:165], v131 offset:62272
	s_waitcnt lgkmcnt(3)
	v_mfma_f32_16x16x32_bf16 v[42:45], v[10:13], v[38:41], v[42:45]
	v_cndmask_b32_e32 v96, v96, v97, vcc
	v_rsq_f32_e32 v96, v96
	v_mfma_f32_16x16x32_bf16 v[34:37], v[2:5], v[34:37], 0
	v_mfma_f32_16x16x32_bf16 v[34:37], v[6:9], v[38:41], v[34:37]
	s_nop 3
	v_max_f32_e32 v42, v42, v42
	v_max_f32_e32 v43, v43, v43
	v_max_f32_e32 v44, v44, v44
	v_max_f32_e32 v133, 0, v45
	v_max_f32_e32 v134, 0, v42
	v_max_f32_e32 v123, 0, v43
	v_max_f32_e32 v135, 0, v44
	s_waitcnt lgkmcnt(2)
	v_mfma_f32_16x16x32_bf16 v[42:45], v[14:17], v[46:49], 0
	v_mul_f32_e32 v123, v123, v75
	v_fmac_f32_e32 v123, v134, v74
	v_fmac_f32_e32 v123, v135, v79
	s_waitcnt lgkmcnt(1)
	v_mfma_f32_16x16x32_bf16 v[42:45], v[10:13], v[136:139], v[42:45]
	v_fmac_f32_e32 v123, v133, v78
	s_nop 5
	s_nop 0
	v_max_f32_e32 v38, 0, v43
	v_mul_f32_e32 v134, v38, v75
	v_mfma_f32_16x16x32_bf16 v[38:41], v[2:5], v[46:49], 0
	ds_read_b128 v[46:49], v131 offset:59904
	v_max_f32_e32 v42, 0, v42
	v_mfma_f32_16x16x32_bf16 v[38:41], v[6:9], v[136:139], v[38:41]
	ds_read_b128 v[136:139], v131 offset:59968
	v_fmac_f32_e32 v134, v42, v74
	s_waitcnt lgkmcnt(1)
	v_mfma_f32_16x16x32_bf16 v[158:161], v[14:17], v[46:49], 0
	v_max_f32_e32 v42, 0, v44
	v_fmac_f32_e32 v134, v42, v79
	s_waitcnt lgkmcnt(0)
	v_mfma_f32_16x16x32_bf16 v[158:161], v[10:13], v[136:139], v[158:161]
	v_max_f32_e32 v42, 0, v45
	v_fmac_f32_e32 v134, v42, v78
	s_nop 5
	v_max_f32_e32 v133, 0, v158
	v_max_f32_e32 v42, 0, v159
	v_mul_f32_e32 v135, v42, v75
	v_mfma_f32_16x16x32_bf16 v[42:45], v[2:5], v[46:49], 0
	ds_read_b128 v[46:49], v131 offset:62208
	v_fmac_f32_e32 v135, v133, v74
	v_mfma_f32_16x16x32_bf16 v[42:45], v[6:9], v[136:139], v[42:45]
	v_max_f32_e32 v133, 0, v160
	v_fmac_f32_e32 v135, v133, v79
	s_waitcnt lgkmcnt(0)
	v_mfma_f32_16x16x32_bf16 v[136:139], v[14:17], v[46:49], 0
	v_max_f32_e32 v133, 0, v161
	v_fmac_f32_e32 v135, v133, v78
	s_nop 1
	v_permlane32_swap_b32_e32 v123, v135
	v_mfma_f32_16x16x32_bf16 v[136:139], v[10:13], v[162:165], v[136:139]
	v_mfma_f32_16x16x32_bf16 v[46:49], v[2:5], v[46:49], 0
	v_mfma_f32_16x16x32_bf16 v[46:49], v[6:9], v[162:165], v[46:49]
	s_nop 5
	v_max_f32_e32 v133, 0, v136
	v_max_f32_e32 v136, 0, v137
	v_mul_f32_e32 v136, v136, v75
	v_fmac_f32_e32 v136, v133, v74
	v_max_f32_e32 v133, 0, v138
	v_fmac_f32_e32 v136, v133, v79
	v_max_f32_e32 v97, 0, v139
	v_fmac_f32_e32 v136, v97, v78
	v_mul_f32_e32 v97, 0x45800000, v96
	v_cndmask_b32_e32 v133, v96, v97, vcc
	v_or_b32_e32 v96, 0x380, v124
	v_cmp_gt_u32_e32 vcc, s81, v96
	v_permlane32_swap_b32_e32 v134, v136
	v_mov_b32_e32 v97, 0xff800000
	v_mov_b32_e32 v96, 0xff800000
	s_and_saveexec_b64 s[4:5], vcc
	s_cbranch_execz .LBB0_649
	v_add_f32_e32 v96, v134, v136
	v_add_f32_e32 v123, v123, v135
	v_cndmask_b32_e64 v134, v123, v96, s[6:7]
	ds_bpermute_b32 v134, v130, v134
	v_cndmask_b32_e64 v96, v96, v123, s[6:7]
	s_waitcnt lgkmcnt(0)
	v_add_f32_e32 v96, v96, v134
	v_mul_f32_e32 v96, v133, v96
.LBB0_649:
	s_or_b64 exec, exec, s[4:5]
	v_max_f32_e32 v123, 0, v34
	v_max_f32_e32 v34, 0, v35
	v_mul_f32_e32 v34, v34, v77
	v_fmac_f32_e32 v34, v123, v76
	v_max_f32_e32 v35, 0, v36
	v_fmac_f32_e32 v34, v35, v81
	v_max_f32_e32 v35, 0, v37
	v_fmac_f32_e32 v34, v35, v80
	v_max_f32_e32 v36, 0, v38
	v_max_f32_e32 v35, 0, v39
	v_mul_f32_e32 v35, v35, v77
	v_fmac_f32_e32 v35, v36, v76
	v_max_f32_e32 v36, 0, v40
	v_fmac_f32_e32 v35, v36, v81
	v_max_f32_e32 v36, 0, v41
	v_fmac_f32_e32 v35, v36, v80
	v_max_f32_e32 v37, 0, v42
	v_max_f32_e32 v36, 0, v43
	v_mul_f32_e32 v36, v36, v77
	v_fmac_f32_e32 v36, v37, v76
	v_max_f32_e32 v37, 0, v44
	v_fmac_f32_e32 v36, v37, v81
	v_max_f32_e32 v37, 0, v45
	v_fmac_f32_e32 v36, v37, v80
	v_max_f32_e32 v38, 0, v46
	v_max_f32_e32 v37, 0, v47
	v_mul_f32_e32 v37, v37, v77
	v_fmac_f32_e32 v37, v38, v76
	v_max_f32_e32 v38, 0, v48
	v_fmac_f32_e32 v37, v38, v81
	v_max_f32_e32 v38, 0, v49
	v_fmac_f32_e32 v37, v38, v80
	v_permlane32_swap_b32_e32 v34, v36
	s_nop 0
	v_permlane32_swap_b32_e32 v35, v37
	s_and_saveexec_b64 s[4:5], vcc
	s_cbranch_execz .LBB0_651
	v_add_f32_e32 v35, v35, v37
	v_add_f32_e32 v34, v34, v36
	v_cndmask_b32_e64 v36, v34, v35, s[6:7]
	ds_bpermute_b32 v36, v130, v36
	v_cndmask_b32_e64 v34, v35, v34, s[6:7]
	s_waitcnt lgkmcnt(0)
	v_add_f32_e32 v34, v34, v36
	v_mul_f32_e32 v97, v133, v34
; #define LAS __attribute__((address_space(3)))
; __device__ __forceinline__ f32x4 mfma16(bf16x8 a, bf16x8 b, f32x4 c) { return __builtin_amdgcn_mfma_f32_16x16x32_bf16(a, b, c, 0, 0, 0); }
; __device__ __forceinline__ void att_unit(LAS unsigned char* lds, const bf16* P, const bf16* AKV, const bf16* IKC, bf16* ACAT, const float* aqg, const float* ssq_ak, const float* ssq_ik, int b, int qg, int tid) {
;     ...
;                 for (int r4 = 0; r4 < 4; ++r4) {
;                     float pt[2][4];
; #pragma unroll
;                     for (int q4 = 0; q4 < 4; ++q4) {
;                         const LAS unsigned char* kp = IKc + (64 * r4 + 16 * q4 + fr) * 144 + fq * 16;
;                         const bf16x8 K0 = *(const LAS bf16x8*)kp, K1 = *(const LAS bf16x8*)(kp + 64);
; #pragma unroll
;                         for (int q = 0; q < 2; ++q) {
;                             f32x4 a = (f32x4){0.f, 0.f, 0.f, 0.f};
;                             a = mfma16(Qi[q][0], K0, a); a = mfma16(Qi[q][1], K1, a);
;                             pt[q][q4] = fmaxf(a[0], 0.f) * wv[q][0] + fmaxf(a[1], 0.f) * wv[q][1] + fmaxf(a[2], 0.f) * wv[q][2] + fmaxf(a[3], 0.f) * wv[q][3];
;                         }
;                     }
;                     const int rr = 4 * tile + r4;
;                     const float rscale = rsqrtf((rc[r4].x + rc[r4].y) * (1.f / 64.f) + EPS);
;                     const bool live = 64 * rr + lane < L;
; #pragma unroll
;                     for (int q = 0; q < 2; ++q) {
;                         float hx; const float A = half_sum32(pt[q][0], pt[q][2], hx), B = half_sum32(pt[q][1], pt[q][3], hx);
;                         const bool odd = fq & 1;
;                         const float send = odd ? A : B, keep = odd ? B : A;
;                         const float sc = live ? (keep + __shfl_xor(send, 16)) * rscale : -INFINITY;
;                         const unsigned bts = __float_as_uint(sc);
;                         uk[q][rr] = bts ^ ((unsigned)((int)bts >> 31) | 0x80000000u);
;                     }
.LBB0_651:
	s_or_b64 exec, exec, s[4:5]
	ds_read_b128 v[34:37], v131 offset:64512
	ds_read_b128 v[38:41], v131 offset:64576
	ds_read_b128 v[46:49], v152 offset:29952
	ds_read_b128 v[136:139], v152 offset:30016
	v_add_f32_e32 v90, v90, v91
	v_fmamk_f32 v90, v90, 0x3c800000, v222
	s_waitcnt lgkmcnt(3)
	v_mfma_f32_16x16x32_bf16 v[42:45], v[14:17], v[34:37], 0
	v_mul_f32_e32 v91, 0x4b800000, v90
	v_cmp_gt_f32_e32 vcc, s18, v90
	ds_read_b128 v[162:165], v152 offset:34624
	s_waitcnt lgkmcnt(3)
	v_mfma_f32_16x16x32_bf16 v[42:45], v[10:13], v[38:41], v[42:45]
	v_cndmask_b32_e32 v90, v90, v91, vcc
	v_rsq_f32_e32 v90, v90
	v_mfma_f32_16x16x32_bf16 v[34:37], v[2:5], v[34:37], 0
	v_mfma_f32_16x16x32_bf16 v[34:37], v[6:9], v[38:41], v[34:37]
	s_nop 3
	v_max_f32_e32 v42, v42, v42
	v_max_f32_e32 v43, v43, v43
	v_max_f32_e32 v44, v44, v44
	v_max_f32_e32 v133, 0, v45
	v_max_f32_e32 v134, 0, v42
	v_max_f32_e32 v123, 0, v43
	v_max_f32_e32 v135, 0, v44
	s_waitcnt lgkmcnt(2)
	v_mfma_f32_16x16x32_bf16 v[42:45], v[14:17], v[46:49], 0
	v_mul_f32_e32 v123, v123, v75
	v_fmac_f32_e32 v123, v134, v74
	v_fmac_f32_e32 v123, v135, v79
	s_waitcnt lgkmcnt(1)
	v_mfma_f32_16x16x32_bf16 v[42:45], v[10:13], v[136:139], v[42:45]
	v_fmac_f32_e32 v123, v133, v78
	s_nop 5
	s_nop 0
	v_max_f32_e32 v38, 0, v43
	v_mul_f32_e32 v134, v38, v75
	v_mfma_f32_16x16x32_bf16 v[38:41], v[2:5], v[46:49], 0
	ds_read_b128 v[46:49], v152 offset:32256
	v_max_f32_e32 v42, 0, v42
	v_mfma_f32_16x16x32_bf16 v[38:41], v[6:9], v[136:139], v[38:41]
	ds_read_b128 v[136:139], v152 offset:32320
	v_fmac_f32_e32 v134, v42, v74
	s_waitcnt lgkmcnt(1)
	v_mfma_f32_16x16x32_bf16 v[158:161], v[14:17], v[46:49], 0
	v_max_f32_e32 v42, 0, v44
	v_fmac_f32_e32 v134, v42, v79
	s_waitcnt lgkmcnt(0)
	v_mfma_f32_16x16x32_bf16 v[158:161], v[10:13], v[136:139], v[158:161]
	v_max_f32_e32 v42, 0, v45
	v_fmac_f32_e32 v134, v42, v78
	s_nop 5
	v_max_f32_e32 v133, 0, v158
	v_max_f32_e32 v42, 0, v159
	v_mul_f32_e32 v135, v42, v75
	v_mfma_f32_16x16x32_bf16 v[42:45], v[2:5], v[46:49], 0
	ds_read_b128 v[46:49], v152 offset:34560
	v_fmac_f32_e32 v135, v133, v74
	v_mfma_f32_16x16x32_bf16 v[42:45], v[6:9], v[136:139], v[42:45]
	v_max_f32_e32 v133, 0, v160
	v_fmac_f32_e32 v135, v133, v79
	s_waitcnt lgkmcnt(0)
	v_mfma_f32_16x16x32_bf16 v[136:139], v[14:17], v[46:49], 0
	v_max_f32_e32 v133, 0, v161
	v_fmac_f32_e32 v135, v133, v78
	s_nop 1
	v_permlane32_swap_b32_e32 v123, v135
	v_mfma_f32_16x16x32_bf16 v[136:139], v[10:13], v[162:165], v[136:139]
	v_mfma_f32_16x16x32_bf16 v[46:49], v[2:5], v[46:49], 0
	v_mfma_f32_16x16x32_bf16 v[46:49], v[6:9], v[162:165], v[46:49]
	s_nop 5
	v_max_f32_e32 v133, 0, v136
	v_max_f32_e32 v136, 0, v137
	v_mul_f32_e32 v136, v136, v75
	v_fmac_f32_e32 v136, v133, v74
	v_max_f32_e32 v133, 0, v138
	v_fmac_f32_e32 v136, v133, v79
	v_max_f32_e32 v91, 0, v139
	v_fmac_f32_e32 v136, v91, v78
	v_mul_f32_e32 v91, 0x45800000, v90
	v_cndmask_b32_e32 v133, v90, v91, vcc
	v_or_b32_e32 v90, 0x3c0, v124
	v_cmp_gt_u32_e32 vcc, s81, v90
	v_permlane32_swap_b32_e32 v134, v136
	v_mov_b32_e32 v91, 0xff800000
	v_mov_b32_e32 v90, 0xff800000
	s_and_saveexec_b64 s[4:5], vcc
	s_cbranch_execz .LBB0_653
	v_add_f32_e32 v90, v134, v136
	v_add_f32_e32 v123, v123, v135
	v_cndmask_b32_e64 v134, v123, v90, s[6:7]
	ds_bpermute_b32 v134, v130, v134
	v_cndmask_b32_e64 v90, v90, v123, s[6:7]
	s_waitcnt lgkmcnt(0)
	v_add_f32_e32 v90, v90, v134
	v_mul_f32_e32 v90, v133, v90
.LBB0_653:
	s_or_b64 exec, exec, s[4:5]
	v_max_f32_e32 v123, 0, v34
	v_max_f32_e32 v34, 0, v35
	v_mul_f32_e32 v34, v34, v77
	v_fmac_f32_e32 v34, v123, v76
	v_max_f32_e32 v35, 0, v36
	v_fmac_f32_e32 v34, v35, v81
	v_max_f32_e32 v35, 0, v37
	v_fmac_f32_e32 v34, v35, v80
	v_max_f32_e32 v36, 0, v38
	v_max_f32_e32 v35, 0, v39
	v_mul_f32_e32 v35, v35, v77
	v_fmac_f32_e32 v35, v36, v76
	v_max_f32_e32 v36, 0, v40
	v_fmac_f32_e32 v35, v36, v81
	v_max_f32_e32 v36, 0, v41
	v_fmac_f32_e32 v35, v36, v80
	v_max_f32_e32 v37, 0, v42
	v_max_f32_e32 v36, 0, v43
	v_mul_f32_e32 v36, v36, v77
	v_fmac_f32_e32 v36, v37, v76
	v_max_f32_e32 v37, 0, v44
	v_fmac_f32_e32 v36, v37, v81
	v_max_f32_e32 v37, 0, v45
	v_fmac_f32_e32 v36, v37, v80
	v_max_f32_e32 v38, 0, v46
	v_max_f32_e32 v37, 0, v47
	v_mul_f32_e32 v37, v37, v77
	v_fmac_f32_e32 v37, v38, v76
	v_max_f32_e32 v38, 0, v48
	v_fmac_f32_e32 v37, v38, v81
	v_max_f32_e32 v38, 0, v49
	v_fmac_f32_e32 v37, v38, v80
	v_permlane32_swap_b32_e32 v34, v36
	s_nop 0
	v_permlane32_swap_b32_e32 v35, v37
	s_and_saveexec_b64 s[4:5], vcc
	s_cbranch_execz .LBB0_655
	v_add_f32_e32 v35, v35, v37
	v_add_f32_e32 v34, v34, v36
	v_cndmask_b32_e64 v36, v34, v35, s[6:7]
	ds_bpermute_b32 v36, v130, v36
	v_cndmask_b32_e64 v34, v35, v34, s[6:7]
	s_waitcnt lgkmcnt(0)
	v_add_f32_e32 v34, v34, v36
	v_mul_f32_e32 v91, v133, v34

; #define LAS __attribute__((address_space(3)))
; __device__ __forceinline__ f32x4 mfma16(bf16x8 a, bf16x8 b, f32x4 c) { return __builtin_amdgcn_mfma_f32_16x16x32_bf16(a, b, c, 0, 0, 0); }
; __device__ __forceinline__ void att_unit(LAS unsigned char* lds, const bf16* P, const bf16* AKV, const bf16* IKC, bf16* ACAT, const float* aqg, const float* ssq_ak, const float* ssq_ik, int b, int qg, int tid) {
;     ...
;                 for (int r4 = 0; r4 < 4; ++r4) {
;                     float pt[2][4];
; #pragma unroll
;                     for (int q4 = 0; q4 < 4; ++q4) {
;                         const LAS unsigned char* kp = IKc + (64 * r4 + 16 * q4 + fr) * 144 + fq * 16;
;                         const bf16x8 K0 = *(const LAS bf16x8*)kp, K1 = *(const LAS bf16x8*)(kp + 64);
; #pragma unroll
;                         for (int q = 0; q < 2; ++q) {
;                             f32x4 a = (f32x4){0.f, 0.f, 0.f, 0.f};
;                             a = mfma16(Qi[q][0], K0, a); a = mfma16(Qi[q][1], K1, a);
;                             pt[q][q4] = fmaxf(a[0], 0.f) * wv[q][0] + fmaxf(a[1], 0.f) * wv[q][1] + fmaxf(a[2], 0.f) * wv[q][2] + fmaxf(a[3], 0.f) * wv[q][3];
;                         }
;                     }
;                     const int rr = 4 * tile + r4;
;                     const float rscale = rsqrtf((rc[r4].x + rc[r4].y) * (1.f / 64.f) + EPS);
;                     const bool live = 64 * rr + lane < L;
; #pragma unroll
;                     for (int q = 0; q < 2; ++q) {
;                         float hx; const float A = half_sum32(pt[q][0], pt[q][2], hx), B = half_sum32(pt[q][1], pt[q][3], hx);
;                         const bool odd = fq & 1;
;                         const float send = odd ? A : B, keep = odd ? B : A;
;                         const float sc = live ? (keep + __shfl_xor(send, 16)) * rscale : -INFINITY;
;                         const unsigned bts = __float_as_uint(sc);
;                         uk[q][rr] = bts ^ ((unsigned)((int)bts >> 31) | 0x80000000u);
;                     }
.LBB0_661:
	s_or_b64 exec, exec, s[4:5]
	ds_read_b128 v[34:37], v131
	ds_read_b128 v[38:41], v131 offset:64
	ds_read_b128 v[46:49], v131 offset:2304
	ds_read_b128 v[160:163], v131 offset:2368
	v_add_f32_e32 v102, v102, v103
	v_fmamk_f32 v102, v102, 0x3c800000, v222
	s_waitcnt lgkmcnt(3)
	v_mfma_f32_16x16x32_bf16 v[42:45], v[14:17], v[34:37], 0
	v_mul_f32_e32 v103, 0x4b800000, v102
	v_cmp_gt_f32_e32 vcc, s18, v102
	s_waitcnt lgkmcnt(2)
	v_mfma_f32_16x16x32_bf16 v[42:45], v[10:13], v[38:41], v[42:45]
	v_cndmask_b32_e32 v102, v102, v103, vcc
	v_rsq_f32_e32 v102, v102
	v_mfma_f32_16x16x32_bf16 v[34:37], v[2:5], v[34:37], 0
	v_mfma_f32_16x16x32_bf16 v[34:37], v[6:9], v[38:41], v[34:37]
	s_nop 3
	v_max_f32_e32 v42, v42, v42
	v_max_f32_e32 v43, v43, v43
	v_max_f32_e32 v44, v44, v44
	v_max_f32_e32 v137, 0, v45
	v_max_f32_e32 v138, 0, v42
	v_max_f32_e32 v136, 0, v43
	v_max_f32_e32 v139, 0, v44
	s_waitcnt lgkmcnt(1)
	v_mfma_f32_16x16x32_bf16 v[42:45], v[14:17], v[46:49], 0
	v_mul_f32_e32 v136, v136, v75
	v_fmac_f32_e32 v136, v138, v74
	v_fmac_f32_e32 v136, v139, v79
	s_waitcnt lgkmcnt(0)
	v_mfma_f32_16x16x32_bf16 v[42:45], v[10:13], v[160:163], v[42:45]
	v_fmac_f32_e32 v136, v137, v78
	s_nop 5
	s_nop 0
	v_max_f32_e32 v38, 0, v43
	v_mul_f32_e32 v138, v38, v75
	v_mfma_f32_16x16x32_bf16 v[38:41], v[2:5], v[46:49], 0
	ds_read_b128 v[46:49], v131 offset:4608
	v_max_f32_e32 v42, 0, v42
	v_mfma_f32_16x16x32_bf16 v[38:41], v[6:9], v[160:163], v[38:41]
	ds_read_b128 v[160:163], v131 offset:4672
	v_fmac_f32_e32 v138, v42, v74
	s_waitcnt lgkmcnt(1)
	v_mfma_f32_16x16x32_bf16 v[164:167], v[14:17], v[46:49], 0
	v_max_f32_e32 v42, 0, v44
	v_fmac_f32_e32 v138, v42, v79
	s_waitcnt lgkmcnt(0)
	v_mfma_f32_16x16x32_bf16 v[164:167], v[10:13], v[160:163], v[164:167]
	v_max_f32_e32 v42, 0, v45
	v_fmac_f32_e32 v138, v42, v78
	s_nop 5
	v_max_f32_e32 v137, 0, v164
	v_max_f32_e32 v42, 0, v165
	v_mul_f32_e32 v139, v42, v75
	v_mfma_f32_16x16x32_bf16 v[42:45], v[2:5], v[46:49], 0
	ds_read_b128 v[46:49], v131 offset:6912
	v_fmac_f32_e32 v139, v137, v74
	v_mfma_f32_16x16x32_bf16 v[42:45], v[6:9], v[160:163], v[42:45]
	ds_read_b128 v[160:163], v131 offset:6976
	v_max_f32_e32 v137, 0, v166
	v_fmac_f32_e32 v139, v137, v79
	s_waitcnt lgkmcnt(1)
	v_mfma_f32_16x16x32_bf16 v[168:171], v[14:17], v[46:49], 0
	v_max_f32_e32 v137, 0, v167
	v_fmac_f32_e32 v139, v137, v78
	s_waitcnt lgkmcnt(0)
	v_mfma_f32_16x16x32_bf16 v[164:167], v[10:13], v[160:163], v[168:171]
	v_permlane32_swap_b32_e32 v136, v139
	v_mfma_f32_16x16x32_bf16 v[46:49], v[2:5], v[46:49], 0
	v_mfma_f32_16x16x32_bf16 v[46:49], v[6:9], v[160:163], v[46:49]
	s_nop 4
	v_max_f32_e32 v147, 0, v165
	v_max_f32_e32 v137, 0, v164
	v_mul_f32_e32 v147, v147, v75
	v_fmac_f32_e32 v147, v137, v74
	v_max_f32_e32 v137, 0, v166
	v_fmac_f32_e32 v147, v137, v79
	v_max_f32_e32 v103, 0, v167
	v_fmac_f32_e32 v147, v103, v78
	v_mul_f32_e32 v103, 0x45800000, v102
	v_cndmask_b32_e32 v137, v102, v103, vcc
	v_or_b32_e32 v102, 0x400, v124
	v_cmp_gt_u32_e32 vcc, s81, v102
	v_permlane32_swap_b32_e32 v138, v147
	v_mov_b32_e32 v103, 0xff800000
	v_mov_b32_e32 v102, 0xff800000
	s_and_saveexec_b64 s[4:5], vcc
	s_cbranch_execz .LBB0_663
	v_add_f32_e32 v102, v138, v147
	v_add_f32_e32 v136, v136, v139
	v_cndmask_b32_e64 v138, v136, v102, s[6:7]
	ds_bpermute_b32 v138, v130, v138
	v_cndmask_b32_e64 v102, v102, v136, s[6:7]
	s_waitcnt lgkmcnt(0)
	v_add_f32_e32 v102, v102, v138
	v_mul_f32_e32 v102, v137, v102
.LBB0_663:
	s_or_b64 exec, exec, s[4:5]
	v_max_f32_e32 v136, 0, v34
	v_max_f32_e32 v34, 0, v35
	v_mul_f32_e32 v34, v34, v77
	v_fmac_f32_e32 v34, v136, v76
	v_max_f32_e32 v35, 0, v36
	v_fmac_f32_e32 v34, v35, v81
	v_max_f32_e32 v35, 0, v37
	v_fmac_f32_e32 v34, v35, v80
	v_max_f32_e32 v36, 0, v38
	v_max_f32_e32 v35, 0, v39
	v_mul_f32_e32 v35, v35, v77
	v_fmac_f32_e32 v35, v36, v76
	v_max_f32_e32 v36, 0, v40
	v_fmac_f32_e32 v35, v36, v81
	v_max_f32_e32 v36, 0, v41
	v_fmac_f32_e32 v35, v36, v80
	v_max_f32_e32 v37, 0, v42
	v_max_f32_e32 v36, 0, v43
	v_mul_f32_e32 v36, v36, v77
	v_fmac_f32_e32 v36, v37, v76
	v_max_f32_e32 v37, 0, v44
	v_fmac_f32_e32 v36, v37, v81
	v_max_f32_e32 v37, 0, v45
	v_fmac_f32_e32 v36, v37, v80
	v_max_f32_e32 v38, 0, v46
	v_max_f32_e32 v37, 0, v47
	v_mul_f32_e32 v37, v37, v77
	v_fmac_f32_e32 v37, v38, v76
	v_max_f32_e32 v38, 0, v48
	v_fmac_f32_e32 v37, v38, v81
	v_max_f32_e32 v38, 0, v49
	v_fmac_f32_e32 v37, v38, v80
	v_permlane32_swap_b32_e32 v34, v36
	s_nop 0
	v_permlane32_swap_b32_e32 v35, v37
	s_and_saveexec_b64 s[4:5], vcc
	s_cbranch_execz .LBB0_665
	v_add_f32_e32 v35, v35, v37
	v_add_f32_e32 v34, v34, v36
	v_cndmask_b32_e64 v36, v34, v35, s[6:7]
	ds_bpermute_b32 v36, v130, v36
	v_cndmask_b32_e64 v34, v35, v34, s[6:7]
	s_waitcnt lgkmcnt(0)
	v_add_f32_e32 v34, v34, v36
	v_mul_f32_e32 v103, v137, v34
; #define LAS __attribute__((address_space(3)))
; __device__ __forceinline__ f32x4 mfma16(bf16x8 a, bf16x8 b, f32x4 c) { return __builtin_amdgcn_mfma_f32_16x16x32_bf16(a, b, c, 0, 0, 0); }
; __device__ __forceinline__ void att_unit(LAS unsigned char* lds, const bf16* P, const bf16* AKV, const bf16* IKC, bf16* ACAT, const float* aqg, const float* ssq_ak, const float* ssq_ik, int b, int qg, int tid) {
;     ...
;                 for (int r4 = 0; r4 < 4; ++r4) {
;                     float pt[2][4];
; #pragma unroll
;                     for (int q4 = 0; q4 < 4; ++q4) {
;                         const LAS unsigned char* kp = IKc + (64 * r4 + 16 * q4 + fr) * 144 + fq * 16;
;                         const bf16x8 K0 = *(const LAS bf16x8*)kp, K1 = *(const LAS bf16x8*)(kp + 64);
; #pragma unroll
;                         for (int q = 0; q < 2; ++q) {
;                             f32x4 a = (f32x4){0.f, 0.f, 0.f, 0.f};
;                             a = mfma16(Qi[q][0], K0, a); a = mfma16(Qi[q][1], K1, a);
;                             pt[q][q4] = fmaxf(a[0], 0.f) * wv[q][0] + fmaxf(a[1], 0.f) * wv[q][1] + fmaxf(a[2], 0.f) * wv[q][2] + fmaxf(a[3], 0.f) * wv[q][3];
;                         }
;                     }
;                     const int rr = 4 * tile + r4;
;                     const float rscale = rsqrtf((rc[r4].x + rc[r4].y) * (1.f / 64.f) + EPS);
;                     const bool live = 64 * rr + lane < L;
; #pragma unroll
;                     for (int q = 0; q < 2; ++q) {
;                         float hx; const float A = half_sum32(pt[q][0], pt[q][2], hx), B = half_sum32(pt[q][1], pt[q][3], hx);
;                         const bool odd = fq & 1;
;                         const float send = odd ? A : B, keep = odd ? B : A;
;                         const float sc = live ? (keep + __shfl_xor(send, 16)) * rscale : -INFINITY;
;                         const unsigned bts = __float_as_uint(sc);
;                         uk[q][rr] = bts ^ ((unsigned)((int)bts >> 31) | 0x80000000u);
;                     }
.LBB0_665:
	s_or_b64 exec, exec, s[4:5]
	ds_read_b128 v[34:37], v131 offset:9216
	ds_read_b128 v[38:41], v131 offset:9280
	ds_read_b128 v[46:49], v131 offset:11520
	ds_read_b128 v[160:163], v131 offset:11584
	v_add_f32_e32 v98, v98, v99
	v_fmamk_f32 v98, v98, 0x3c800000, v222
	s_waitcnt lgkmcnt(3)
	v_mfma_f32_16x16x32_bf16 v[42:45], v[14:17], v[34:37], 0
	v_mul_f32_e32 v99, 0x4b800000, v98
	v_cmp_gt_f32_e32 vcc, s18, v98
	s_waitcnt lgkmcnt(2)
	v_mfma_f32_16x16x32_bf16 v[42:45], v[10:13], v[38:41], v[42:45]
	v_cndmask_b32_e32 v98, v98, v99, vcc
	v_rsq_f32_e32 v98, v98
	v_mfma_f32_16x16x32_bf16 v[34:37], v[2:5], v[34:37], 0
	v_mfma_f32_16x16x32_bf16 v[34:37], v[6:9], v[38:41], v[34:37]
	s_nop 3
	v_max_f32_e32 v42, v42, v42
	v_max_f32_e32 v43, v43, v43
	v_max_f32_e32 v44, v44, v44
	v_max_f32_e32 v137, 0, v45
	v_max_f32_e32 v138, 0, v42
	v_max_f32_e32 v136, 0, v43
	v_max_f32_e32 v139, 0, v44
	s_waitcnt lgkmcnt(1)
	v_mfma_f32_16x16x32_bf16 v[42:45], v[14:17], v[46:49], 0
	v_mul_f32_e32 v136, v136, v75
	v_fmac_f32_e32 v136, v138, v74
	v_fmac_f32_e32 v136, v139, v79
	s_waitcnt lgkmcnt(0)
	v_mfma_f32_16x16x32_bf16 v[42:45], v[10:13], v[160:163], v[42:45]
	v_fmac_f32_e32 v136, v137, v78
	s_nop 5
	s_nop 0
	v_max_f32_e32 v38, 0, v43
	v_mul_f32_e32 v138, v38, v75
	v_mfma_f32_16x16x32_bf16 v[38:41], v[2:5], v[46:49], 0
	ds_read_b128 v[46:49], v131 offset:13824
	v_max_f32_e32 v42, 0, v42
	v_mfma_f32_16x16x32_bf16 v[38:41], v[6:9], v[160:163], v[38:41]
	ds_read_b128 v[160:163], v131 offset:13888
	v_fmac_f32_e32 v138, v42, v74
	s_waitcnt lgkmcnt(1)
	v_mfma_f32_16x16x32_bf16 v[164:167], v[14:17], v[46:49], 0
	v_max_f32_e32 v42, 0, v44
	v_fmac_f32_e32 v138, v42, v79
	s_waitcnt lgkmcnt(0)
	v_mfma_f32_16x16x32_bf16 v[164:167], v[10:13], v[160:163], v[164:167]
	v_max_f32_e32 v42, 0, v45
	v_fmac_f32_e32 v138, v42, v78
	s_nop 5
	v_max_f32_e32 v137, 0, v164
	v_max_f32_e32 v42, 0, v165
	v_mul_f32_e32 v139, v42, v75
	v_mfma_f32_16x16x32_bf16 v[42:45], v[2:5], v[46:49], 0
	ds_read_b128 v[46:49], v131 offset:16128
	v_fmac_f32_e32 v139, v137, v74
	v_mfma_f32_16x16x32_bf16 v[42:45], v[6:9], v[160:163], v[42:45]
	ds_read_b128 v[160:163], v131 offset:16192
	v_max_f32_e32 v137, 0, v166
	v_fmac_f32_e32 v139, v137, v79
	s_waitcnt lgkmcnt(1)
	v_mfma_f32_16x16x32_bf16 v[168:171], v[14:17], v[46:49], 0
	v_max_f32_e32 v137, 0, v167
	v_fmac_f32_e32 v139, v137, v78
	s_waitcnt lgkmcnt(0)
	v_mfma_f32_16x16x32_bf16 v[164:167], v[10:13], v[160:163], v[168:171]
	v_permlane32_swap_b32_e32 v136, v139
	v_mfma_f32_16x16x32_bf16 v[46:49], v[2:5], v[46:49], 0
	v_mfma_f32_16x16x32_bf16 v[46:49], v[6:9], v[160:163], v[46:49]
	s_nop 4
	v_max_f32_e32 v147, 0, v165
	v_max_f32_e32 v137, 0, v164
	v_mul_f32_e32 v147, v147, v75
	v_fmac_f32_e32 v147, v137, v74
	v_max_f32_e32 v137, 0, v166
	v_fmac_f32_e32 v147, v137, v79
	v_max_f32_e32 v99, 0, v167
	v_fmac_f32_e32 v147, v99, v78
	v_mul_f32_e32 v99, 0x45800000, v98
	v_cndmask_b32_e32 v137, v98, v99, vcc
	v_or_b32_e32 v98, 0x440, v124
	v_cmp_gt_u32_e32 vcc, s81, v98
	v_permlane32_swap_b32_e32 v138, v147
	v_mov_b32_e32 v99, 0xff800000
	v_mov_b32_e32 v98, 0xff800000
	s_and_saveexec_b64 s[4:5], vcc
	s_cbranch_execz .LBB0_667
	v_add_f32_e32 v98, v138, v147
	v_add_f32_e32 v136, v136, v139
	v_cndmask_b32_e64 v138, v136, v98, s[6:7]
	ds_bpermute_b32 v138, v130, v138
	v_cndmask_b32_e64 v98, v98, v136, s[6:7]
	s_waitcnt lgkmcnt(0)
	v_add_f32_e32 v98, v98, v138
	v_mul_f32_e32 v98, v137, v98
.LBB0_667:
	s_or_b64 exec, exec, s[4:5]
	v_max_f32_e32 v136, 0, v34
	v_max_f32_e32 v34, 0, v35
	v_mul_f32_e32 v34, v34, v77
	v_fmac_f32_e32 v34, v136, v76
	v_max_f32_e32 v35, 0, v36
	v_fmac_f32_e32 v34, v35, v81
	v_max_f32_e32 v35, 0, v37
	v_fmac_f32_e32 v34, v35, v80
	v_max_f32_e32 v36, 0, v38
	v_max_f32_e32 v35, 0, v39
	v_mul_f32_e32 v35, v35, v77
	v_fmac_f32_e32 v35, v36, v76
	v_max_f32_e32 v36, 0, v40
	v_fmac_f32_e32 v35, v36, v81
	v_max_f32_e32 v36, 0, v41
	v_fmac_f32_e32 v35, v36, v80
	v_max_f32_e32 v37, 0, v42
	v_max_f32_e32 v36, 0, v43
	v_mul_f32_e32 v36, v36, v77
	v_fmac_f32_e32 v36, v37, v76
	v_max_f32_e32 v37, 0, v44
	v_fmac_f32_e32 v36, v37, v81
	v_max_f32_e32 v37, 0, v45
	v_fmac_f32_e32 v36, v37, v80
	v_max_f32_e32 v38, 0, v46
	v_max_f32_e32 v37, 0, v47
	v_mul_f32_e32 v37, v37, v77
	v_fmac_f32_e32 v37, v38, v76
	v_max_f32_e32 v38, 0, v48
	v_fmac_f32_e32 v37, v38, v81
	v_max_f32_e32 v38, 0, v49
	v_fmac_f32_e32 v37, v38, v80
	v_permlane32_swap_b32_e32 v34, v36
	s_nop 0
	v_permlane32_swap_b32_e32 v35, v37
	s_and_saveexec_b64 s[4:5], vcc
	s_cbranch_execz .LBB0_669
	v_add_f32_e32 v35, v35, v37
	v_add_f32_e32 v34, v34, v36
	v_cndmask_b32_e64 v36, v34, v35, s[6:7]
	ds_bpermute_b32 v36, v130, v36
	v_cndmask_b32_e64 v34, v35, v34, s[6:7]
	s_waitcnt lgkmcnt(0)
	v_add_f32_e32 v34, v34, v36
	v_mul_f32_e32 v99, v137, v34
; #define LAS __attribute__((address_space(3)))
; __device__ __forceinline__ f32x4 mfma16(bf16x8 a, bf16x8 b, f32x4 c) { return __builtin_amdgcn_mfma_f32_16x16x32_bf16(a, b, c, 0, 0, 0); }
; __device__ __forceinline__ void att_unit(LAS unsigned char* lds, const bf16* P, const bf16* AKV, const bf16* IKC, bf16* ACAT, const float* aqg, const float* ssq_ak, const float* ssq_ik, int b, int qg, int tid) {
;     ...
;                 for (int r4 = 0; r4 < 4; ++r4) {
;                     float pt[2][4];
; #pragma unroll
;                     for (int q4 = 0; q4 < 4; ++q4) {
;                         const LAS unsigned char* kp = IKc + (64 * r4 + 16 * q4 + fr) * 144 + fq * 16;
;                         const bf16x8 K0 = *(const LAS bf16x8*)kp, K1 = *(const LAS bf16x8*)(kp + 64);
; #pragma unroll
;                         for (int q = 0; q < 2; ++q) {
;                             f32x4 a = (f32x4){0.f, 0.f, 0.f, 0.f};
;                             a = mfma16(Qi[q][0], K0, a); a = mfma16(Qi[q][1], K1, a);
;                             pt[q][q4] = fmaxf(a[0], 0.f) * wv[q][0] + fmaxf(a[1], 0.f) * wv[q][1] + fmaxf(a[2], 0.f) * wv[q][2] + fmaxf(a[3], 0.f) * wv[q][3];
;                         }
;                     }
;                     const int rr = 4 * tile + r4;
;                     const float rscale = rsqrtf((rc[r4].x + rc[r4].y) * (1.f / 64.f) + EPS);
;                     const bool live = 64 * rr + lane < L;
; #pragma unroll
;                     for (int q = 0; q < 2; ++q) {
;                         float hx; const float A = half_sum32(pt[q][0], pt[q][2], hx), B = half_sum32(pt[q][1], pt[q][3], hx);
;                         const bool odd = fq & 1;
;                         const float send = odd ? A : B, keep = odd ? B : A;
;                         const float sc = live ? (keep + __shfl_xor(send, 16)) * rscale : -INFINITY;
;                         const unsigned bts = __float_as_uint(sc);
;                         uk[q][rr] = bts ^ ((unsigned)((int)bts >> 31) | 0x80000000u);
;                     }
.LBB0_669:
	s_or_b64 exec, exec, s[4:5]
	ds_read_b128 v[34:37], v131 offset:18432
	ds_read_b128 v[38:41], v131 offset:18496
	ds_read_b128 v[46:49], v131 offset:20736
	ds_read_b128 v[160:163], v131 offset:20800
	v_add_f32_e32 v96, v96, v97
	v_fmamk_f32 v96, v96, 0x3c800000, v222
	s_waitcnt lgkmcnt(3)
	v_mfma_f32_16x16x32_bf16 v[42:45], v[14:17], v[34:37], 0
	v_mul_f32_e32 v97, 0x4b800000, v96
	v_cmp_gt_f32_e32 vcc, s18, v96
	s_waitcnt lgkmcnt(2)
	v_mfma_f32_16x16x32_bf16 v[42:45], v[10:13], v[38:41], v[42:45]
	v_cndmask_b32_e32 v96, v96, v97, vcc
	v_rsq_f32_e32 v96, v96
	v_mfma_f32_16x16x32_bf16 v[34:37], v[2:5], v[34:37], 0
	v_mfma_f32_16x16x32_bf16 v[34:37], v[6:9], v[38:41], v[34:37]
	s_nop 3
	v_max_f32_e32 v42, v42, v42
	v_max_f32_e32 v43, v43, v43
	v_max_f32_e32 v44, v44, v44
	v_max_f32_e32 v137, 0, v45
	v_max_f32_e32 v138, 0, v42
	v_max_f32_e32 v136, 0, v43
	v_max_f32_e32 v139, 0, v44
	s_waitcnt lgkmcnt(1)
	v_mfma_f32_16x16x32_bf16 v[42:45], v[14:17], v[46:49], 0
	v_mul_f32_e32 v136, v136, v75
	v_fmac_f32_e32 v136, v138, v74
	v_fmac_f32_e32 v136, v139, v79
	s_waitcnt lgkmcnt(0)
	v_mfma_f32_16x16x32_bf16 v[42:45], v[10:13], v[160:163], v[42:45]
	v_fmac_f32_e32 v136, v137, v78
	s_nop 5
	s_nop 0
	v_max_f32_e32 v38, 0, v43
	v_mul_f32_e32 v138, v38, v75
	v_mfma_f32_16x16x32_bf16 v[38:41], v[2:5], v[46:49], 0
	ds_read_b128 v[46:49], v131 offset:23040
	v_max_f32_e32 v42, 0, v42
	v_mfma_f32_16x16x32_bf16 v[38:41], v[6:9], v[160:163], v[38:41]
	ds_read_b128 v[160:163], v131 offset:23104
	v_fmac_f32_e32 v138, v42, v74
	s_waitcnt lgkmcnt(1)
	v_mfma_f32_16x16x32_bf16 v[164:167], v[14:17], v[46:49], 0
	v_max_f32_e32 v42, 0, v44
	v_fmac_f32_e32 v138, v42, v79
	s_waitcnt lgkmcnt(0)
	v_mfma_f32_16x16x32_bf16 v[164:167], v[10:13], v[160:163], v[164:167]
	v_max_f32_e32 v42, 0, v45
	v_fmac_f32_e32 v138, v42, v78
	s_nop 5
	v_max_f32_e32 v137, 0, v164
	v_max_f32_e32 v42, 0, v165
	v_mul_f32_e32 v139, v42, v75
	v_mfma_f32_16x16x32_bf16 v[42:45], v[2:5], v[46:49], 0
	ds_read_b128 v[46:49], v131 offset:25344
	v_fmac_f32_e32 v139, v137, v74
	v_mfma_f32_16x16x32_bf16 v[42:45], v[6:9], v[160:163], v[42:45]
	ds_read_b128 v[160:163], v131 offset:25408
	v_max_f32_e32 v137, 0, v166
	v_fmac_f32_e32 v139, v137, v79
	s_waitcnt lgkmcnt(1)
	v_mfma_f32_16x16x32_bf16 v[168:171], v[14:17], v[46:49], 0
	v_max_f32_e32 v137, 0, v167
	v_fmac_f32_e32 v139, v137, v78
	s_waitcnt lgkmcnt(0)
	v_mfma_f32_16x16x32_bf16 v[164:167], v[10:13], v[160:163], v[168:171]
	v_permlane32_swap_b32_e32 v136, v139
	v_mfma_f32_16x16x32_bf16 v[46:49], v[2:5], v[46:49], 0
	v_mfma_f32_16x16x32_bf16 v[46:49], v[6:9], v[160:163], v[46:49]
	s_nop 4
	v_max_f32_e32 v147, 0, v165
	v_max_f32_e32 v137, 0, v164
	v_mul_f32_e32 v147, v147, v75
	v_fmac_f32_e32 v147, v137, v74
	v_max_f32_e32 v137, 0, v166
	v_fmac_f32_e32 v147, v137, v79
	v_max_f32_e32 v97, 0, v167
	v_fmac_f32_e32 v147, v97, v78
	v_mul_f32_e32 v97, 0x45800000, v96
	v_cndmask_b32_e32 v137, v96, v97, vcc
	v_or_b32_e32 v96, 0x480, v124
	v_cmp_gt_u32_e32 vcc, s81, v96
	v_permlane32_swap_b32_e32 v138, v147
	v_mov_b32_e32 v97, 0xff800000
	v_mov_b32_e32 v96, 0xff800000
	s_and_saveexec_b64 s[4:5], vcc
	s_cbranch_execz .LBB0_671
	v_add_f32_e32 v96, v138, v147
	v_add_f32_e32 v136, v136, v139
	v_cndmask_b32_e64 v138, v136, v96, s[6:7]
	ds_bpermute_b32 v138, v130, v138
	v_cndmask_b32_e64 v96, v96, v136, s[6:7]
	s_waitcnt lgkmcnt(0)
	v_add_f32_e32 v96, v96, v138
	v_mul_f32_e32 v96, v137, v96
.LBB0_671:
	s_or_b64 exec, exec, s[4:5]
	v_max_f32_e32 v136, 0, v34
	v_max_f32_e32 v34, 0, v35
	v_mul_f32_e32 v34, v34, v77
	v_fmac_f32_e32 v34, v136, v76
	v_max_f32_e32 v35, 0, v36
	v_fmac_f32_e32 v34, v35, v81
	v_max_f32_e32 v35, 0, v37
	v_fmac_f32_e32 v34, v35, v80
	v_max_f32_e32 v36, 0, v38
	v_max_f32_e32 v35, 0, v39
	v_mul_f32_e32 v35, v35, v77
	v_fmac_f32_e32 v35, v36, v76
	v_max_f32_e32 v36, 0, v40
	v_fmac_f32_e32 v35, v36, v81
	v_max_f32_e32 v36, 0, v41
	v_fmac_f32_e32 v35, v36, v80
	v_max_f32_e32 v37, 0, v42
	v_max_f32_e32 v36, 0, v43
	v_mul_f32_e32 v36, v36, v77
	v_fmac_f32_e32 v36, v37, v76
	v_max_f32_e32 v37, 0, v44
	v_fmac_f32_e32 v36, v37, v81
	v_max_f32_e32 v37, 0, v45
	v_fmac_f32_e32 v36, v37, v80
	v_max_f32_e32 v38, 0, v46
	v_max_f32_e32 v37, 0, v47
	v_mul_f32_e32 v37, v37, v77
	v_fmac_f32_e32 v37, v38, v76
	v_max_f32_e32 v38, 0, v48
	v_fmac_f32_e32 v37, v38, v81
	v_max_f32_e32 v38, 0, v49
	v_fmac_f32_e32 v37, v38, v80
	v_permlane32_swap_b32_e32 v34, v36
	s_nop 0
	v_permlane32_swap_b32_e32 v35, v37
	s_and_saveexec_b64 s[4:5], vcc
	s_cbranch_execz .LBB0_673
	v_add_f32_e32 v35, v35, v37
	v_add_f32_e32 v34, v34, v36
	v_cndmask_b32_e64 v36, v34, v35, s[6:7]
	ds_bpermute_b32 v36, v130, v36
	v_cndmask_b32_e64 v34, v35, v34, s[6:7]
	s_waitcnt lgkmcnt(0)
	v_add_f32_e32 v34, v34, v36
	v_mul_f32_e32 v97, v137, v34
; #define LAS __attribute__((address_space(3)))
; __device__ __forceinline__ f32x4 mfma16(bf16x8 a, bf16x8 b, f32x4 c) { return __builtin_amdgcn_mfma_f32_16x16x32_bf16(a, b, c, 0, 0, 0); }
; __device__ __forceinline__ void att_unit(LAS unsigned char* lds, const bf16* P, const bf16* AKV, const bf16* IKC, bf16* ACAT, const float* aqg, const float* ssq_ak, const float* ssq_ik, int b, int qg, int tid) {
;     ...
;                 for (int r4 = 0; r4 < 4; ++r4) {
;                     float pt[2][4];
; #pragma unroll
;                     for (int q4 = 0; q4 < 4; ++q4) {
;                         const LAS unsigned char* kp = IKc + (64 * r4 + 16 * q4 + fr) * 144 + fq * 16;
;                         const bf16x8 K0 = *(const LAS bf16x8*)kp, K1 = *(const LAS bf16x8*)(kp + 64);
; #pragma unroll
;                         for (int q = 0; q < 2; ++q) {
;                             f32x4 a = (f32x4){0.f, 0.f, 0.f, 0.f};
;                             a = mfma16(Qi[q][0], K0, a); a = mfma16(Qi[q][1], K1, a);
;                             pt[q][q4] = fmaxf(a[0], 0.f) * wv[q][0] + fmaxf(a[1], 0.f) * wv[q][1] + fmaxf(a[2], 0.f) * wv[q][2] + fmaxf(a[3], 0.f) * wv[q][3];
;                         }
;                     }
;                     const int rr = 4 * tile + r4;
;                     const float rscale = rsqrtf((rc[r4].x + rc[r4].y) * (1.f / 64.f) + EPS);
;                     const bool live = 64 * rr + lane < L;
; #pragma unroll
;                     for (int q = 0; q < 2; ++q) {
;                         float hx; const float A = half_sum32(pt[q][0], pt[q][2], hx), B = half_sum32(pt[q][1], pt[q][3], hx);
;                         const bool odd = fq & 1;
;                         const float send = odd ? A : B, keep = odd ? B : A;
;                         const float sc = live ? (keep + __shfl_xor(send, 16)) * rscale : -INFINITY;
;                         const unsigned bts = __float_as_uint(sc);
;                         uk[q][rr] = bts ^ ((unsigned)((int)bts >> 31) | 0x80000000u);
;                     }
.LBB0_673:
	s_or_b64 exec, exec, s[4:5]
	ds_read_b128 v[34:37], v131 offset:27648
	ds_read_b128 v[38:41], v131 offset:27712
	ds_read_b128 v[46:49], v131 offset:29952
	ds_read_b128 v[160:163], v131 offset:30016
	v_add_f32_e32 v90, v90, v91
	v_fmamk_f32 v90, v90, 0x3c800000, v222
	s_waitcnt lgkmcnt(3)
	v_mfma_f32_16x16x32_bf16 v[42:45], v[14:17], v[34:37], 0
	v_mul_f32_e32 v91, 0x4b800000, v90
	v_cmp_gt_f32_e32 vcc, s18, v90
	s_waitcnt lgkmcnt(2)
	v_mfma_f32_16x16x32_bf16 v[42:45], v[10:13], v[38:41], v[42:45]
	v_cndmask_b32_e32 v90, v90, v91, vcc
	v_rsq_f32_e32 v90, v90
	v_mfma_f32_16x16x32_bf16 v[34:37], v[2:5], v[34:37], 0
	v_mfma_f32_16x16x32_bf16 v[34:37], v[6:9], v[38:41], v[34:37]
	s_nop 3
	v_max_f32_e32 v42, v42, v42
	v_max_f32_e32 v43, v43, v43
	v_max_f32_e32 v44, v44, v44
	v_max_f32_e32 v137, 0, v45
	v_max_f32_e32 v138, 0, v42
	v_max_f32_e32 v136, 0, v43
	v_max_f32_e32 v139, 0, v44
	s_waitcnt lgkmcnt(1)
	v_mfma_f32_16x16x32_bf16 v[42:45], v[14:17], v[46:49], 0
	v_mul_f32_e32 v136, v136, v75
	v_fmac_f32_e32 v136, v138, v74
	v_fmac_f32_e32 v136, v139, v79
	s_waitcnt lgkmcnt(0)
	v_mfma_f32_16x16x32_bf16 v[42:45], v[10:13], v[160:163], v[42:45]
	v_fmac_f32_e32 v136, v137, v78
	s_nop 5
	s_nop 0
	v_max_f32_e32 v38, 0, v43
	v_mul_f32_e32 v138, v38, v75
	v_mfma_f32_16x16x32_bf16 v[38:41], v[2:5], v[46:49], 0
	ds_read_b128 v[46:49], v131 offset:32256
	v_max_f32_e32 v42, 0, v42
	v_mfma_f32_16x16x32_bf16 v[38:41], v[6:9], v[160:163], v[38:41]
	ds_read_b128 v[160:163], v131 offset:32320
	v_fmac_f32_e32 v138, v42, v74
	s_waitcnt lgkmcnt(1)
	v_mfma_f32_16x16x32_bf16 v[164:167], v[14:17], v[46:49], 0
	v_max_f32_e32 v42, 0, v44
	v_fmac_f32_e32 v138, v42, v79
	s_waitcnt lgkmcnt(0)
	v_mfma_f32_16x16x32_bf16 v[164:167], v[10:13], v[160:163], v[164:167]
	v_max_f32_e32 v42, 0, v45
	v_fmac_f32_e32 v138, v42, v78
	s_nop 5
	v_max_f32_e32 v137, 0, v164
	v_max_f32_e32 v42, 0, v165
	v_mul_f32_e32 v139, v42, v75
	v_mfma_f32_16x16x32_bf16 v[42:45], v[2:5], v[46:49], 0
	ds_read_b128 v[46:49], v131 offset:34560
	v_fmac_f32_e32 v139, v137, v74
	v_mfma_f32_16x16x32_bf16 v[42:45], v[6:9], v[160:163], v[42:45]
	ds_read_b128 v[160:163], v131 offset:34624
	v_max_f32_e32 v137, 0, v166
	v_fmac_f32_e32 v139, v137, v79
	s_waitcnt lgkmcnt(1)
	v_mfma_f32_16x16x32_bf16 v[168:171], v[14:17], v[46:49], 0
	v_max_f32_e32 v137, 0, v167
	v_fmac_f32_e32 v139, v137, v78
	s_waitcnt lgkmcnt(0)
	v_mfma_f32_16x16x32_bf16 v[164:167], v[10:13], v[160:163], v[168:171]
	v_permlane32_swap_b32_e32 v136, v139
	v_mfma_f32_16x16x32_bf16 v[46:49], v[2:5], v[46:49], 0
	v_mfma_f32_16x16x32_bf16 v[46:49], v[6:9], v[160:163], v[46:49]
	s_nop 4
	v_max_f32_e32 v147, 0, v165
	v_max_f32_e32 v137, 0, v164
	v_mul_f32_e32 v147, v147, v75
	v_fmac_f32_e32 v147, v137, v74
	v_max_f32_e32 v137, 0, v166
	v_fmac_f32_e32 v147, v137, v79
	v_max_f32_e32 v91, 0, v167
	v_fmac_f32_e32 v147, v91, v78
	v_mul_f32_e32 v91, 0x45800000, v90
	v_cndmask_b32_e32 v137, v90, v91, vcc
	v_or_b32_e32 v90, 0x4c0, v124
	v_cmp_gt_u32_e32 vcc, s81, v90
	v_permlane32_swap_b32_e32 v138, v147
	v_mov_b32_e32 v91, 0xff800000
	v_mov_b32_e32 v90, 0xff800000
	s_and_saveexec_b64 s[4:5], vcc
	s_cbranch_execz .LBB0_675
	v_add_f32_e32 v90, v138, v147
	v_add_f32_e32 v136, v136, v139
	v_cndmask_b32_e64 v138, v136, v90, s[6:7]
	ds_bpermute_b32 v138, v130, v138
	v_cndmask_b32_e64 v90, v90, v136, s[6:7]
	s_waitcnt lgkmcnt(0)
	v_add_f32_e32 v90, v90, v138
	v_mul_f32_e32 v90, v137, v90
.LBB0_675:
	s_or_b64 exec, exec, s[4:5]
	v_max_f32_e32 v136, 0, v34
	v_max_f32_e32 v34, 0, v35
	v_mul_f32_e32 v34, v34, v77
	v_fmac_f32_e32 v34, v136, v76
	v_max_f32_e32 v35, 0, v36
	v_fmac_f32_e32 v34, v35, v81
	v_max_f32_e32 v35, 0, v37
	v_fmac_f32_e32 v34, v35, v80
	v_max_f32_e32 v36, 0, v38
	v_max_f32_e32 v35, 0, v39
	v_mul_f32_e32 v35, v35, v77
	v_fmac_f32_e32 v35, v36, v76
	v_max_f32_e32 v36, 0, v40
	v_fmac_f32_e32 v35, v36, v81
	v_max_f32_e32 v36, 0, v41
	v_fmac_f32_e32 v35, v36, v80
	v_max_f32_e32 v37, 0, v42
	v_max_f32_e32 v36, 0, v43
	v_mul_f32_e32 v36, v36, v77
	v_fmac_f32_e32 v36, v37, v76
	v_max_f32_e32 v37, 0, v44
	v_fmac_f32_e32 v36, v37, v81
	v_max_f32_e32 v37, 0, v45
	v_fmac_f32_e32 v36, v37, v80
	v_max_f32_e32 v38, 0, v46
	v_max_f32_e32 v37, 0, v47
	v_mul_f32_e32 v37, v37, v77
	v_fmac_f32_e32 v37, v38, v76
	v_max_f32_e32 v38, 0, v48
	v_fmac_f32_e32 v37, v38, v81
	v_max_f32_e32 v38, 0, v49
	v_fmac_f32_e32 v37, v38, v80
	v_permlane32_swap_b32_e32 v34, v36
	s_nop 0
	v_permlane32_swap_b32_e32 v35, v37
	s_and_saveexec_b64 s[4:5], vcc
	s_cbranch_execz .LBB0_677
	v_add_f32_e32 v35, v35, v37
	v_add_f32_e32 v34, v34, v36
	v_cndmask_b32_e64 v36, v34, v35, s[6:7]
	ds_bpermute_b32 v36, v130, v36
	v_cndmask_b32_e64 v34, v35, v34, s[6:7]
	s_waitcnt lgkmcnt(0)
	v_add_f32_e32 v34, v34, v36
	v_mul_f32_e32 v91, v137, v34

; #define LAS __attribute__((address_space(3)))
; __device__ __forceinline__ f32x4 mfma16(bf16x8 a, bf16x8 b, f32x4 c) { return __builtin_amdgcn_mfma_f32_16x16x32_bf16(a, b, c, 0, 0, 0); }
; __device__ __forceinline__ void att_unit(LAS unsigned char* lds, const bf16* P, const bf16* AKV, const bf16* IKC, bf16* ACAT, const float* aqg, const float* ssq_ak, const float* ssq_ik, int b, int qg, int tid) {
;     ...
;                 for (int r4 = 0; r4 < 4; ++r4) {
;                     float pt[2][4];
; #pragma unroll
;                     for (int q4 = 0; q4 < 4; ++q4) {
;                         const LAS unsigned char* kp = IKc + (64 * r4 + 16 * q4 + fr) * 144 + fq * 16;
;                         const bf16x8 K0 = *(const LAS bf16x8*)kp, K1 = *(const LAS bf16x8*)(kp + 64);
; #pragma unroll
;                         for (int q = 0; q < 2; ++q) {
;                             f32x4 a = (f32x4){0.f, 0.f, 0.f, 0.f};
;                             a = mfma16(Qi[q][0], K0, a); a = mfma16(Qi[q][1], K1, a);
;                             pt[q][q4] = fmaxf(a[0], 0.f) * wv[q][0] + fmaxf(a[1], 0.f) * wv[q][1] + fmaxf(a[2], 0.f) * wv[q][2] + fmaxf(a[3], 0.f) * wv[q][3];
;                         }
;                     }
;                     const int rr = 4 * tile + r4;
;                     const float rscale = rsqrtf((rc[r4].x + rc[r4].y) * (1.f / 64.f) + EPS);
;                     const bool live = 64 * rr + lane < L;
; #pragma unroll
;                     for (int q = 0; q < 2; ++q) {
;                         float hx; const float A = half_sum32(pt[q][0], pt[q][2], hx), B = half_sum32(pt[q][1], pt[q][3], hx);
;                         const bool odd = fq & 1;
;                         const float send = odd ? A : B, keep = odd ? B : A;
;                         const float sc = live ? (keep + __shfl_xor(send, 16)) * rscale : -INFINITY;
;                         const unsigned bts = __float_as_uint(sc);
;                         uk[q][rr] = bts ^ ((unsigned)((int)bts >> 31) | 0x80000000u);
;                     }
.LBB0_683:
	s_or_b64 exec, exec, s[4:5]
	ds_read_b128 v[34:37], v131 offset:36864
	ds_read_b128 v[38:41], v131 offset:36928
	ds_read_b128 v[46:49], v131 offset:39168
	ds_read_b128 v[160:163], v131 offset:39232
	v_add_f32_e32 v102, v102, v103
	v_fmamk_f32 v102, v102, 0x3c800000, v222
	s_waitcnt lgkmcnt(3)
	v_mfma_f32_16x16x32_bf16 v[42:45], v[14:17], v[34:37], 0
	v_mul_f32_e32 v103, 0x4b800000, v102
	v_cmp_gt_f32_e32 vcc, s18, v102
	ds_read_b128 v[172:175], v131 offset:43840
	s_waitcnt lgkmcnt(3)
	v_mfma_f32_16x16x32_bf16 v[42:45], v[10:13], v[38:41], v[42:45]
	v_cndmask_b32_e32 v102, v102, v103, vcc
	v_rsq_f32_e32 v102, v102
	v_mfma_f32_16x16x32_bf16 v[34:37], v[2:5], v[34:37], 0
	v_mfma_f32_16x16x32_bf16 v[34:37], v[6:9], v[38:41], v[34:37]
	s_nop 3
	v_max_f32_e32 v42, v42, v42
	v_max_f32_e32 v43, v43, v43
	v_max_f32_e32 v44, v44, v44
	v_max_f32_e32 v148, 0, v45
	v_max_f32_e32 v149, 0, v42
	v_max_f32_e32 v147, 0, v43
	v_max_f32_e32 v151, 0, v44
	s_waitcnt lgkmcnt(2)
	v_mfma_f32_16x16x32_bf16 v[42:45], v[14:17], v[46:49], 0
	v_mul_f32_e32 v147, v147, v75
	v_fmac_f32_e32 v147, v149, v74
	v_fmac_f32_e32 v147, v151, v79
	s_waitcnt lgkmcnt(1)
	v_mfma_f32_16x16x32_bf16 v[42:45], v[10:13], v[160:163], v[42:45]
	v_fmac_f32_e32 v147, v148, v78
	s_nop 5
	s_nop 0
	v_max_f32_e32 v38, 0, v43
	v_mul_f32_e32 v149, v38, v75
	v_mfma_f32_16x16x32_bf16 v[38:41], v[2:5], v[46:49], 0
	ds_read_b128 v[46:49], v131 offset:41472
	v_max_f32_e32 v42, 0, v42
	v_mfma_f32_16x16x32_bf16 v[38:41], v[6:9], v[160:163], v[38:41]
	ds_read_b128 v[160:163], v131 offset:41536
	v_fmac_f32_e32 v149, v42, v74
	s_waitcnt lgkmcnt(1)
	v_mfma_f32_16x16x32_bf16 v[168:171], v[14:17], v[46:49], 0
	v_max_f32_e32 v42, 0, v44
	v_fmac_f32_e32 v149, v42, v79
	s_waitcnt lgkmcnt(0)
	v_mfma_f32_16x16x32_bf16 v[168:171], v[10:13], v[160:163], v[168:171]
	v_max_f32_e32 v42, 0, v45
	v_fmac_f32_e32 v149, v42, v78
	s_nop 5
	v_max_f32_e32 v148, 0, v168
	v_max_f32_e32 v42, 0, v169
	v_mul_f32_e32 v151, v42, v75
	v_mfma_f32_16x16x32_bf16 v[42:45], v[2:5], v[46:49], 0
	ds_read_b128 v[46:49], v131 offset:43776
	v_fmac_f32_e32 v151, v148, v74
	v_mfma_f32_16x16x32_bf16 v[42:45], v[6:9], v[160:163], v[42:45]
	v_max_f32_e32 v148, 0, v170
	v_fmac_f32_e32 v151, v148, v79
	s_waitcnt lgkmcnt(0)
	v_mfma_f32_16x16x32_bf16 v[160:163], v[14:17], v[46:49], 0
	v_max_f32_e32 v148, 0, v171
	v_fmac_f32_e32 v151, v148, v78
	s_nop 1
	v_permlane32_swap_b32_e32 v147, v151
	v_mfma_f32_16x16x32_bf16 v[160:163], v[10:13], v[172:175], v[160:163]
	v_mfma_f32_16x16x32_bf16 v[46:49], v[2:5], v[46:49], 0
	v_mfma_f32_16x16x32_bf16 v[46:49], v[6:9], v[172:175], v[46:49]
	s_nop 5
	v_max_f32_e32 v148, 0, v160
	v_max_f32_e32 v160, 0, v161
	v_mul_f32_e32 v160, v160, v75
	v_fmac_f32_e32 v160, v148, v74
	v_max_f32_e32 v148, 0, v162
	v_fmac_f32_e32 v160, v148, v79
	v_max_f32_e32 v103, 0, v163
	v_fmac_f32_e32 v160, v103, v78
	v_mul_f32_e32 v103, 0x45800000, v102
	v_cndmask_b32_e32 v148, v102, v103, vcc
	v_or_b32_e32 v102, 0x500, v124
	v_cmp_gt_u32_e32 vcc, s81, v102
	v_permlane32_swap_b32_e32 v149, v160
	v_mov_b32_e32 v103, 0xff800000
	v_mov_b32_e32 v102, 0xff800000
	s_and_saveexec_b64 s[4:5], vcc
	s_cbranch_execz .LBB0_685
	v_add_f32_e32 v102, v149, v160
	v_add_f32_e32 v147, v147, v151
	v_cndmask_b32_e64 v149, v147, v102, s[6:7]
	ds_bpermute_b32 v149, v130, v149
	v_cndmask_b32_e64 v102, v102, v147, s[6:7]
	s_waitcnt lgkmcnt(0)
	v_add_f32_e32 v102, v102, v149
	v_mul_f32_e32 v102, v148, v102
.LBB0_685:
	s_or_b64 exec, exec, s[4:5]
	v_max_f32_e32 v147, 0, v34
	v_max_f32_e32 v34, 0, v35
	v_mul_f32_e32 v34, v34, v77
	v_fmac_f32_e32 v34, v147, v76
	v_max_f32_e32 v35, 0, v36
	v_fmac_f32_e32 v34, v35, v81
	v_max_f32_e32 v35, 0, v37
	v_fmac_f32_e32 v34, v35, v80
	v_max_f32_e32 v36, 0, v38
	v_max_f32_e32 v35, 0, v39
	v_mul_f32_e32 v35, v35, v77
	v_fmac_f32_e32 v35, v36, v76
	v_max_f32_e32 v36, 0, v40
	v_fmac_f32_e32 v35, v36, v81
	v_max_f32_e32 v36, 0, v41
	v_fmac_f32_e32 v35, v36, v80
	v_max_f32_e32 v37, 0, v42
	v_max_f32_e32 v36, 0, v43
	v_mul_f32_e32 v36, v36, v77
	v_fmac_f32_e32 v36, v37, v76
	v_max_f32_e32 v37, 0, v44
	v_fmac_f32_e32 v36, v37, v81
	v_max_f32_e32 v37, 0, v45
	v_fmac_f32_e32 v36, v37, v80
	v_max_f32_e32 v38, 0, v46
	v_max_f32_e32 v37, 0, v47
	v_mul_f32_e32 v37, v37, v77
	v_fmac_f32_e32 v37, v38, v76
	v_max_f32_e32 v38, 0, v48
	v_fmac_f32_e32 v37, v38, v81
	v_max_f32_e32 v38, 0, v49
	v_fmac_f32_e32 v37, v38, v80
	v_permlane32_swap_b32_e32 v34, v36
	s_nop 0
	v_permlane32_swap_b32_e32 v35, v37
	s_and_saveexec_b64 s[4:5], vcc
	s_cbranch_execz .LBB0_687
	v_add_f32_e32 v35, v35, v37
	v_add_f32_e32 v34, v34, v36
	v_cndmask_b32_e64 v36, v34, v35, s[6:7]
	ds_bpermute_b32 v36, v130, v36
	v_cndmask_b32_e64 v34, v35, v34, s[6:7]
	s_waitcnt lgkmcnt(0)
	v_add_f32_e32 v34, v34, v36
	v_mul_f32_e32 v103, v148, v34
; #define LAS __attribute__((address_space(3)))
; __device__ __forceinline__ f32x4 mfma16(bf16x8 a, bf16x8 b, f32x4 c) { return __builtin_amdgcn_mfma_f32_16x16x32_bf16(a, b, c, 0, 0, 0); }
; __device__ __forceinline__ void att_unit(LAS unsigned char* lds, const bf16* P, const bf16* AKV, const bf16* IKC, bf16* ACAT, const float* aqg, const float* ssq_ak, const float* ssq_ik, int b, int qg, int tid) {
;     ...
;                 for (int r4 = 0; r4 < 4; ++r4) {
;                     float pt[2][4];
; #pragma unroll
;                     for (int q4 = 0; q4 < 4; ++q4) {
;                         const LAS unsigned char* kp = IKc + (64 * r4 + 16 * q4 + fr) * 144 + fq * 16;
;                         const bf16x8 K0 = *(const LAS bf16x8*)kp, K1 = *(const LAS bf16x8*)(kp + 64);
; #pragma unroll
;                         for (int q = 0; q < 2; ++q) {
;                             f32x4 a = (f32x4){0.f, 0.f, 0.f, 0.f};
;                             a = mfma16(Qi[q][0], K0, a); a = mfma16(Qi[q][1], K1, a);
;                             pt[q][q4] = fmaxf(a[0], 0.f) * wv[q][0] + fmaxf(a[1], 0.f) * wv[q][1] + fmaxf(a[2], 0.f) * wv[q][2] + fmaxf(a[3], 0.f) * wv[q][3];
;                         }
;                     }
;                     const int rr = 4 * tile + r4;
;                     const float rscale = rsqrtf((rc[r4].x + rc[r4].y) * (1.f / 64.f) + EPS);
;                     const bool live = 64 * rr + lane < L;
; #pragma unroll
;                     for (int q = 0; q < 2; ++q) {
;                         float hx; const float A = half_sum32(pt[q][0], pt[q][2], hx), B = half_sum32(pt[q][1], pt[q][3], hx);
;                         const bool odd = fq & 1;
;                         const float send = odd ? A : B, keep = odd ? B : A;
;                         const float sc = live ? (keep + __shfl_xor(send, 16)) * rscale : -INFINITY;
;                         const unsigned bts = __float_as_uint(sc);
;                         uk[q][rr] = bts ^ ((unsigned)((int)bts >> 31) | 0x80000000u);
;                     }
.LBB0_687:
	s_or_b64 exec, exec, s[4:5]
	ds_read_b128 v[34:37], v131 offset:46080
	ds_read_b128 v[38:41], v131 offset:46144
	ds_read_b128 v[46:49], v131 offset:48384
	ds_read_b128 v[160:163], v131 offset:48448
	v_add_f32_e32 v98, v98, v99
	v_fmamk_f32 v98, v98, 0x3c800000, v222
	s_waitcnt lgkmcnt(3)
	v_mfma_f32_16x16x32_bf16 v[42:45], v[14:17], v[34:37], 0
	v_mul_f32_e32 v99, 0x4b800000, v98
	v_cmp_gt_f32_e32 vcc, s18, v98
	ds_read_b128 v[172:175], v131 offset:53056
	s_waitcnt lgkmcnt(3)
	v_mfma_f32_16x16x32_bf16 v[42:45], v[10:13], v[38:41], v[42:45]
	v_cndmask_b32_e32 v98, v98, v99, vcc
	v_rsq_f32_e32 v98, v98
	v_mfma_f32_16x16x32_bf16 v[34:37], v[2:5], v[34:37], 0
	v_mfma_f32_16x16x32_bf16 v[34:37], v[6:9], v[38:41], v[34:37]
	s_nop 3
	v_max_f32_e32 v42, v42, v42
	v_max_f32_e32 v43, v43, v43
	v_max_f32_e32 v44, v44, v44
	v_max_f32_e32 v148, 0, v45
	v_max_f32_e32 v149, 0, v42
	v_max_f32_e32 v147, 0, v43
	v_max_f32_e32 v151, 0, v44
	s_waitcnt lgkmcnt(2)
	v_mfma_f32_16x16x32_bf16 v[42:45], v[14:17], v[46:49], 0
	v_mul_f32_e32 v147, v147, v75
	v_fmac_f32_e32 v147, v149, v74
	v_fmac_f32_e32 v147, v151, v79
	s_waitcnt lgkmcnt(1)
	v_mfma_f32_16x16x32_bf16 v[42:45], v[10:13], v[160:163], v[42:45]
	v_fmac_f32_e32 v147, v148, v78
	s_nop 5
	s_nop 0
	v_max_f32_e32 v38, 0, v43
	v_mul_f32_e32 v149, v38, v75
	v_mfma_f32_16x16x32_bf16 v[38:41], v[2:5], v[46:49], 0
	ds_read_b128 v[46:49], v131 offset:50688
	v_max_f32_e32 v42, 0, v42
	v_mfma_f32_16x16x32_bf16 v[38:41], v[6:9], v[160:163], v[38:41]
	ds_read_b128 v[160:163], v131 offset:50752
	v_fmac_f32_e32 v149, v42, v74
	s_waitcnt lgkmcnt(1)
	v_mfma_f32_16x16x32_bf16 v[168:171], v[14:17], v[46:49], 0
	v_max_f32_e32 v42, 0, v44
	v_fmac_f32_e32 v149, v42, v79
	s_waitcnt lgkmcnt(0)
	v_mfma_f32_16x16x32_bf16 v[168:171], v[10:13], v[160:163], v[168:171]
	v_max_f32_e32 v42, 0, v45
	v_fmac_f32_e32 v149, v42, v78
	s_nop 5
	v_max_f32_e32 v148, 0, v168
	v_max_f32_e32 v42, 0, v169
	v_mul_f32_e32 v151, v42, v75
	v_mfma_f32_16x16x32_bf16 v[42:45], v[2:5], v[46:49], 0
	ds_read_b128 v[46:49], v131 offset:52992
	v_fmac_f32_e32 v151, v148, v74
	v_mfma_f32_16x16x32_bf16 v[42:45], v[6:9], v[160:163], v[42:45]
	v_max_f32_e32 v148, 0, v170
	v_fmac_f32_e32 v151, v148, v79
	s_waitcnt lgkmcnt(0)
	v_mfma_f32_16x16x32_bf16 v[160:163], v[14:17], v[46:49], 0
	v_max_f32_e32 v148, 0, v171
	v_fmac_f32_e32 v151, v148, v78
	s_nop 1
	v_permlane32_swap_b32_e32 v147, v151
	v_mfma_f32_16x16x32_bf16 v[160:163], v[10:13], v[172:175], v[160:163]
	v_mfma_f32_16x16x32_bf16 v[46:49], v[2:5], v[46:49], 0
	v_mfma_f32_16x16x32_bf16 v[46:49], v[6:9], v[172:175], v[46:49]
	s_nop 5
	v_max_f32_e32 v148, 0, v160
	v_max_f32_e32 v160, 0, v161
	v_mul_f32_e32 v160, v160, v75
	v_fmac_f32_e32 v160, v148, v74
	v_max_f32_e32 v148, 0, v162
	v_fmac_f32_e32 v160, v148, v79
	v_max_f32_e32 v99, 0, v163
	v_fmac_f32_e32 v160, v99, v78
	v_mul_f32_e32 v99, 0x45800000, v98
	v_cndmask_b32_e32 v148, v98, v99, vcc
	v_or_b32_e32 v98, 0x540, v124
	v_cmp_gt_u32_e32 vcc, s81, v98
	v_permlane32_swap_b32_e32 v149, v160
	v_mov_b32_e32 v99, 0xff800000
	v_mov_b32_e32 v98, 0xff800000
	s_and_saveexec_b64 s[4:5], vcc
	s_cbranch_execz .LBB0_689
	v_add_f32_e32 v98, v149, v160
	v_add_f32_e32 v147, v147, v151
	v_cndmask_b32_e64 v149, v147, v98, s[6:7]
	ds_bpermute_b32 v149, v130, v149
	v_cndmask_b32_e64 v98, v98, v147, s[6:7]
	s_waitcnt lgkmcnt(0)
	v_add_f32_e32 v98, v98, v149
	v_mul_f32_e32 v98, v148, v98
.LBB0_689:
	s_or_b64 exec, exec, s[4:5]
	v_max_f32_e32 v147, 0, v34
	v_max_f32_e32 v34, 0, v35
	v_mul_f32_e32 v34, v34, v77
	v_fmac_f32_e32 v34, v147, v76
	v_max_f32_e32 v35, 0, v36
	v_fmac_f32_e32 v34, v35, v81
	v_max_f32_e32 v35, 0, v37
	v_fmac_f32_e32 v34, v35, v80
	v_max_f32_e32 v36, 0, v38
	v_max_f32_e32 v35, 0, v39
	v_mul_f32_e32 v35, v35, v77
	v_fmac_f32_e32 v35, v36, v76
	v_max_f32_e32 v36, 0, v40
	v_fmac_f32_e32 v35, v36, v81
	v_max_f32_e32 v36, 0, v41
	v_fmac_f32_e32 v35, v36, v80
	v_max_f32_e32 v37, 0, v42
	v_max_f32_e32 v36, 0, v43
	v_mul_f32_e32 v36, v36, v77
	v_fmac_f32_e32 v36, v37, v76
	v_max_f32_e32 v37, 0, v44
	v_fmac_f32_e32 v36, v37, v81
	v_max_f32_e32 v37, 0, v45
	v_fmac_f32_e32 v36, v37, v80
	v_max_f32_e32 v38, 0, v46
	v_max_f32_e32 v37, 0, v47
	v_mul_f32_e32 v37, v37, v77
	v_fmac_f32_e32 v37, v38, v76
	v_max_f32_e32 v38, 0, v48
	v_fmac_f32_e32 v37, v38, v81
	v_max_f32_e32 v38, 0, v49
	v_fmac_f32_e32 v37, v38, v80
	v_permlane32_swap_b32_e32 v34, v36
	s_nop 0
	v_permlane32_swap_b32_e32 v35, v37
	s_and_saveexec_b64 s[4:5], vcc
	s_cbranch_execz .LBB0_691
	v_add_f32_e32 v35, v35, v37
	v_add_f32_e32 v34, v34, v36
	v_cndmask_b32_e64 v36, v34, v35, s[6:7]
	ds_bpermute_b32 v36, v130, v36
	v_cndmask_b32_e64 v34, v35, v34, s[6:7]
	s_waitcnt lgkmcnt(0)
	v_add_f32_e32 v34, v34, v36
	v_mul_f32_e32 v99, v148, v34
; #define LAS __attribute__((address_space(3)))
; __device__ __forceinline__ f32x4 mfma16(bf16x8 a, bf16x8 b, f32x4 c) { return __builtin_amdgcn_mfma_f32_16x16x32_bf16(a, b, c, 0, 0, 0); }
; __device__ __forceinline__ void att_unit(LAS unsigned char* lds, const bf16* P, const bf16* AKV, const bf16* IKC, bf16* ACAT, const float* aqg, const float* ssq_ak, const float* ssq_ik, int b, int qg, int tid) {
;     ...
;                 for (int r4 = 0; r4 < 4; ++r4) {
;                     float pt[2][4];
; #pragma unroll
;                     for (int q4 = 0; q4 < 4; ++q4) {
;                         const LAS unsigned char* kp = IKc + (64 * r4 + 16 * q4 + fr) * 144 + fq * 16;
;                         const bf16x8 K0 = *(const LAS bf16x8*)kp, K1 = *(const LAS bf16x8*)(kp + 64);
; #pragma unroll
;                         for (int q = 0; q < 2; ++q) {
;                             f32x4 a = (f32x4){0.f, 0.f, 0.f, 0.f};
;                             a = mfma16(Qi[q][0], K0, a); a = mfma16(Qi[q][1], K1, a);
;                             pt[q][q4] = fmaxf(a[0], 0.f) * wv[q][0] + fmaxf(a[1], 0.f) * wv[q][1] + fmaxf(a[2], 0.f) * wv[q][2] + fmaxf(a[3], 0.f) * wv[q][3];
;                         }
;                     }
;                     const int rr = 4 * tile + r4;
;                     const float rscale = rsqrtf((rc[r4].x + rc[r4].y) * (1.f / 64.f) + EPS);
;                     const bool live = 64 * rr + lane < L;
; #pragma unroll
;                     for (int q = 0; q < 2; ++q) {
;                         float hx; const float A = half_sum32(pt[q][0], pt[q][2], hx), B = half_sum32(pt[q][1], pt[q][3], hx);
;                         const bool odd = fq & 1;
;                         const float send = odd ? A : B, keep = odd ? B : A;
;                         const float sc = live ? (keep + __shfl_xor(send, 16)) * rscale : -INFINITY;
;                         const unsigned bts = __float_as_uint(sc);
;                         uk[q][rr] = bts ^ ((unsigned)((int)bts >> 31) | 0x80000000u);
;                     }
.LBB0_691:
	s_or_b64 exec, exec, s[4:5]
	ds_read_b128 v[34:37], v131 offset:55296
	ds_read_b128 v[38:41], v131 offset:55360
	ds_read_b128 v[46:49], v131 offset:57600
	ds_read_b128 v[160:163], v131 offset:57664
	v_add_f32_e32 v96, v96, v97
	v_fmamk_f32 v96, v96, 0x3c800000, v222
	s_waitcnt lgkmcnt(3)
	v_mfma_f32_16x16x32_bf16 v[42:45], v[14:17], v[34:37], 0
	v_mul_f32_e32 v97, 0x4b800000, v96
	v_cmp_gt_f32_e32 vcc, s18, v96
	ds_read_b128 v[172:175], v131 offset:62272
	s_waitcnt lgkmcnt(3)
	v_mfma_f32_16x16x32_bf16 v[42:45], v[10:13], v[38:41], v[42:45]
	v_cndmask_b32_e32 v96, v96, v97, vcc
	v_rsq_f32_e32 v96, v96
	v_mfma_f32_16x16x32_bf16 v[34:37], v[2:5], v[34:37], 0
	v_mfma_f32_16x16x32_bf16 v[34:37], v[6:9], v[38:41], v[34:37]
	s_nop 3
	v_max_f32_e32 v42, v42, v42
	v_max_f32_e32 v43, v43, v43
	v_max_f32_e32 v44, v44, v44
	v_max_f32_e32 v148, 0, v45
	v_max_f32_e32 v149, 0, v42
	v_max_f32_e32 v147, 0, v43
	v_max_f32_e32 v151, 0, v44
	s_waitcnt lgkmcnt(2)
	v_mfma_f32_16x16x32_bf16 v[42:45], v[14:17], v[46:49], 0
	v_mul_f32_e32 v147, v147, v75
	v_fmac_f32_e32 v147, v149, v74
	v_fmac_f32_e32 v147, v151, v79
	s_waitcnt lgkmcnt(1)
	v_mfma_f32_16x16x32_bf16 v[42:45], v[10:13], v[160:163], v[42:45]
	v_fmac_f32_e32 v147, v148, v78
	s_nop 5
	s_nop 0
	v_max_f32_e32 v38, 0, v43
	v_mul_f32_e32 v149, v38, v75
	v_mfma_f32_16x16x32_bf16 v[38:41], v[2:5], v[46:49], 0
	ds_read_b128 v[46:49], v131 offset:59904
	v_max_f32_e32 v42, 0, v42
	v_mfma_f32_16x16x32_bf16 v[38:41], v[6:9], v[160:163], v[38:41]
	ds_read_b128 v[160:163], v131 offset:59968
	v_fmac_f32_e32 v149, v42, v74
	s_waitcnt lgkmcnt(1)
	v_mfma_f32_16x16x32_bf16 v[168:171], v[14:17], v[46:49], 0
	v_max_f32_e32 v42, 0, v44
	v_fmac_f32_e32 v149, v42, v79
	s_waitcnt lgkmcnt(0)
	v_mfma_f32_16x16x32_bf16 v[168:171], v[10:13], v[160:163], v[168:171]
	v_max_f32_e32 v42, 0, v45
	v_fmac_f32_e32 v149, v42, v78
	s_nop 5
	v_max_f32_e32 v148, 0, v168
	v_max_f32_e32 v42, 0, v169
	v_mul_f32_e32 v151, v42, v75
	v_mfma_f32_16x16x32_bf16 v[42:45], v[2:5], v[46:49], 0
	ds_read_b128 v[46:49], v131 offset:62208
	v_fmac_f32_e32 v151, v148, v74
	v_mfma_f32_16x16x32_bf16 v[42:45], v[6:9], v[160:163], v[42:45]
	v_max_f32_e32 v148, 0, v170
	v_fmac_f32_e32 v151, v148, v79
	s_waitcnt lgkmcnt(0)
	v_mfma_f32_16x16x32_bf16 v[160:163], v[14:17], v[46:49], 0
	v_max_f32_e32 v148, 0, v171
	v_fmac_f32_e32 v151, v148, v78
	s_nop 1
	v_permlane32_swap_b32_e32 v147, v151
	v_mfma_f32_16x16x32_bf16 v[160:163], v[10:13], v[172:175], v[160:163]
	v_mfma_f32_16x16x32_bf16 v[46:49], v[2:5], v[46:49], 0
	v_mfma_f32_16x16x32_bf16 v[46:49], v[6:9], v[172:175], v[46:49]
	s_nop 5
	v_max_f32_e32 v148, 0, v160
	v_max_f32_e32 v160, 0, v161
	v_mul_f32_e32 v160, v160, v75
	v_fmac_f32_e32 v160, v148, v74
	v_max_f32_e32 v148, 0, v162
	v_fmac_f32_e32 v160, v148, v79
	v_max_f32_e32 v97, 0, v163
	v_fmac_f32_e32 v160, v97, v78
	v_mul_f32_e32 v97, 0x45800000, v96
	v_cndmask_b32_e32 v148, v96, v97, vcc
	v_or_b32_e32 v96, 0x580, v124
	v_cmp_gt_u32_e32 vcc, s81, v96
	v_permlane32_swap_b32_e32 v149, v160
	v_mov_b32_e32 v97, 0xff800000
	v_mov_b32_e32 v96, 0xff800000
	s_and_saveexec_b64 s[4:5], vcc
	s_cbranch_execz .LBB0_693
	v_add_f32_e32 v96, v149, v160
	v_add_f32_e32 v147, v147, v151
	v_cndmask_b32_e64 v149, v147, v96, s[6:7]
	ds_bpermute_b32 v149, v130, v149
	v_cndmask_b32_e64 v96, v96, v147, s[6:7]
	s_waitcnt lgkmcnt(0)
	v_add_f32_e32 v96, v96, v149
	v_mul_f32_e32 v96, v148, v96
.LBB0_693:
	s_or_b64 exec, exec, s[4:5]
	v_max_f32_e32 v147, 0, v34
	v_max_f32_e32 v34, 0, v35
	v_mul_f32_e32 v34, v34, v77
	v_fmac_f32_e32 v34, v147, v76
	v_max_f32_e32 v35, 0, v36
	v_fmac_f32_e32 v34, v35, v81
	v_max_f32_e32 v35, 0, v37
	v_fmac_f32_e32 v34, v35, v80
	v_max_f32_e32 v36, 0, v38
	v_max_f32_e32 v35, 0, v39
	v_mul_f32_e32 v35, v35, v77
	v_fmac_f32_e32 v35, v36, v76
	v_max_f32_e32 v36, 0, v40
	v_fmac_f32_e32 v35, v36, v81
	v_max_f32_e32 v36, 0, v41
	v_fmac_f32_e32 v35, v36, v80
	v_max_f32_e32 v37, 0, v42
	v_max_f32_e32 v36, 0, v43
	v_mul_f32_e32 v36, v36, v77
	v_fmac_f32_e32 v36, v37, v76
	v_max_f32_e32 v37, 0, v44
	v_fmac_f32_e32 v36, v37, v81
	v_max_f32_e32 v37, 0, v45
	v_fmac_f32_e32 v36, v37, v80
	v_max_f32_e32 v38, 0, v46
	v_max_f32_e32 v37, 0, v47
	v_mul_f32_e32 v37, v37, v77
	v_fmac_f32_e32 v37, v38, v76
	v_max_f32_e32 v38, 0, v48
	v_fmac_f32_e32 v37, v38, v81
	v_max_f32_e32 v38, 0, v49
	v_fmac_f32_e32 v37, v38, v80
	v_permlane32_swap_b32_e32 v34, v36
	s_nop 0
	v_permlane32_swap_b32_e32 v35, v37
	s_and_saveexec_b64 s[4:5], vcc
	s_cbranch_execz .LBB0_695
	v_add_f32_e32 v35, v35, v37
	v_add_f32_e32 v34, v34, v36
	v_cndmask_b32_e64 v36, v34, v35, s[6:7]
	ds_bpermute_b32 v36, v130, v36
	v_cndmask_b32_e64 v34, v35, v34, s[6:7]
	s_waitcnt lgkmcnt(0)
	v_add_f32_e32 v34, v34, v36
	v_mul_f32_e32 v97, v148, v34
; #define LAS __attribute__((address_space(3)))
; __device__ __forceinline__ f32x4 mfma16(bf16x8 a, bf16x8 b, f32x4 c) { return __builtin_amdgcn_mfma_f32_16x16x32_bf16(a, b, c, 0, 0, 0); }
; __device__ __forceinline__ void att_unit(LAS unsigned char* lds, const bf16* P, const bf16* AKV, const bf16* IKC, bf16* ACAT, const float* aqg, const float* ssq_ak, const float* ssq_ik, int b, int qg, int tid) {
;     ...
;                 for (int r4 = 0; r4 < 4; ++r4) {
;                     float pt[2][4];
; #pragma unroll
;                     for (int q4 = 0; q4 < 4; ++q4) {
;                         const LAS unsigned char* kp = IKc + (64 * r4 + 16 * q4 + fr) * 144 + fq * 16;
;                         const bf16x8 K0 = *(const LAS bf16x8*)kp, K1 = *(const LAS bf16x8*)(kp + 64);
; #pragma unroll
;                         for (int q = 0; q < 2; ++q) {
;                             f32x4 a = (f32x4){0.f, 0.f, 0.f, 0.f};
;                             a = mfma16(Qi[q][0], K0, a); a = mfma16(Qi[q][1], K1, a);
;                             pt[q][q4] = fmaxf(a[0], 0.f) * wv[q][0] + fmaxf(a[1], 0.f) * wv[q][1] + fmaxf(a[2], 0.f) * wv[q][2] + fmaxf(a[3], 0.f) * wv[q][3];
;                         }
;                     }
;                     const int rr = 4 * tile + r4;
;                     const float rscale = rsqrtf((rc[r4].x + rc[r4].y) * (1.f / 64.f) + EPS);
;                     const bool live = 64 * rr + lane < L;
; #pragma unroll
;                     for (int q = 0; q < 2; ++q) {
;                         float hx; const float A = half_sum32(pt[q][0], pt[q][2], hx), B = half_sum32(pt[q][1], pt[q][3], hx);
;                         const bool odd = fq & 1;
;                         const float send = odd ? A : B, keep = odd ? B : A;
;                         const float sc = live ? (keep + __shfl_xor(send, 16)) * rscale : -INFINITY;
;                         const unsigned bts = __float_as_uint(sc);
;                         uk[q][rr] = bts ^ ((unsigned)((int)bts >> 31) | 0x80000000u);
;                     }
.LBB0_695:
	s_or_b64 exec, exec, s[4:5]
	ds_read_b128 v[34:37], v131 offset:64512
	ds_read_b128 v[38:41], v131 offset:64576
	ds_read_b128 v[46:49], v152 offset:29952
	ds_read_b128 v[160:163], v152 offset:30016
	v_add_f32_e32 v90, v90, v91
	v_fmamk_f32 v90, v90, 0x3c800000, v222
	s_waitcnt lgkmcnt(3)
	v_mfma_f32_16x16x32_bf16 v[42:45], v[14:17], v[34:37], 0
	v_mul_f32_e32 v91, 0x4b800000, v90
	v_cmp_gt_f32_e32 vcc, s18, v90
	ds_read_b128 v[172:175], v152 offset:34624
	s_waitcnt lgkmcnt(3)
	v_mfma_f32_16x16x32_bf16 v[42:45], v[10:13], v[38:41], v[42:45]
	v_cndmask_b32_e32 v90, v90, v91, vcc
	v_rsq_f32_e32 v90, v90
	v_mfma_f32_16x16x32_bf16 v[34:37], v[2:5], v[34:37], 0
	v_mfma_f32_16x16x32_bf16 v[34:37], v[6:9], v[38:41], v[34:37]
	s_nop 3
	v_max_f32_e32 v42, v42, v42
	v_max_f32_e32 v43, v43, v43
	v_max_f32_e32 v44, v44, v44
	v_max_f32_e32 v148, 0, v45
	v_max_f32_e32 v149, 0, v42
	v_max_f32_e32 v147, 0, v43
	v_max_f32_e32 v151, 0, v44
	s_waitcnt lgkmcnt(2)
	v_mfma_f32_16x16x32_bf16 v[42:45], v[14:17], v[46:49], 0
	v_mul_f32_e32 v147, v147, v75
	v_fmac_f32_e32 v147, v149, v74
	v_fmac_f32_e32 v147, v151, v79
	s_waitcnt lgkmcnt(1)
	v_mfma_f32_16x16x32_bf16 v[42:45], v[10:13], v[160:163], v[42:45]
	v_fmac_f32_e32 v147, v148, v78
	s_nop 5
	s_nop 0
	v_max_f32_e32 v38, 0, v43
	v_mul_f32_e32 v149, v38, v75
	v_mfma_f32_16x16x32_bf16 v[38:41], v[2:5], v[46:49], 0
	ds_read_b128 v[46:49], v152 offset:32256
	v_max_f32_e32 v42, 0, v42
	v_mfma_f32_16x16x32_bf16 v[38:41], v[6:9], v[160:163], v[38:41]
	ds_read_b128 v[160:163], v152 offset:32320
	v_fmac_f32_e32 v149, v42, v74
	s_waitcnt lgkmcnt(1)
	v_mfma_f32_16x16x32_bf16 v[168:171], v[14:17], v[46:49], 0
	v_max_f32_e32 v42, 0, v44
	v_fmac_f32_e32 v149, v42, v79
	s_waitcnt lgkmcnt(0)
	v_mfma_f32_16x16x32_bf16 v[168:171], v[10:13], v[160:163], v[168:171]
	v_max_f32_e32 v42, 0, v45
	v_fmac_f32_e32 v149, v42, v78
	s_nop 5
	v_max_f32_e32 v148, 0, v168
	v_max_f32_e32 v42, 0, v169
	v_mul_f32_e32 v151, v42, v75
	v_mfma_f32_16x16x32_bf16 v[42:45], v[2:5], v[46:49], 0
	ds_read_b128 v[46:49], v152 offset:34560
	v_fmac_f32_e32 v151, v148, v74
	v_mfma_f32_16x16x32_bf16 v[42:45], v[6:9], v[160:163], v[42:45]
	v_max_f32_e32 v148, 0, v170
	v_fmac_f32_e32 v151, v148, v79
	s_waitcnt lgkmcnt(0)
	v_mfma_f32_16x16x32_bf16 v[160:163], v[14:17], v[46:49], 0
	v_max_f32_e32 v148, 0, v171
	v_fmac_f32_e32 v151, v148, v78
	s_nop 1
	v_permlane32_swap_b32_e32 v147, v151
	v_mfma_f32_16x16x32_bf16 v[160:163], v[10:13], v[172:175], v[160:163]
	v_mfma_f32_16x16x32_bf16 v[46:49], v[2:5], v[46:49], 0
	v_mfma_f32_16x16x32_bf16 v[46:49], v[6:9], v[172:175], v[46:49]
	s_nop 5
	v_max_f32_e32 v148, 0, v160
	v_max_f32_e32 v160, 0, v161
	v_mul_f32_e32 v160, v160, v75
	v_fmac_f32_e32 v160, v148, v74
	v_max_f32_e32 v148, 0, v162
	v_fmac_f32_e32 v160, v148, v79
	v_max_f32_e32 v91, 0, v163
	v_fmac_f32_e32 v160, v91, v78
	v_mul_f32_e32 v91, 0x45800000, v90
	v_cndmask_b32_e32 v148, v90, v91, vcc
	v_or_b32_e32 v90, 0x5c0, v124
	v_cmp_gt_u32_e32 vcc, s81, v90
	v_permlane32_swap_b32_e32 v149, v160
	v_mov_b32_e32 v91, 0xff800000
	v_mov_b32_e32 v90, 0xff800000
	s_and_saveexec_b64 s[4:5], vcc
	s_cbranch_execz .LBB0_697
	v_add_f32_e32 v90, v149, v160
	v_add_f32_e32 v147, v147, v151
	v_cndmask_b32_e64 v149, v147, v90, s[6:7]
	ds_bpermute_b32 v149, v130, v149
	v_cndmask_b32_e64 v90, v90, v147, s[6:7]
	s_waitcnt lgkmcnt(0)
	v_add_f32_e32 v90, v90, v149
	v_mul_f32_e32 v90, v148, v90
.LBB0_697:
	s_or_b64 exec, exec, s[4:5]
	v_max_f32_e32 v147, 0, v34
	v_max_f32_e32 v34, 0, v35
	v_mul_f32_e32 v34, v34, v77
	v_fmac_f32_e32 v34, v147, v76
	v_max_f32_e32 v35, 0, v36
	v_fmac_f32_e32 v34, v35, v81
	v_max_f32_e32 v35, 0, v37
	v_fmac_f32_e32 v34, v35, v80
	v_max_f32_e32 v36, 0, v38
	v_max_f32_e32 v35, 0, v39
	v_mul_f32_e32 v35, v35, v77
	v_fmac_f32_e32 v35, v36, v76
	v_max_f32_e32 v36, 0, v40
	v_fmac_f32_e32 v35, v36, v81
	v_max_f32_e32 v36, 0, v41
	v_fmac_f32_e32 v35, v36, v80
	v_max_f32_e32 v37, 0, v42
	v_max_f32_e32 v36, 0, v43
	v_mul_f32_e32 v36, v36, v77
	v_fmac_f32_e32 v36, v37, v76
	v_max_f32_e32 v37, 0, v44
	v_fmac_f32_e32 v36, v37, v81
	v_max_f32_e32 v37, 0, v45
	v_fmac_f32_e32 v36, v37, v80
	v_max_f32_e32 v38, 0, v46
	v_max_f32_e32 v37, 0, v47
	v_mul_f32_e32 v37, v37, v77
	v_fmac_f32_e32 v37, v38, v76
	v_max_f32_e32 v38, 0, v48
	v_fmac_f32_e32 v37, v38, v81
	v_max_f32_e32 v38, 0, v49
	v_fmac_f32_e32 v37, v38, v80
	v_permlane32_swap_b32_e32 v34, v36
	s_nop 0
	v_permlane32_swap_b32_e32 v35, v37
	s_and_saveexec_b64 s[4:5], vcc
	s_cbranch_execz .LBB0_699
	v_add_f32_e32 v35, v35, v37
	v_add_f32_e32 v34, v34, v36
	v_cndmask_b32_e64 v36, v34, v35, s[6:7]
	ds_bpermute_b32 v36, v130, v36
	v_cndmask_b32_e64 v34, v35, v34, s[6:7]
	s_waitcnt lgkmcnt(0)
	v_add_f32_e32 v34, v34, v36
	v_mul_f32_e32 v91, v148, v34

; #define LAS __attribute__((address_space(3)))
; __device__ __forceinline__ f32x4 mfma16(bf16x8 a, bf16x8 b, f32x4 c) { return __builtin_amdgcn_mfma_f32_16x16x32_bf16(a, b, c, 0, 0, 0); }
; __device__ __forceinline__ void att_unit(LAS unsigned char* lds, const bf16* P, const bf16* AKV, const bf16* IKC, bf16* ACAT, const float* aqg, const float* ssq_ak, const float* ssq_ik, int b, int qg, int tid) {
;     ...
;                 for (int r4 = 0; r4 < 4; ++r4) {
;                     float pt[2][4];
; #pragma unroll
;                     for (int q4 = 0; q4 < 4; ++q4) {
;                         const LAS unsigned char* kp = IKc + (64 * r4 + 16 * q4 + fr) * 144 + fq * 16;
;                         const bf16x8 K0 = *(const LAS bf16x8*)kp, K1 = *(const LAS bf16x8*)(kp + 64);
; #pragma unroll
;                         for (int q = 0; q < 2; ++q) {
;                             f32x4 a = (f32x4){0.f, 0.f, 0.f, 0.f};
;                             a = mfma16(Qi[q][0], K0, a); a = mfma16(Qi[q][1], K1, a);
;                             pt[q][q4] = fmaxf(a[0], 0.f) * wv[q][0] + fmaxf(a[1], 0.f) * wv[q][1] + fmaxf(a[2], 0.f) * wv[q][2] + fmaxf(a[3], 0.f) * wv[q][3];
;                         }
;                     }
;                     const int rr = 4 * tile + r4;
;                     const float rscale = rsqrtf((rc[r4].x + rc[r4].y) * (1.f / 64.f) + EPS);
;                     const bool live = 64 * rr + lane < L;
; #pragma unroll
;                     for (int q = 0; q < 2; ++q) {
;                         float hx; const float A = half_sum32(pt[q][0], pt[q][2], hx), B = half_sum32(pt[q][1], pt[q][3], hx);
;                         const bool odd = fq & 1;
;                         const float send = odd ? A : B, keep = odd ? B : A;
;                         const float sc = live ? (keep + __shfl_xor(send, 16)) * rscale : -INFINITY;
;                         const unsigned bts = __float_as_uint(sc);
;                         uk[q][rr] = bts ^ ((unsigned)((int)bts >> 31) | 0x80000000u);
;                     }
.LBB0_705:
	s_or_b64 exec, exec, s[4:5]
	ds_read_b128 v[34:37], v131
	ds_read_b128 v[38:41], v131 offset:64
	ds_read_b128 v[46:49], v131 offset:2304
	ds_read_b128 v[172:175], v131 offset:2368
	s_waitcnt lgkmcnt(3)
	v_mfma_f32_16x16x32_bf16 v[42:45], v[14:17], v[34:37], 0
	s_waitcnt lgkmcnt(2)
	v_mfma_f32_16x16x32_bf16 v[42:45], v[10:13], v[38:41], v[42:45]
	v_mfma_f32_16x16x32_bf16 v[34:37], v[2:5], v[34:37], 0
	v_mfma_f32_16x16x32_bf16 v[34:37], v[6:9], v[38:41], v[34:37]
	s_nop 5
	v_max_f32_e32 v42, v42, v42
	v_max_f32_e32 v43, v43, v43
	v_max_f32_e32 v44, v44, v44
	v_max_f32_e32 v88, 0, v45
	v_max_f32_e32 v89, 0, v42
	v_max_f32_e32 v160, 0, v43
	v_max_f32_e32 v161, 0, v44
	s_waitcnt lgkmcnt(1)
	v_mfma_f32_16x16x32_bf16 v[42:45], v[14:17], v[46:49], 0
	v_mul_f32_e32 v160, v160, v75
	v_fmac_f32_e32 v160, v89, v74
	v_fmac_f32_e32 v160, v161, v79
	s_waitcnt lgkmcnt(0)
	v_mfma_f32_16x16x32_bf16 v[42:45], v[10:13], v[172:175], v[42:45]
	v_fmac_f32_e32 v160, v88, v78
	s_nop 5
	s_nop 0
	v_max_f32_e32 v38, 0, v43
	v_mul_f32_e32 v161, v38, v75
	v_mfma_f32_16x16x32_bf16 v[38:41], v[2:5], v[46:49], 0
	ds_read_b128 v[46:49], v131 offset:4608
	v_max_f32_e32 v42, 0, v42
	v_mfma_f32_16x16x32_bf16 v[38:41], v[6:9], v[172:175], v[38:41]
	ds_read_b128 v[172:175], v131 offset:4672
	v_fmac_f32_e32 v161, v42, v74
	s_waitcnt lgkmcnt(1)
	v_mfma_f32_16x16x32_bf16 v[176:179], v[14:17], v[46:49], 0
	v_max_f32_e32 v42, 0, v44
	v_fmac_f32_e32 v161, v42, v79
	s_waitcnt lgkmcnt(0)
	v_mfma_f32_16x16x32_bf16 v[176:179], v[10:13], v[172:175], v[176:179]
	v_max_f32_e32 v42, 0, v45
	v_fmac_f32_e32 v161, v42, v78
	s_nop 5
	v_max_f32_e32 v88, 0, v176
	v_max_f32_e32 v42, 0, v177
	v_mul_f32_e32 v162, v42, v75
	v_mfma_f32_16x16x32_bf16 v[42:45], v[2:5], v[46:49], 0
	ds_read_b128 v[46:49], v131 offset:6912
	v_fmac_f32_e32 v162, v88, v74
	v_mfma_f32_16x16x32_bf16 v[42:45], v[6:9], v[172:175], v[42:45]
	ds_read_b128 v[172:175], v131 offset:6976
	v_max_f32_e32 v88, 0, v178
	v_fmac_f32_e32 v162, v88, v79
	s_waitcnt lgkmcnt(1)
	v_mfma_f32_16x16x32_bf16 v[180:183], v[14:17], v[46:49], 0
	v_max_f32_e32 v88, 0, v179
	v_fmac_f32_e32 v162, v88, v78
	s_waitcnt lgkmcnt(0)
	v_mfma_f32_16x16x32_bf16 v[176:179], v[10:13], v[172:175], v[180:183]
	v_permlane32_swap_b32_e32 v160, v162
	v_mfma_f32_16x16x32_bf16 v[46:49], v[2:5], v[46:49], 0
	v_mfma_f32_16x16x32_bf16 v[46:49], v[6:9], v[172:175], v[46:49]
	s_nop 4
	v_max_f32_e32 v89, 0, v177
	v_mul_f32_e32 v163, v89, v75
	v_add_f32_e32 v89, v102, v103
	v_fmamk_f32 v89, v89, 0x3c800000, v222
	v_mul_f32_e32 v102, 0x4b800000, v89
	v_cmp_gt_f32_e32 vcc, s18, v89
	v_max_f32_e32 v88, 0, v176
	v_fmac_f32_e32 v163, v88, v74
	v_cndmask_b32_e32 v89, v89, v102, vcc
	v_rsq_f32_e32 v89, v89
	v_max_f32_e32 v88, 0, v178
	v_fmac_f32_e32 v163, v88, v79
	v_max_f32_e32 v88, 0, v179
	v_fmac_f32_e32 v163, v88, v78
	v_mul_f32_e32 v88, 0x45800000, v89
	v_cndmask_b32_e32 v102, v89, v88, vcc
	v_or_b32_e32 v88, 0x600, v124
	v_cmp_gt_u32_e32 vcc, s81, v88
	v_permlane32_swap_b32_e32 v161, v163
	v_mov_b32_e32 v89, 0xff800000
	v_mov_b32_e32 v88, 0xff800000
	s_and_saveexec_b64 s[4:5], vcc
	s_cbranch_execz .LBB0_707
	v_add_f32_e32 v88, v161, v163
	v_add_f32_e32 v103, v160, v162
	v_cndmask_b32_e64 v160, v103, v88, s[6:7]
	ds_bpermute_b32 v160, v130, v160
	v_cndmask_b32_e64 v88, v88, v103, s[6:7]
	s_waitcnt lgkmcnt(0)
	v_add_f32_e32 v88, v88, v160
	v_mul_f32_e32 v88, v102, v88
.LBB0_707:
	s_or_b64 exec, exec, s[4:5]
	v_max_f32_e32 v103, 0, v34
	v_max_f32_e32 v34, 0, v35
	v_mul_f32_e32 v34, v34, v77
	v_fmac_f32_e32 v34, v103, v76
	v_max_f32_e32 v35, 0, v36
	v_fmac_f32_e32 v34, v35, v81
	v_max_f32_e32 v35, 0, v37
	v_fmac_f32_e32 v34, v35, v80
	v_max_f32_e32 v36, 0, v38
	v_max_f32_e32 v35, 0, v39
	v_mul_f32_e32 v35, v35, v77
	v_fmac_f32_e32 v35, v36, v76
	v_max_f32_e32 v36, 0, v40
	v_fmac_f32_e32 v35, v36, v81
	v_max_f32_e32 v36, 0, v41
	v_fmac_f32_e32 v35, v36, v80
	v_max_f32_e32 v37, 0, v42
	v_max_f32_e32 v36, 0, v43
	v_mul_f32_e32 v36, v36, v77
	v_fmac_f32_e32 v36, v37, v76
	v_max_f32_e32 v37, 0, v44
	v_fmac_f32_e32 v36, v37, v81
	v_max_f32_e32 v37, 0, v45
	v_fmac_f32_e32 v36, v37, v80
	v_max_f32_e32 v38, 0, v46
	v_max_f32_e32 v37, 0, v47
	v_mul_f32_e32 v37, v37, v77
	v_fmac_f32_e32 v37, v38, v76
	v_max_f32_e32 v38, 0, v48
	v_fmac_f32_e32 v37, v38, v81
	v_max_f32_e32 v38, 0, v49
	v_fmac_f32_e32 v37, v38, v80
	v_permlane32_swap_b32_e32 v34, v36
	s_nop 0
	v_permlane32_swap_b32_e32 v35, v37
	s_and_saveexec_b64 s[4:5], vcc
	s_cbranch_execz .LBB0_709
	v_add_f32_e32 v35, v35, v37
	v_add_f32_e32 v34, v34, v36
	v_cndmask_b32_e64 v36, v34, v35, s[6:7]
	ds_bpermute_b32 v36, v130, v36
	v_cndmask_b32_e64 v34, v35, v34, s[6:7]
	s_waitcnt lgkmcnt(0)
	v_add_f32_e32 v34, v34, v36
	v_mul_f32_e32 v89, v102, v34
; #define LAS __attribute__((address_space(3)))
; __device__ __forceinline__ f32x4 mfma16(bf16x8 a, bf16x8 b, f32x4 c) { return __builtin_amdgcn_mfma_f32_16x16x32_bf16(a, b, c, 0, 0, 0); }
; __device__ __forceinline__ void att_unit(LAS unsigned char* lds, const bf16* P, const bf16* AKV, const bf16* IKC, bf16* ACAT, const float* aqg, const float* ssq_ak, const float* ssq_ik, int b, int qg, int tid) {
;     ...
;                 for (int r4 = 0; r4 < 4; ++r4) {
;                     float pt[2][4];
; #pragma unroll
;                     for (int q4 = 0; q4 < 4; ++q4) {
;                         const LAS unsigned char* kp = IKc + (64 * r4 + 16 * q4 + fr) * 144 + fq * 16;
;                         const bf16x8 K0 = *(const LAS bf16x8*)kp, K1 = *(const LAS bf16x8*)(kp + 64);
; #pragma unroll
;                         for (int q = 0; q < 2; ++q) {
;                             f32x4 a = (f32x4){0.f, 0.f, 0.f, 0.f};
;                             a = mfma16(Qi[q][0], K0, a); a = mfma16(Qi[q][1], K1, a);
;                             pt[q][q4] = fmaxf(a[0], 0.f) * wv[q][0] + fmaxf(a[1], 0.f) * wv[q][1] + fmaxf(a[2], 0.f) * wv[q][2] + fmaxf(a[3], 0.f) * wv[q][3];
;                         }
;                     }
;                     const int rr = 4 * tile + r4;
;                     const float rscale = rsqrtf((rc[r4].x + rc[r4].y) * (1.f / 64.f) + EPS);
;                     const bool live = 64 * rr + lane < L;
; #pragma unroll
;                     for (int q = 0; q < 2; ++q) {
;                         float hx; const float A = half_sum32(pt[q][0], pt[q][2], hx), B = half_sum32(pt[q][1], pt[q][3], hx);
;                         const bool odd = fq & 1;
;                         const float send = odd ? A : B, keep = odd ? B : A;
;                         const float sc = live ? (keep + __shfl_xor(send, 16)) * rscale : -INFINITY;
;                         const unsigned bts = __float_as_uint(sc);
;                         uk[q][rr] = bts ^ ((unsigned)((int)bts >> 31) | 0x80000000u);
;                     }
.LBB0_709:
	s_or_b64 exec, exec, s[4:5]
	ds_read_b128 v[34:37], v131 offset:9216
	ds_read_b128 v[38:41], v131 offset:9280
	ds_read_b128 v[46:49], v131 offset:11520
	ds_read_b128 v[172:175], v131 offset:11584
	v_add_f32_e32 v98, v98, v99
	v_fmamk_f32 v98, v98, 0x3c800000, v222
	s_waitcnt lgkmcnt(3)
	v_mfma_f32_16x16x32_bf16 v[42:45], v[14:17], v[34:37], 0
	v_mul_f32_e32 v99, 0x4b800000, v98
	v_cmp_gt_f32_e32 vcc, s18, v98
	s_waitcnt lgkmcnt(2)
	v_mfma_f32_16x16x32_bf16 v[42:45], v[10:13], v[38:41], v[42:45]
	v_cndmask_b32_e32 v98, v98, v99, vcc
	v_rsq_f32_e32 v98, v98
	v_mfma_f32_16x16x32_bf16 v[34:37], v[2:5], v[34:37], 0
	v_mfma_f32_16x16x32_bf16 v[34:37], v[6:9], v[38:41], v[34:37]
	s_nop 3
	v_max_f32_e32 v42, v42, v42
	v_max_f32_e32 v43, v43, v43
	v_max_f32_e32 v44, v44, v44
	v_max_f32_e32 v103, 0, v45
	v_max_f32_e32 v160, 0, v42
	v_max_f32_e32 v102, 0, v43
	v_max_f32_e32 v161, 0, v44
	s_waitcnt lgkmcnt(1)
	v_mfma_f32_16x16x32_bf16 v[42:45], v[14:17], v[46:49], 0
	v_mul_f32_e32 v102, v102, v75
	v_fmac_f32_e32 v102, v160, v74
	v_fmac_f32_e32 v102, v161, v79
	s_waitcnt lgkmcnt(0)
	v_mfma_f32_16x16x32_bf16 v[42:45], v[10:13], v[172:175], v[42:45]
	v_fmac_f32_e32 v102, v103, v78
	s_nop 5
	s_nop 0
	v_max_f32_e32 v38, 0, v43
	v_mul_f32_e32 v160, v38, v75
	v_mfma_f32_16x16x32_bf16 v[38:41], v[2:5], v[46:49], 0
	ds_read_b128 v[46:49], v131 offset:13824
	v_max_f32_e32 v42, 0, v42
	v_mfma_f32_16x16x32_bf16 v[38:41], v[6:9], v[172:175], v[38:41]
	ds_read_b128 v[172:175], v131 offset:13888
	v_fmac_f32_e32 v160, v42, v74
	s_waitcnt lgkmcnt(1)
	v_mfma_f32_16x16x32_bf16 v[176:179], v[14:17], v[46:49], 0
	v_max_f32_e32 v42, 0, v44
	v_fmac_f32_e32 v160, v42, v79
	s_waitcnt lgkmcnt(0)
	v_mfma_f32_16x16x32_bf16 v[176:179], v[10:13], v[172:175], v[176:179]
	v_max_f32_e32 v42, 0, v45
	v_fmac_f32_e32 v160, v42, v78
	s_nop 5
	v_max_f32_e32 v103, 0, v176
	v_max_f32_e32 v42, 0, v177
	v_mul_f32_e32 v161, v42, v75
	v_mfma_f32_16x16x32_bf16 v[42:45], v[2:5], v[46:49], 0
	ds_read_b128 v[46:49], v131 offset:16128
	v_fmac_f32_e32 v161, v103, v74
	v_mfma_f32_16x16x32_bf16 v[42:45], v[6:9], v[172:175], v[42:45]
	ds_read_b128 v[172:175], v131 offset:16192
	v_max_f32_e32 v103, 0, v178
	v_fmac_f32_e32 v161, v103, v79
	s_waitcnt lgkmcnt(1)
	v_mfma_f32_16x16x32_bf16 v[180:183], v[14:17], v[46:49], 0
	v_max_f32_e32 v103, 0, v179
	v_fmac_f32_e32 v161, v103, v78
	s_waitcnt lgkmcnt(0)
	v_mfma_f32_16x16x32_bf16 v[176:179], v[10:13], v[172:175], v[180:183]
	v_permlane32_swap_b32_e32 v102, v161
	v_mfma_f32_16x16x32_bf16 v[46:49], v[2:5], v[46:49], 0
	v_mfma_f32_16x16x32_bf16 v[46:49], v[6:9], v[172:175], v[46:49]
	s_nop 4
	v_max_f32_e32 v162, 0, v177
	v_max_f32_e32 v103, 0, v176
	v_mul_f32_e32 v162, v162, v75
	v_fmac_f32_e32 v162, v103, v74
	v_max_f32_e32 v103, 0, v178
	v_fmac_f32_e32 v162, v103, v79
	v_max_f32_e32 v99, 0, v179
	v_fmac_f32_e32 v162, v99, v78
	v_mul_f32_e32 v99, 0x45800000, v98
	v_cndmask_b32_e32 v103, v98, v99, vcc
	v_or_b32_e32 v98, 0x640, v124
	v_cmp_gt_u32_e32 vcc, s81, v98
	v_permlane32_swap_b32_e32 v160, v162
	v_mov_b32_e32 v99, 0xff800000
	v_mov_b32_e32 v98, 0xff800000
	s_and_saveexec_b64 s[4:5], vcc
	s_cbranch_execz .LBB0_711
	v_add_f32_e32 v98, v160, v162
	v_add_f32_e32 v102, v102, v161
	v_cndmask_b32_e64 v160, v102, v98, s[6:7]
	ds_bpermute_b32 v160, v130, v160
	v_cndmask_b32_e64 v98, v98, v102, s[6:7]
	s_waitcnt lgkmcnt(0)
	v_add_f32_e32 v98, v98, v160
	v_mul_f32_e32 v98, v103, v98
.LBB0_711:
	s_or_b64 exec, exec, s[4:5]
	v_max_f32_e32 v102, 0, v34
	v_max_f32_e32 v34, 0, v35
	v_mul_f32_e32 v34, v34, v77
	v_fmac_f32_e32 v34, v102, v76
	v_max_f32_e32 v35, 0, v36
	v_fmac_f32_e32 v34, v35, v81
	v_max_f32_e32 v35, 0, v37
	v_fmac_f32_e32 v34, v35, v80
	v_max_f32_e32 v36, 0, v38
	v_max_f32_e32 v35, 0, v39
	v_mul_f32_e32 v35, v35, v77
	v_fmac_f32_e32 v35, v36, v76
	v_max_f32_e32 v36, 0, v40
	v_fmac_f32_e32 v35, v36, v81
	v_max_f32_e32 v36, 0, v41
	v_fmac_f32_e32 v35, v36, v80
	v_max_f32_e32 v37, 0, v42
	v_max_f32_e32 v36, 0, v43
	v_mul_f32_e32 v36, v36, v77
	v_fmac_f32_e32 v36, v37, v76
	v_max_f32_e32 v37, 0, v44
	v_fmac_f32_e32 v36, v37, v81
	v_max_f32_e32 v37, 0, v45
	v_fmac_f32_e32 v36, v37, v80
	v_max_f32_e32 v38, 0, v46
	v_max_f32_e32 v37, 0, v47
	v_mul_f32_e32 v37, v37, v77
	v_fmac_f32_e32 v37, v38, v76
	v_max_f32_e32 v38, 0, v48
	v_fmac_f32_e32 v37, v38, v81
	v_max_f32_e32 v38, 0, v49
	v_fmac_f32_e32 v37, v38, v80
	v_permlane32_swap_b32_e32 v34, v36
	s_nop 0
	v_permlane32_swap_b32_e32 v35, v37
	s_and_saveexec_b64 s[4:5], vcc
	s_cbranch_execz .LBB0_713
	v_add_f32_e32 v35, v35, v37
	v_add_f32_e32 v34, v34, v36
	v_cndmask_b32_e64 v36, v34, v35, s[6:7]
	ds_bpermute_b32 v36, v130, v36
	v_cndmask_b32_e64 v34, v35, v34, s[6:7]
	s_waitcnt lgkmcnt(0)
	v_add_f32_e32 v34, v34, v36
	v_mul_f32_e32 v99, v103, v34
; #define LAS __attribute__((address_space(3)))
; __device__ __forceinline__ f32x4 mfma16(bf16x8 a, bf16x8 b, f32x4 c) { return __builtin_amdgcn_mfma_f32_16x16x32_bf16(a, b, c, 0, 0, 0); }
; __device__ __forceinline__ void att_unit(LAS unsigned char* lds, const bf16* P, const bf16* AKV, const bf16* IKC, bf16* ACAT, const float* aqg, const float* ssq_ak, const float* ssq_ik, int b, int qg, int tid) {
;     ...
;                 for (int r4 = 0; r4 < 4; ++r4) {
;                     float pt[2][4];
; #pragma unroll
;                     for (int q4 = 0; q4 < 4; ++q4) {
;                         const LAS unsigned char* kp = IKc + (64 * r4 + 16 * q4 + fr) * 144 + fq * 16;
;                         const bf16x8 K0 = *(const LAS bf16x8*)kp, K1 = *(const LAS bf16x8*)(kp + 64);
; #pragma unroll
;                         for (int q = 0; q < 2; ++q) {
;                             f32x4 a = (f32x4){0.f, 0.f, 0.f, 0.f};
;                             a = mfma16(Qi[q][0], K0, a); a = mfma16(Qi[q][1], K1, a);
;                             pt[q][q4] = fmaxf(a[0], 0.f) * wv[q][0] + fmaxf(a[1], 0.f) * wv[q][1] + fmaxf(a[2], 0.f) * wv[q][2] + fmaxf(a[3], 0.f) * wv[q][3];
;                         }
;                     }
;                     const int rr = 4 * tile + r4;
;                     const float rscale = rsqrtf((rc[r4].x + rc[r4].y) * (1.f / 64.f) + EPS);
;                     const bool live = 64 * rr + lane < L;
; #pragma unroll
;                     for (int q = 0; q < 2; ++q) {
;                         float hx; const float A = half_sum32(pt[q][0], pt[q][2], hx), B = half_sum32(pt[q][1], pt[q][3], hx);
;                         const bool odd = fq & 1;
;                         const float send = odd ? A : B, keep = odd ? B : A;
;                         const float sc = live ? (keep + __shfl_xor(send, 16)) * rscale : -INFINITY;
;                         const unsigned bts = __float_as_uint(sc);
;                         uk[q][rr] = bts ^ ((unsigned)((int)bts >> 31) | 0x80000000u);
;                     }
.LBB0_713:
	s_or_b64 exec, exec, s[4:5]
	ds_read_b128 v[34:37], v131 offset:18432
	ds_read_b128 v[38:41], v131 offset:18496
	ds_read_b128 v[46:49], v131 offset:20736
	ds_read_b128 v[172:175], v131 offset:20800
	v_add_f32_e32 v96, v96, v97
	v_fmamk_f32 v96, v96, 0x3c800000, v222
	s_waitcnt lgkmcnt(3)
	v_mfma_f32_16x16x32_bf16 v[42:45], v[14:17], v[34:37], 0
	v_mul_f32_e32 v97, 0x4b800000, v96
	v_cmp_gt_f32_e32 vcc, s18, v96
	s_waitcnt lgkmcnt(2)
	v_mfma_f32_16x16x32_bf16 v[42:45], v[10:13], v[38:41], v[42:45]
	v_cndmask_b32_e32 v96, v96, v97, vcc
	v_rsq_f32_e32 v96, v96
	v_mfma_f32_16x16x32_bf16 v[34:37], v[2:5], v[34:37], 0
	v_mfma_f32_16x16x32_bf16 v[34:37], v[6:9], v[38:41], v[34:37]
	s_nop 3
	v_max_f32_e32 v42, v42, v42
	v_max_f32_e32 v43, v43, v43
	v_max_f32_e32 v44, v44, v44
	v_max_f32_e32 v103, 0, v45
	v_max_f32_e32 v160, 0, v42
	v_max_f32_e32 v102, 0, v43
	v_max_f32_e32 v161, 0, v44
	s_waitcnt lgkmcnt(1)
	v_mfma_f32_16x16x32_bf16 v[42:45], v[14:17], v[46:49], 0
	v_mul_f32_e32 v102, v102, v75
	v_fmac_f32_e32 v102, v160, v74
	v_fmac_f32_e32 v102, v161, v79
	s_waitcnt lgkmcnt(0)
	v_mfma_f32_16x16x32_bf16 v[42:45], v[10:13], v[172:175], v[42:45]
	v_fmac_f32_e32 v102, v103, v78
	s_nop 5
	s_nop 0
	v_max_f32_e32 v38, 0, v43
	v_mul_f32_e32 v160, v38, v75
	v_mfma_f32_16x16x32_bf16 v[38:41], v[2:5], v[46:49], 0
	ds_read_b128 v[46:49], v131 offset:23040
	v_max_f32_e32 v42, 0, v42
	v_mfma_f32_16x16x32_bf16 v[38:41], v[6:9], v[172:175], v[38:41]
	ds_read_b128 v[172:175], v131 offset:23104
	v_fmac_f32_e32 v160, v42, v74
	s_waitcnt lgkmcnt(1)
	v_mfma_f32_16x16x32_bf16 v[176:179], v[14:17], v[46:49], 0
	v_max_f32_e32 v42, 0, v44
	v_fmac_f32_e32 v160, v42, v79
	s_waitcnt lgkmcnt(0)
	v_mfma_f32_16x16x32_bf16 v[176:179], v[10:13], v[172:175], v[176:179]
	v_max_f32_e32 v42, 0, v45
	v_fmac_f32_e32 v160, v42, v78
	s_nop 5
	v_max_f32_e32 v103, 0, v176
	v_max_f32_e32 v42, 0, v177
	v_mul_f32_e32 v161, v42, v75
	v_mfma_f32_16x16x32_bf16 v[42:45], v[2:5], v[46:49], 0
	ds_read_b128 v[46:49], v131 offset:25344
	v_fmac_f32_e32 v161, v103, v74
	v_mfma_f32_16x16x32_bf16 v[42:45], v[6:9], v[172:175], v[42:45]
	ds_read_b128 v[172:175], v131 offset:25408
	v_max_f32_e32 v103, 0, v178
	v_fmac_f32_e32 v161, v103, v79
	s_waitcnt lgkmcnt(1)
	v_mfma_f32_16x16x32_bf16 v[180:183], v[14:17], v[46:49], 0
	v_max_f32_e32 v103, 0, v179
	v_fmac_f32_e32 v161, v103, v78
	s_waitcnt lgkmcnt(0)
	v_mfma_f32_16x16x32_bf16 v[176:179], v[10:13], v[172:175], v[180:183]
	v_permlane32_swap_b32_e32 v102, v161
	v_mfma_f32_16x16x32_bf16 v[46:49], v[2:5], v[46:49], 0
	v_mfma_f32_16x16x32_bf16 v[46:49], v[6:9], v[172:175], v[46:49]
	s_nop 4
	v_max_f32_e32 v162, 0, v177
	v_max_f32_e32 v103, 0, v176
	v_mul_f32_e32 v162, v162, v75
	v_fmac_f32_e32 v162, v103, v74
	v_max_f32_e32 v103, 0, v178
	v_fmac_f32_e32 v162, v103, v79
	v_max_f32_e32 v97, 0, v179
	v_fmac_f32_e32 v162, v97, v78
	v_mul_f32_e32 v97, 0x45800000, v96
	v_cndmask_b32_e32 v103, v96, v97, vcc
	v_or_b32_e32 v96, 0x680, v124
	v_cmp_gt_u32_e32 vcc, s81, v96
	v_permlane32_swap_b32_e32 v160, v162
	v_mov_b32_e32 v97, 0xff800000
	v_mov_b32_e32 v96, 0xff800000
	s_and_saveexec_b64 s[4:5], vcc
	s_cbranch_execz .LBB0_715
	v_add_f32_e32 v96, v160, v162
	v_add_f32_e32 v102, v102, v161
	v_cndmask_b32_e64 v160, v102, v96, s[6:7]
	ds_bpermute_b32 v160, v130, v160
	v_cndmask_b32_e64 v96, v96, v102, s[6:7]
	s_waitcnt lgkmcnt(0)
	v_add_f32_e32 v96, v96, v160
	v_mul_f32_e32 v96, v103, v96
.LBB0_715:
	s_or_b64 exec, exec, s[4:5]
	v_max_f32_e32 v102, 0, v34
	v_max_f32_e32 v34, 0, v35
	v_mul_f32_e32 v34, v34, v77
	v_fmac_f32_e32 v34, v102, v76
	v_max_f32_e32 v35, 0, v36
	v_fmac_f32_e32 v34, v35, v81
	v_max_f32_e32 v35, 0, v37
	v_fmac_f32_e32 v34, v35, v80
	v_max_f32_e32 v36, 0, v38
	v_max_f32_e32 v35, 0, v39
	v_mul_f32_e32 v35, v35, v77
	v_fmac_f32_e32 v35, v36, v76
	v_max_f32_e32 v36, 0, v40
	v_fmac_f32_e32 v35, v36, v81
	v_max_f32_e32 v36, 0, v41
	v_fmac_f32_e32 v35, v36, v80
	v_max_f32_e32 v37, 0, v42
	v_max_f32_e32 v36, 0, v43
	v_mul_f32_e32 v36, v36, v77
	v_fmac_f32_e32 v36, v37, v76
	v_max_f32_e32 v37, 0, v44
	v_fmac_f32_e32 v36, v37, v81
	v_max_f32_e32 v37, 0, v45
	v_fmac_f32_e32 v36, v37, v80
	v_max_f32_e32 v38, 0, v46
	v_max_f32_e32 v37, 0, v47
	v_mul_f32_e32 v37, v37, v77
	v_fmac_f32_e32 v37, v38, v76
	v_max_f32_e32 v38, 0, v48
	v_fmac_f32_e32 v37, v38, v81
	v_max_f32_e32 v38, 0, v49
	v_fmac_f32_e32 v37, v38, v80
	v_permlane32_swap_b32_e32 v34, v36
	s_nop 0
	v_permlane32_swap_b32_e32 v35, v37
	s_and_saveexec_b64 s[4:5], vcc
	s_cbranch_execz .LBB0_717
	v_add_f32_e32 v35, v35, v37
	v_add_f32_e32 v34, v34, v36
	v_cndmask_b32_e64 v36, v34, v35, s[6:7]
	ds_bpermute_b32 v36, v130, v36
	v_cndmask_b32_e64 v34, v35, v34, s[6:7]
	s_waitcnt lgkmcnt(0)
	v_add_f32_e32 v34, v34, v36
	v_mul_f32_e32 v97, v103, v34
; #define LAS __attribute__((address_space(3)))
; __device__ __forceinline__ f32x4 mfma16(bf16x8 a, bf16x8 b, f32x4 c) { return __builtin_amdgcn_mfma_f32_16x16x32_bf16(a, b, c, 0, 0, 0); }
; __device__ __forceinline__ void att_unit(LAS unsigned char* lds, const bf16* P, const bf16* AKV, const bf16* IKC, bf16* ACAT, const float* aqg, const float* ssq_ak, const float* ssq_ik, int b, int qg, int tid) {
;     ...
;                 for (int r4 = 0; r4 < 4; ++r4) {
;                     float pt[2][4];
; #pragma unroll
;                     for (int q4 = 0; q4 < 4; ++q4) {
;                         const LAS unsigned char* kp = IKc + (64 * r4 + 16 * q4 + fr) * 144 + fq * 16;
;                         const bf16x8 K0 = *(const LAS bf16x8*)kp, K1 = *(const LAS bf16x8*)(kp + 64);
; #pragma unroll
;                         for (int q = 0; q < 2; ++q) {
;                             f32x4 a = (f32x4){0.f, 0.f, 0.f, 0.f};
;                             a = mfma16(Qi[q][0], K0, a); a = mfma16(Qi[q][1], K1, a);
;                             pt[q][q4] = fmaxf(a[0], 0.f) * wv[q][0] + fmaxf(a[1], 0.f) * wv[q][1] + fmaxf(a[2], 0.f) * wv[q][2] + fmaxf(a[3], 0.f) * wv[q][3];
;                         }
;                     }
;                     const int rr = 4 * tile + r4;
;                     const float rscale = rsqrtf((rc[r4].x + rc[r4].y) * (1.f / 64.f) + EPS);
;                     const bool live = 64 * rr + lane < L;
; #pragma unroll
;                     for (int q = 0; q < 2; ++q) {
;                         float hx; const float A = half_sum32(pt[q][0], pt[q][2], hx), B = half_sum32(pt[q][1], pt[q][3], hx);
;                         const bool odd = fq & 1;
;                         const float send = odd ? A : B, keep = odd ? B : A;
;                         const float sc = live ? (keep + __shfl_xor(send, 16)) * rscale : -INFINITY;
;                         const unsigned bts = __float_as_uint(sc);
;                         uk[q][rr] = bts ^ ((unsigned)((int)bts >> 31) | 0x80000000u);
;                     }
.LBB0_717:
	s_or_b64 exec, exec, s[4:5]
	ds_read_b128 v[34:37], v131 offset:27648
	ds_read_b128 v[38:41], v131 offset:27712
	ds_read_b128 v[46:49], v131 offset:29952
	ds_read_b128 v[172:175], v131 offset:30016
	v_add_f32_e32 v90, v90, v91
	v_fmamk_f32 v90, v90, 0x3c800000, v222
	s_waitcnt lgkmcnt(3)
	v_mfma_f32_16x16x32_bf16 v[42:45], v[14:17], v[34:37], 0
	v_mul_f32_e32 v91, 0x4b800000, v90
	v_cmp_gt_f32_e32 vcc, s18, v90
	s_waitcnt lgkmcnt(2)
	v_mfma_f32_16x16x32_bf16 v[42:45], v[10:13], v[38:41], v[42:45]
	v_cndmask_b32_e32 v90, v90, v91, vcc
	v_rsq_f32_e32 v90, v90
	v_mfma_f32_16x16x32_bf16 v[34:37], v[2:5], v[34:37], 0
	v_mfma_f32_16x16x32_bf16 v[34:37], v[6:9], v[38:41], v[34:37]
	s_nop 3
	v_max_f32_e32 v42, v42, v42
	v_max_f32_e32 v43, v43, v43
	v_max_f32_e32 v44, v44, v44
	v_max_f32_e32 v103, 0, v45
	v_max_f32_e32 v160, 0, v42
	v_max_f32_e32 v102, 0, v43
	v_max_f32_e32 v161, 0, v44
	s_waitcnt lgkmcnt(1)
	v_mfma_f32_16x16x32_bf16 v[42:45], v[14:17], v[46:49], 0
	v_mul_f32_e32 v102, v102, v75
	v_fmac_f32_e32 v102, v160, v74
	v_fmac_f32_e32 v102, v161, v79
	s_waitcnt lgkmcnt(0)
	v_mfma_f32_16x16x32_bf16 v[42:45], v[10:13], v[172:175], v[42:45]
	v_fmac_f32_e32 v102, v103, v78
	s_nop 5
	s_nop 0
	v_max_f32_e32 v38, 0, v43
	v_mul_f32_e32 v160, v38, v75
	v_mfma_f32_16x16x32_bf16 v[38:41], v[2:5], v[46:49], 0
	ds_read_b128 v[46:49], v131 offset:32256
	v_max_f32_e32 v42, 0, v42
	v_mfma_f32_16x16x32_bf16 v[38:41], v[6:9], v[172:175], v[38:41]
	ds_read_b128 v[172:175], v131 offset:32320
	v_fmac_f32_e32 v160, v42, v74
	s_waitcnt lgkmcnt(1)
	v_mfma_f32_16x16x32_bf16 v[176:179], v[14:17], v[46:49], 0
	v_max_f32_e32 v42, 0, v44
	v_fmac_f32_e32 v160, v42, v79
	s_waitcnt lgkmcnt(0)
	v_mfma_f32_16x16x32_bf16 v[176:179], v[10:13], v[172:175], v[176:179]
	v_max_f32_e32 v42, 0, v45
	v_fmac_f32_e32 v160, v42, v78
	s_nop 5
	v_max_f32_e32 v103, 0, v176
	v_max_f32_e32 v42, 0, v177
	v_mul_f32_e32 v161, v42, v75
	v_mfma_f32_16x16x32_bf16 v[42:45], v[2:5], v[46:49], 0
	ds_read_b128 v[46:49], v131 offset:34560
	v_fmac_f32_e32 v161, v103, v74
	v_mfma_f32_16x16x32_bf16 v[42:45], v[6:9], v[172:175], v[42:45]
	ds_read_b128 v[172:175], v131 offset:34624
	v_max_f32_e32 v103, 0, v178
	v_fmac_f32_e32 v161, v103, v79
	s_waitcnt lgkmcnt(1)
	v_mfma_f32_16x16x32_bf16 v[180:183], v[14:17], v[46:49], 0
	v_max_f32_e32 v103, 0, v179
	v_fmac_f32_e32 v161, v103, v78
	s_waitcnt lgkmcnt(0)
	v_mfma_f32_16x16x32_bf16 v[176:179], v[10:13], v[172:175], v[180:183]
	v_permlane32_swap_b32_e32 v102, v161
	v_mfma_f32_16x16x32_bf16 v[46:49], v[2:5], v[46:49], 0
	v_mfma_f32_16x16x32_bf16 v[46:49], v[6:9], v[172:175], v[46:49]
	s_nop 4
	v_max_f32_e32 v162, 0, v177
	v_max_f32_e32 v103, 0, v176
	v_mul_f32_e32 v162, v162, v75
	v_fmac_f32_e32 v162, v103, v74
	v_max_f32_e32 v103, 0, v178
	v_fmac_f32_e32 v162, v103, v79
	v_max_f32_e32 v91, 0, v179
	v_fmac_f32_e32 v162, v91, v78
	v_mul_f32_e32 v91, 0x45800000, v90
	v_cndmask_b32_e32 v103, v90, v91, vcc
	v_or_b32_e32 v90, 0x6c0, v124
	v_cmp_gt_u32_e32 vcc, s81, v90
	v_permlane32_swap_b32_e32 v160, v162
	v_mov_b32_e32 v91, 0xff800000
	v_mov_b32_e32 v90, 0xff800000
	s_and_saveexec_b64 s[4:5], vcc
	s_cbranch_execz .LBB0_719
	v_add_f32_e32 v90, v160, v162
	v_add_f32_e32 v102, v102, v161
	v_cndmask_b32_e64 v160, v102, v90, s[6:7]
	ds_bpermute_b32 v160, v130, v160
	v_cndmask_b32_e64 v90, v90, v102, s[6:7]
	s_waitcnt lgkmcnt(0)
	v_add_f32_e32 v90, v90, v160
	v_mul_f32_e32 v90, v103, v90
.LBB0_719:
	s_or_b64 exec, exec, s[4:5]
	v_max_f32_e32 v102, 0, v34
	v_max_f32_e32 v34, 0, v35
	v_mul_f32_e32 v34, v34, v77
	v_fmac_f32_e32 v34, v102, v76
	v_max_f32_e32 v35, 0, v36
	v_fmac_f32_e32 v34, v35, v81
	v_max_f32_e32 v35, 0, v37
	v_fmac_f32_e32 v34, v35, v80
	v_max_f32_e32 v36, 0, v38
	v_max_f32_e32 v35, 0, v39
	v_mul_f32_e32 v35, v35, v77
	v_fmac_f32_e32 v35, v36, v76
	v_max_f32_e32 v36, 0, v40
	v_fmac_f32_e32 v35, v36, v81
	v_max_f32_e32 v36, 0, v41
	v_fmac_f32_e32 v35, v36, v80
	v_max_f32_e32 v37, 0, v42
	v_max_f32_e32 v36, 0, v43
	v_mul_f32_e32 v36, v36, v77
	v_fmac_f32_e32 v36, v37, v76
	v_max_f32_e32 v37, 0, v44
	v_fmac_f32_e32 v36, v37, v81
	v_max_f32_e32 v37, 0, v45
	v_fmac_f32_e32 v36, v37, v80
	v_max_f32_e32 v38, 0, v46
	v_max_f32_e32 v37, 0, v47
	v_mul_f32_e32 v37, v37, v77
	v_fmac_f32_e32 v37, v38, v76
	v_max_f32_e32 v38, 0, v48
	v_fmac_f32_e32 v37, v38, v81
	v_max_f32_e32 v38, 0, v49
	v_fmac_f32_e32 v37, v38, v80
	v_permlane32_swap_b32_e32 v34, v36
	s_nop 0
	v_permlane32_swap_b32_e32 v35, v37
	s_and_saveexec_b64 s[4:5], vcc
	s_cbranch_execz .LBB0_721
	v_add_f32_e32 v35, v35, v37
	v_add_f32_e32 v34, v34, v36
	v_cndmask_b32_e64 v36, v34, v35, s[6:7]
	ds_bpermute_b32 v36, v130, v36
	v_cndmask_b32_e64 v34, v35, v34, s[6:7]
	s_waitcnt lgkmcnt(0)
	v_add_f32_e32 v34, v34, v36
	v_mul_f32_e32 v91, v103, v34

; #define LAS __attribute__((address_space(3)))
; __device__ __forceinline__ f32x4 mfma16(bf16x8 a, bf16x8 b, f32x4 c) { return __builtin_amdgcn_mfma_f32_16x16x32_bf16(a, b, c, 0, 0, 0); }
; __device__ __forceinline__ void att_unit(LAS unsigned char* lds, const bf16* P, const bf16* AKV, const bf16* IKC, bf16* ACAT, const float* aqg, const float* ssq_ak, const float* ssq_ik, int b, int qg, int tid) {
;     ...
;                 for (int r4 = 0; r4 < 4; ++r4) {
;                     float pt[2][4];
; #pragma unroll
;                     for (int q4 = 0; q4 < 4; ++q4) {
;                         const LAS unsigned char* kp = IKc + (64 * r4 + 16 * q4 + fr) * 144 + fq * 16;
;                         const bf16x8 K0 = *(const LAS bf16x8*)kp, K1 = *(const LAS bf16x8*)(kp + 64);
; #pragma unroll
;                         for (int q = 0; q < 2; ++q) {
;                             f32x4 a = (f32x4){0.f, 0.f, 0.f, 0.f};
;                             a = mfma16(Qi[q][0], K0, a); a = mfma16(Qi[q][1], K1, a);
;                             pt[q][q4] = fmaxf(a[0], 0.f) * wv[q][0] + fmaxf(a[1], 0.f) * wv[q][1] + fmaxf(a[2], 0.f) * wv[q][2] + fmaxf(a[3], 0.f) * wv[q][3];
;                         }
;                     }
;                     const int rr = 4 * tile + r4;
;                     const float rscale = rsqrtf((rc[r4].x + rc[r4].y) * (1.f / 64.f) + EPS);
;                     const bool live = 64 * rr + lane < L;
; #pragma unroll
;                     for (int q = 0; q < 2; ++q) {
;                         float hx; const float A = half_sum32(pt[q][0], pt[q][2], hx), B = half_sum32(pt[q][1], pt[q][3], hx);
;                         const bool odd = fq & 1;
;                         const float send = odd ? A : B, keep = odd ? B : A;
;                         const float sc = live ? (keep + __shfl_xor(send, 16)) * rscale : -INFINITY;
;                         const unsigned bts = __float_as_uint(sc);
;                         uk[q][rr] = bts ^ ((unsigned)((int)bts >> 31) | 0x80000000u);
;                     }
.LBB0_727:
	s_or_b64 exec, exec, s[4:5]
	ds_read_b128 v[34:37], v131 offset:36864
	ds_read_b128 v[38:41], v131 offset:36928
	ds_read_b128 v[46:49], v131 offset:39168
	ds_read_b128 v[104:107], v131 offset:39232
	s_waitcnt lgkmcnt(3)
	v_mfma_f32_16x16x32_bf16 v[42:45], v[14:17], v[34:37], 0
	s_waitcnt lgkmcnt(2)
	v_mfma_f32_16x16x32_bf16 v[42:45], v[10:13], v[38:41], v[42:45]
	v_mfma_f32_16x16x32_bf16 v[34:37], v[2:5], v[34:37], 0
	v_mfma_f32_16x16x32_bf16 v[34:37], v[6:9], v[38:41], v[34:37]
	s_nop 5
	v_max_f32_e32 v42, v42, v42
	v_max_f32_e32 v43, v43, v43
	v_max_f32_e32 v44, v44, v44
	v_max_f32_e32 v66, 0, v45
	v_max_f32_e32 v67, 0, v42
	v_max_f32_e32 v88, 0, v43
	v_max_f32_e32 v89, 0, v44
	s_waitcnt lgkmcnt(1)
	v_mfma_f32_16x16x32_bf16 v[42:45], v[14:17], v[46:49], 0
	v_mul_f32_e32 v88, v88, v75
	v_fmac_f32_e32 v88, v67, v74
	v_fmac_f32_e32 v88, v89, v79
	s_waitcnt lgkmcnt(0)
	v_mfma_f32_16x16x32_bf16 v[42:45], v[10:13], v[104:107], v[42:45]
	v_fmac_f32_e32 v88, v66, v78
	s_nop 5
	s_nop 0
	v_max_f32_e32 v38, 0, v43
	v_mul_f32_e32 v100, v38, v75
	v_mfma_f32_16x16x32_bf16 v[38:41], v[2:5], v[46:49], 0
	ds_read_b128 v[46:49], v131 offset:41472
	v_max_f32_e32 v42, 0, v42
	v_mfma_f32_16x16x32_bf16 v[38:41], v[6:9], v[104:107], v[38:41]
	ds_read_b128 v[104:107], v131 offset:41536
	v_fmac_f32_e32 v100, v42, v74
	s_waitcnt lgkmcnt(1)
	v_mfma_f32_16x16x32_bf16 v[176:179], v[14:17], v[46:49], 0
	v_max_f32_e32 v42, 0, v44
	v_fmac_f32_e32 v100, v42, v79
	s_waitcnt lgkmcnt(0)
	v_mfma_f32_16x16x32_bf16 v[176:179], v[10:13], v[104:107], v[176:179]
	v_max_f32_e32 v42, 0, v45
	v_fmac_f32_e32 v100, v42, v78
	s_nop 5
	v_max_f32_e32 v66, 0, v176
	v_max_f32_e32 v42, 0, v177
	v_mul_f32_e32 v101, v42, v75
	v_mfma_f32_16x16x32_bf16 v[42:45], v[2:5], v[46:49], 0
	ds_read_b128 v[46:49], v131 offset:43776
	v_fmac_f32_e32 v101, v66, v74
	v_mfma_f32_16x16x32_bf16 v[42:45], v[6:9], v[104:107], v[42:45]
	ds_read_b128 v[106:109], v131 offset:43840
	v_max_f32_e32 v66, 0, v178
	v_fmac_f32_e32 v101, v66, v79
	s_waitcnt lgkmcnt(1)
	v_mfma_f32_16x16x32_bf16 v[180:183], v[14:17], v[46:49], 0
	v_max_f32_e32 v66, 0, v179
	v_fmac_f32_e32 v101, v66, v78
	s_waitcnt lgkmcnt(0)
	v_mfma_f32_16x16x32_bf16 v[176:179], v[10:13], v[106:109], v[180:183]
	v_permlane32_swap_b32_e32 v88, v101
	v_mfma_f32_16x16x32_bf16 v[46:49], v[2:5], v[46:49], 0
	v_mfma_f32_16x16x32_bf16 v[46:49], v[6:9], v[106:109], v[46:49]
	s_nop 4
	v_max_f32_e32 v67, 0, v177
	v_mul_f32_e32 v104, v67, v75
	s_waitcnt vmcnt(3)
	v_add_f32_e32 v67, v102, v103
	v_fmamk_f32 v67, v67, 0x3c800000, v222
	v_mul_f32_e32 v89, 0x4b800000, v67
	v_cmp_gt_f32_e32 vcc, s18, v67
	v_max_f32_e32 v66, 0, v176
	v_fmac_f32_e32 v104, v66, v74
	v_cndmask_b32_e32 v67, v67, v89, vcc
	v_rsq_f32_e32 v67, v67
	v_max_f32_e32 v66, 0, v178
	v_fmac_f32_e32 v104, v66, v79
	v_max_f32_e32 v66, 0, v179
	v_fmac_f32_e32 v104, v66, v78
	v_mul_f32_e32 v66, 0x45800000, v67
	v_cndmask_b32_e32 v89, v67, v66, vcc
	v_or_b32_e32 v66, 0x700, v124
	v_cmp_gt_u32_e32 vcc, s81, v66
	v_permlane32_swap_b32_e32 v100, v104
	v_mov_b32_e32 v67, 0xff800000
	v_mov_b32_e32 v66, 0xff800000
	s_and_saveexec_b64 s[4:5], vcc
	s_cbranch_execz .LBB0_729
	v_add_f32_e32 v66, v100, v104
	v_add_f32_e32 v88, v88, v101
	v_cndmask_b32_e64 v100, v88, v66, s[6:7]
	ds_bpermute_b32 v100, v130, v100
	v_cndmask_b32_e64 v66, v66, v88, s[6:7]
	s_waitcnt lgkmcnt(0)
	v_add_f32_e32 v66, v66, v100
	v_mul_f32_e32 v66, v89, v66
.LBB0_729:
	s_or_b64 exec, exec, s[4:5]
	v_max_f32_e32 v88, 0, v34
	v_max_f32_e32 v34, 0, v35
	v_mul_f32_e32 v34, v34, v77
	v_fmac_f32_e32 v34, v88, v76
	v_max_f32_e32 v35, 0, v36
	v_fmac_f32_e32 v34, v35, v81
	v_max_f32_e32 v35, 0, v37
	v_fmac_f32_e32 v34, v35, v80
	v_max_f32_e32 v36, 0, v38
	v_max_f32_e32 v35, 0, v39
	v_mul_f32_e32 v35, v35, v77
	v_fmac_f32_e32 v35, v36, v76
	v_max_f32_e32 v36, 0, v40
	v_fmac_f32_e32 v35, v36, v81
	v_max_f32_e32 v36, 0, v41
	v_fmac_f32_e32 v35, v36, v80
	v_max_f32_e32 v37, 0, v42
	v_max_f32_e32 v36, 0, v43
	v_mul_f32_e32 v36, v36, v77
	v_fmac_f32_e32 v36, v37, v76
	v_max_f32_e32 v37, 0, v44
	v_fmac_f32_e32 v36, v37, v81
	v_max_f32_e32 v37, 0, v45
	v_fmac_f32_e32 v36, v37, v80
	v_max_f32_e32 v38, 0, v46
	v_max_f32_e32 v37, 0, v47
	v_mul_f32_e32 v37, v37, v77
	v_fmac_f32_e32 v37, v38, v76
	v_max_f32_e32 v38, 0, v48
	v_fmac_f32_e32 v37, v38, v81
	v_max_f32_e32 v38, 0, v49
	v_fmac_f32_e32 v37, v38, v80
	v_permlane32_swap_b32_e32 v34, v36
	s_nop 0
	v_permlane32_swap_b32_e32 v35, v37
	s_and_saveexec_b64 s[4:5], vcc
	s_cbranch_execz .LBB0_731
	v_add_f32_e32 v35, v35, v37
	v_add_f32_e32 v34, v34, v36
	v_cndmask_b32_e64 v36, v34, v35, s[6:7]
	ds_bpermute_b32 v36, v130, v36
	v_cndmask_b32_e64 v34, v35, v34, s[6:7]
	s_waitcnt lgkmcnt(0)
	v_add_f32_e32 v34, v34, v36
	v_mul_f32_e32 v67, v89, v34
; #define LAS __attribute__((address_space(3)))
; __device__ __forceinline__ f32x4 mfma16(bf16x8 a, bf16x8 b, f32x4 c) { return __builtin_amdgcn_mfma_f32_16x16x32_bf16(a, b, c, 0, 0, 0); }
; __device__ __forceinline__ void att_unit(LAS unsigned char* lds, const bf16* P, const bf16* AKV, const bf16* IKC, bf16* ACAT, const float* aqg, const float* ssq_ak, const float* ssq_ik, int b, int qg, int tid) {
;     ...
;                 for (int r4 = 0; r4 < 4; ++r4) {
;                     float pt[2][4];
; #pragma unroll
;                     for (int q4 = 0; q4 < 4; ++q4) {
;                         const LAS unsigned char* kp = IKc + (64 * r4 + 16 * q4 + fr) * 144 + fq * 16;
;                         const bf16x8 K0 = *(const LAS bf16x8*)kp, K1 = *(const LAS bf16x8*)(kp + 64);
; #pragma unroll
;                         for (int q = 0; q < 2; ++q) {
;                             f32x4 a = (f32x4){0.f, 0.f, 0.f, 0.f};
;                             a = mfma16(Qi[q][0], K0, a); a = mfma16(Qi[q][1], K1, a);
;                             pt[q][q4] = fmaxf(a[0], 0.f) * wv[q][0] + fmaxf(a[1], 0.f) * wv[q][1] + fmaxf(a[2], 0.f) * wv[q][2] + fmaxf(a[3], 0.f) * wv[q][3];
;                         }
;                     }
;                     const int rr = 4 * tile + r4;
;                     const float rscale = rsqrtf((rc[r4].x + rc[r4].y) * (1.f / 64.f) + EPS);
;                     const bool live = 64 * rr + lane < L;
; #pragma unroll
;                     for (int q = 0; q < 2; ++q) {
;                         float hx; const float A = half_sum32(pt[q][0], pt[q][2], hx), B = half_sum32(pt[q][1], pt[q][3], hx);
;                         const bool odd = fq & 1;
;                         const float send = odd ? A : B, keep = odd ? B : A;
;                         const float sc = live ? (keep + __shfl_xor(send, 16)) * rscale : -INFINITY;
;                         const unsigned bts = __float_as_uint(sc);
;                         uk[q][rr] = bts ^ ((unsigned)((int)bts >> 31) | 0x80000000u);
;                     }
.LBB0_731:
	s_or_b64 exec, exec, s[4:5]
	ds_read_b128 v[34:37], v131 offset:46080
	ds_read_b128 v[38:41], v131 offset:46144
	ds_read_b128 v[46:49], v131 offset:48384
	ds_read_b128 v[102:105], v131 offset:48448
	s_waitcnt vmcnt(2)
	v_add_f32_e32 v98, v98, v99
	v_fmamk_f32 v98, v98, 0x3c800000, v222
	s_waitcnt lgkmcnt(3)
	v_mfma_f32_16x16x32_bf16 v[42:45], v[14:17], v[34:37], 0
	v_mul_f32_e32 v99, 0x4b800000, v98
	v_cmp_gt_f32_e32 vcc, s18, v98
	s_waitcnt lgkmcnt(2)
	v_mfma_f32_16x16x32_bf16 v[42:45], v[10:13], v[38:41], v[42:45]
	v_cndmask_b32_e32 v98, v98, v99, vcc
	v_rsq_f32_e32 v98, v98
	v_mfma_f32_16x16x32_bf16 v[34:37], v[2:5], v[34:37], 0
	v_mfma_f32_16x16x32_bf16 v[34:37], v[6:9], v[38:41], v[34:37]
	s_nop 3
	v_max_f32_e32 v42, v42, v42
	v_max_f32_e32 v43, v43, v43
	v_max_f32_e32 v44, v44, v44
	v_max_f32_e32 v89, 0, v45
	v_max_f32_e32 v100, 0, v42
	v_max_f32_e32 v88, 0, v43
	v_max_f32_e32 v101, 0, v44
	s_waitcnt lgkmcnt(1)
	v_mfma_f32_16x16x32_bf16 v[42:45], v[14:17], v[46:49], 0
	v_mul_f32_e32 v88, v88, v75
	v_fmac_f32_e32 v88, v100, v74
	v_fmac_f32_e32 v88, v101, v79
	s_waitcnt lgkmcnt(0)
	v_mfma_f32_16x16x32_bf16 v[42:45], v[10:13], v[102:105], v[42:45]
	v_fmac_f32_e32 v88, v89, v78
	s_nop 5
	s_nop 0
	v_max_f32_e32 v38, 0, v43
	v_mul_f32_e32 v100, v38, v75
	v_mfma_f32_16x16x32_bf16 v[38:41], v[2:5], v[46:49], 0
	ds_read_b128 v[46:49], v131 offset:50688
	v_max_f32_e32 v42, 0, v42
	v_mfma_f32_16x16x32_bf16 v[38:41], v[6:9], v[102:105], v[38:41]
	ds_read_b128 v[102:105], v131 offset:50752
	v_fmac_f32_e32 v100, v42, v74
	s_waitcnt lgkmcnt(1)
	v_mfma_f32_16x16x32_bf16 v[106:109], v[14:17], v[46:49], 0
	v_max_f32_e32 v42, 0, v44
	v_fmac_f32_e32 v100, v42, v79
	s_waitcnt lgkmcnt(0)
	v_mfma_f32_16x16x32_bf16 v[106:109], v[10:13], v[102:105], v[106:109]
	v_max_f32_e32 v42, 0, v45
	v_fmac_f32_e32 v100, v42, v78
	s_nop 5
	v_max_f32_e32 v89, 0, v106
	v_max_f32_e32 v42, 0, v107
	v_mul_f32_e32 v101, v42, v75
	v_mfma_f32_16x16x32_bf16 v[42:45], v[2:5], v[46:49], 0
	ds_read_b128 v[46:49], v131 offset:52992
	v_fmac_f32_e32 v101, v89, v74
	v_mfma_f32_16x16x32_bf16 v[42:45], v[6:9], v[102:105], v[42:45]
	ds_read_b128 v[104:107], v131 offset:53056
	v_max_f32_e32 v89, 0, v108
	v_fmac_f32_e32 v101, v89, v79
	s_waitcnt lgkmcnt(1)
	v_mfma_f32_16x16x32_bf16 v[176:179], v[14:17], v[46:49], 0
	v_max_f32_e32 v89, 0, v109
	v_fmac_f32_e32 v101, v89, v78
	s_waitcnt lgkmcnt(0)
	v_mfma_f32_16x16x32_bf16 v[176:179], v[10:13], v[104:107], v[176:179]
	v_permlane32_swap_b32_e32 v88, v101
	v_mfma_f32_16x16x32_bf16 v[46:49], v[2:5], v[46:49], 0
	v_mfma_f32_16x16x32_bf16 v[46:49], v[6:9], v[104:107], v[46:49]
	s_nop 4
	v_max_f32_e32 v102, 0, v177
	v_max_f32_e32 v89, 0, v176
	v_mul_f32_e32 v102, v102, v75
	v_fmac_f32_e32 v102, v89, v74
	v_max_f32_e32 v89, 0, v178
	v_fmac_f32_e32 v102, v89, v79
	v_max_f32_e32 v89, 0, v179
	v_fmac_f32_e32 v102, v89, v78
	v_mul_f32_e32 v89, 0x45800000, v98
	v_cndmask_b32_e32 v99, v98, v89, vcc
	v_or_b32_e32 v89, 0x740, v124
	v_cmp_gt_u32_e32 vcc, s81, v89
	v_permlane32_swap_b32_e32 v100, v102
	v_mov_b32_e32 v98, 0xff800000
	v_mov_b32_e32 v89, 0xff800000
	s_and_saveexec_b64 s[4:5], vcc
	s_cbranch_execz .LBB0_733
	v_add_f32_e32 v89, v100, v102
	v_add_f32_e32 v88, v88, v101
	v_cndmask_b32_e64 v100, v88, v89, s[6:7]
	ds_bpermute_b32 v100, v130, v100
	v_cndmask_b32_e64 v88, v89, v88, s[6:7]
	s_waitcnt lgkmcnt(0)
	v_add_f32_e32 v88, v88, v100
	v_mul_f32_e32 v89, v99, v88
.LBB0_733:
	s_or_b64 exec, exec, s[4:5]
	v_max_f32_e32 v88, 0, v34
	v_max_f32_e32 v34, 0, v35
	v_mul_f32_e32 v34, v34, v77
	v_fmac_f32_e32 v34, v88, v76
	v_max_f32_e32 v35, 0, v36
	v_fmac_f32_e32 v34, v35, v81
	v_max_f32_e32 v35, 0, v37
	v_fmac_f32_e32 v34, v35, v80
	v_max_f32_e32 v36, 0, v38
	v_max_f32_e32 v35, 0, v39
	v_mul_f32_e32 v35, v35, v77
	v_fmac_f32_e32 v35, v36, v76
	v_max_f32_e32 v36, 0, v40
	v_fmac_f32_e32 v35, v36, v81
	v_max_f32_e32 v36, 0, v41
	v_fmac_f32_e32 v35, v36, v80
	v_max_f32_e32 v37, 0, v42
	v_max_f32_e32 v36, 0, v43
	v_mul_f32_e32 v36, v36, v77
	v_fmac_f32_e32 v36, v37, v76
	v_max_f32_e32 v37, 0, v44
	v_fmac_f32_e32 v36, v37, v81
	v_max_f32_e32 v37, 0, v45
	v_fmac_f32_e32 v36, v37, v80
	v_max_f32_e32 v38, 0, v46
	v_max_f32_e32 v37, 0, v47
	v_mul_f32_e32 v37, v37, v77
	v_fmac_f32_e32 v37, v38, v76
	v_max_f32_e32 v38, 0, v48
	v_fmac_f32_e32 v37, v38, v81
	v_max_f32_e32 v38, 0, v49
	v_fmac_f32_e32 v37, v38, v80
	v_permlane32_swap_b32_e32 v34, v36
	s_nop 0
	v_permlane32_swap_b32_e32 v35, v37
	s_and_saveexec_b64 s[4:5], vcc
	s_cbranch_execz .LBB0_735
	v_add_f32_e32 v35, v35, v37
	v_add_f32_e32 v34, v34, v36
	v_cndmask_b32_e64 v36, v34, v35, s[6:7]
	ds_bpermute_b32 v36, v130, v36
	v_cndmask_b32_e64 v34, v35, v34, s[6:7]
	s_waitcnt lgkmcnt(0)
	v_add_f32_e32 v34, v34, v36
	v_mul_f32_e32 v98, v99, v34
; #define LAS __attribute__((address_space(3)))
; __device__ __forceinline__ f32x4 mfma16(bf16x8 a, bf16x8 b, f32x4 c) { return __builtin_amdgcn_mfma_f32_16x16x32_bf16(a, b, c, 0, 0, 0); }
; __device__ __forceinline__ void att_unit(LAS unsigned char* lds, const bf16* P, const bf16* AKV, const bf16* IKC, bf16* ACAT, const float* aqg, const float* ssq_ak, const float* ssq_ik, int b, int qg, int tid) {
;     ...
;                 for (int r4 = 0; r4 < 4; ++r4) {
;                     float pt[2][4];
; #pragma unroll
;                     for (int q4 = 0; q4 < 4; ++q4) {
;                         const LAS unsigned char* kp = IKc + (64 * r4 + 16 * q4 + fr) * 144 + fq * 16;
;                         const bf16x8 K0 = *(const LAS bf16x8*)kp, K1 = *(const LAS bf16x8*)(kp + 64);
; #pragma unroll
;                         for (int q = 0; q < 2; ++q) {
;                             f32x4 a = (f32x4){0.f, 0.f, 0.f, 0.f};
;                             a = mfma16(Qi[q][0], K0, a); a = mfma16(Qi[q][1], K1, a);
;                             pt[q][q4] = fmaxf(a[0], 0.f) * wv[q][0] + fmaxf(a[1], 0.f) * wv[q][1] + fmaxf(a[2], 0.f) * wv[q][2] + fmaxf(a[3], 0.f) * wv[q][3];
;                         }
;                     }
;                     const int rr = 4 * tile + r4;
;                     const float rscale = rsqrtf((rc[r4].x + rc[r4].y) * (1.f / 64.f) + EPS);
;                     const bool live = 64 * rr + lane < L;
; #pragma unroll
;                     for (int q = 0; q < 2; ++q) {
;                         float hx; const float A = half_sum32(pt[q][0], pt[q][2], hx), B = half_sum32(pt[q][1], pt[q][3], hx);
;                         const bool odd = fq & 1;
;                         const float send = odd ? A : B, keep = odd ? B : A;
;                         const float sc = live ? (keep + __shfl_xor(send, 16)) * rscale : -INFINITY;
;                         const unsigned bts = __float_as_uint(sc);
;                         uk[q][rr] = bts ^ ((unsigned)((int)bts >> 31) | 0x80000000u);
;                     }
.LBB0_735:
	s_or_b64 exec, exec, s[4:5]
	ds_read_b128 v[34:37], v131 offset:55296
	ds_read_b128 v[38:41], v131 offset:55360
	ds_read_b128 v[46:49], v131 offset:57600
	ds_read_b128 v[102:105], v131 offset:57664
	s_waitcnt vmcnt(1)
	v_add_f32_e32 v96, v96, v97
	v_fmamk_f32 v96, v96, 0x3c800000, v222
	s_waitcnt lgkmcnt(3)
	v_mfma_f32_16x16x32_bf16 v[42:45], v[14:17], v[34:37], 0
	v_mul_f32_e32 v97, 0x4b800000, v96
	v_cmp_gt_f32_e32 vcc, s18, v96
	s_waitcnt lgkmcnt(2)
	v_mfma_f32_16x16x32_bf16 v[42:45], v[10:13], v[38:41], v[42:45]
	v_cndmask_b32_e32 v96, v96, v97, vcc
	v_rsq_f32_e32 v96, v96
	v_mfma_f32_16x16x32_bf16 v[34:37], v[2:5], v[34:37], 0
	v_mfma_f32_16x16x32_bf16 v[34:37], v[6:9], v[38:41], v[34:37]
	s_nop 3
	v_max_f32_e32 v42, v42, v42
	v_max_f32_e32 v43, v43, v43
	v_max_f32_e32 v44, v44, v44
	v_max_f32_e32 v88, 0, v45
	v_max_f32_e32 v100, 0, v42
	v_max_f32_e32 v99, 0, v43
	v_max_f32_e32 v101, 0, v44
	s_waitcnt lgkmcnt(1)
	v_mfma_f32_16x16x32_bf16 v[42:45], v[14:17], v[46:49], 0
	v_mul_f32_e32 v99, v99, v75
	v_fmac_f32_e32 v99, v100, v74
	v_fmac_f32_e32 v99, v101, v79
	s_waitcnt lgkmcnt(0)
	v_mfma_f32_16x16x32_bf16 v[42:45], v[10:13], v[102:105], v[42:45]
	v_fmac_f32_e32 v99, v88, v78
	s_nop 5
	s_nop 0
	v_max_f32_e32 v38, 0, v43
	v_mul_f32_e32 v100, v38, v75
	v_mfma_f32_16x16x32_bf16 v[38:41], v[2:5], v[46:49], 0
	ds_read_b128 v[46:49], v131 offset:59904
	v_max_f32_e32 v42, 0, v42
	v_mfma_f32_16x16x32_bf16 v[38:41], v[6:9], v[102:105], v[38:41]
	ds_read_b128 v[102:105], v131 offset:59968
	v_fmac_f32_e32 v100, v42, v74
	s_waitcnt lgkmcnt(1)
	v_mfma_f32_16x16x32_bf16 v[106:109], v[14:17], v[46:49], 0
	v_max_f32_e32 v42, 0, v44
	v_fmac_f32_e32 v100, v42, v79
	s_waitcnt lgkmcnt(0)
	v_mfma_f32_16x16x32_bf16 v[106:109], v[10:13], v[102:105], v[106:109]
	v_max_f32_e32 v42, 0, v45
	v_fmac_f32_e32 v100, v42, v78
	s_nop 5
	v_max_f32_e32 v88, 0, v106
	v_max_f32_e32 v42, 0, v107
	v_mul_f32_e32 v101, v42, v75
	v_mfma_f32_16x16x32_bf16 v[42:45], v[2:5], v[46:49], 0
	ds_read_b128 v[46:49], v131 offset:62208
	v_fmac_f32_e32 v101, v88, v74
	v_mfma_f32_16x16x32_bf16 v[42:45], v[6:9], v[102:105], v[42:45]
	ds_read_b128 v[104:107], v131 offset:62272
	v_max_f32_e32 v88, 0, v108
	v_fmac_f32_e32 v101, v88, v79
	s_waitcnt lgkmcnt(1)
	v_mfma_f32_16x16x32_bf16 v[176:179], v[14:17], v[46:49], 0
	v_max_f32_e32 v88, 0, v109
	v_fmac_f32_e32 v101, v88, v78
	s_waitcnt lgkmcnt(0)
	v_mfma_f32_16x16x32_bf16 v[176:179], v[10:13], v[104:107], v[176:179]
	v_permlane32_swap_b32_e32 v99, v101
	v_mfma_f32_16x16x32_bf16 v[46:49], v[2:5], v[46:49], 0
	v_mfma_f32_16x16x32_bf16 v[46:49], v[6:9], v[104:107], v[46:49]
	s_nop 4
	v_max_f32_e32 v102, 0, v177
	v_max_f32_e32 v88, 0, v176
	v_mul_f32_e32 v102, v102, v75
	v_fmac_f32_e32 v102, v88, v74
	v_max_f32_e32 v88, 0, v178
	v_fmac_f32_e32 v102, v88, v79
	v_max_f32_e32 v88, 0, v179
	v_fmac_f32_e32 v102, v88, v78
	v_mul_f32_e32 v88, 0x45800000, v96
	v_cndmask_b32_e32 v97, v96, v88, vcc
	v_or_b32_e32 v88, 0x780, v124
	v_cmp_gt_u32_e32 vcc, s81, v88
	v_permlane32_swap_b32_e32 v100, v102
	v_mov_b32_e32 v96, 0xff800000
	v_mov_b32_e32 v88, 0xff800000
	s_and_saveexec_b64 s[4:5], vcc
	s_cbranch_execz .LBB0_737
	v_add_f32_e32 v88, v100, v102
	v_add_f32_e32 v99, v99, v101
	v_cndmask_b32_e64 v100, v99, v88, s[6:7]
	ds_bpermute_b32 v100, v130, v100
	v_cndmask_b32_e64 v88, v88, v99, s[6:7]
	s_waitcnt lgkmcnt(0)
	v_add_f32_e32 v88, v88, v100
	v_mul_f32_e32 v88, v97, v88
.LBB0_737:
	s_or_b64 exec, exec, s[4:5]
	v_max_f32_e32 v99, 0, v34
	v_max_f32_e32 v34, 0, v35
	v_mul_f32_e32 v34, v34, v77
	v_fmac_f32_e32 v34, v99, v76
	v_max_f32_e32 v35, 0, v36
	v_fmac_f32_e32 v34, v35, v81
	v_max_f32_e32 v35, 0, v37
	v_fmac_f32_e32 v34, v35, v80
	v_max_f32_e32 v36, 0, v38
	v_max_f32_e32 v35, 0, v39
	v_mul_f32_e32 v35, v35, v77
	v_fmac_f32_e32 v35, v36, v76
	v_max_f32_e32 v36, 0, v40
	v_fmac_f32_e32 v35, v36, v81
	v_max_f32_e32 v36, 0, v41
	v_fmac_f32_e32 v35, v36, v80
	v_max_f32_e32 v37, 0, v42
	v_max_f32_e32 v36, 0, v43
	v_mul_f32_e32 v36, v36, v77
	v_fmac_f32_e32 v36, v37, v76
	v_max_f32_e32 v37, 0, v44
	v_fmac_f32_e32 v36, v37, v81
	v_max_f32_e32 v37, 0, v45
	v_fmac_f32_e32 v36, v37, v80
	v_max_f32_e32 v38, 0, v46
	v_max_f32_e32 v37, 0, v47
	v_mul_f32_e32 v37, v37, v77
	v_fmac_f32_e32 v37, v38, v76
	v_max_f32_e32 v38, 0, v48
	v_fmac_f32_e32 v37, v38, v81
	v_max_f32_e32 v38, 0, v49
	v_fmac_f32_e32 v37, v38, v80
	v_permlane32_swap_b32_e32 v34, v36
	s_nop 0
	v_permlane32_swap_b32_e32 v35, v37
	s_and_saveexec_b64 s[4:5], vcc
	s_cbranch_execz .LBB0_739
	v_add_f32_e32 v35, v35, v37
	v_add_f32_e32 v34, v34, v36
	v_cndmask_b32_e64 v36, v34, v35, s[6:7]
	ds_bpermute_b32 v36, v130, v36
	v_cndmask_b32_e64 v34, v35, v34, s[6:7]
	s_waitcnt lgkmcnt(0)
	v_add_f32_e32 v34, v34, v36
	v_mul_f32_e32 v96, v97, v34
; #define LAS __attribute__((address_space(3)))
; __device__ __forceinline__ f32x4 mfma16(bf16x8 a, bf16x8 b, f32x4 c) { return __builtin_amdgcn_mfma_f32_16x16x32_bf16(a, b, c, 0, 0, 0); }
; __device__ __forceinline__ void att_unit(LAS unsigned char* lds, const bf16* P, const bf16* AKV, const bf16* IKC, bf16* ACAT, const float* aqg, const float* ssq_ak, const float* ssq_ik, int b, int qg, int tid) {
;     ...
;                 for (int r4 = 0; r4 < 4; ++r4) {
;                     float pt[2][4];
; #pragma unroll
;                     for (int q4 = 0; q4 < 4; ++q4) {
;                         const LAS unsigned char* kp = IKc + (64 * r4 + 16 * q4 + fr) * 144 + fq * 16;
;                         const bf16x8 K0 = *(const LAS bf16x8*)kp, K1 = *(const LAS bf16x8*)(kp + 64);
; #pragma unroll
;                         for (int q = 0; q < 2; ++q) {
;                             f32x4 a = (f32x4){0.f, 0.f, 0.f, 0.f};
;                             a = mfma16(Qi[q][0], K0, a); a = mfma16(Qi[q][1], K1, a);
;                             pt[q][q4] = fmaxf(a[0], 0.f) * wv[q][0] + fmaxf(a[1], 0.f) * wv[q][1] + fmaxf(a[2], 0.f) * wv[q][2] + fmaxf(a[3], 0.f) * wv[q][3];
;                         }
;                     }
;                     const int rr = 4 * tile + r4;
;                     const float rscale = rsqrtf((rc[r4].x + rc[r4].y) * (1.f / 64.f) + EPS);
;                     const bool live = 64 * rr + lane < L;
; #pragma unroll
;                     for (int q = 0; q < 2; ++q) {
;                         float hx; const float A = half_sum32(pt[q][0], pt[q][2], hx), B = half_sum32(pt[q][1], pt[q][3], hx);
;                         const bool odd = fq & 1;
;                         const float send = odd ? A : B, keep = odd ? B : A;
;                         const float sc = live ? (keep + __shfl_xor(send, 16)) * rscale : -INFINITY;
;                         const unsigned bts = __float_as_uint(sc);
;                         uk[q][rr] = bts ^ ((unsigned)((int)bts >> 31) | 0x80000000u);
;                     }
.LBB0_739:
	s_or_b64 exec, exec, s[4:5]
	ds_read_b128 v[34:37], v131 offset:64512
	ds_read_b128 v[38:41], v131 offset:64576
	s_waitcnt lgkmcnt(1)
	v_mfma_f32_16x16x32_bf16 v[42:45], v[14:17], v[34:37], 0
	s_waitcnt lgkmcnt(0)
	v_mfma_f32_16x16x32_bf16 v[42:45], v[10:13], v[38:41], v[42:45]
	v_mfma_f32_16x16x32_bf16 v[34:37], v[2:5], v[34:37], 0
	v_mfma_f32_16x16x32_bf16 v[34:37], v[6:9], v[38:41], v[34:37]
	s_nop 5
	v_max_f32_e32 v43, 0, v43
	v_max_f32_e32 v42, 0, v42
	v_mul_f32_e32 v46, v43, v75
	v_fmac_f32_e32 v46, v42, v74
	v_max_f32_e32 v42, 0, v44
	v_fmac_f32_e32 v46, v42, v79
	v_max_f32_e32 v42, 0, v45
	v_fmac_f32_e32 v46, v42, v78
	ds_read_b128 v[38:41], v152 offset:29952
	ds_read_b128 v[42:45], v152 offset:30016
	s_waitcnt lgkmcnt(1)
	v_mfma_f32_16x16x32_bf16 v[100:103], v[14:17], v[38:41], 0
	s_waitcnt lgkmcnt(0)
	v_mfma_f32_16x16x32_bf16 v[100:103], v[10:13], v[42:45], v[100:103]
	v_mfma_f32_16x16x32_bf16 v[38:41], v[2:5], v[38:41], 0
	v_mfma_f32_16x16x32_bf16 v[38:41], v[6:9], v[42:45], v[38:41]
	s_nop 5
	v_max_f32_e32 v48, 0, v100
	v_max_f32_e32 v47, 0, v101
	v_mul_f32_e32 v47, v47, v75
	v_fmac_f32_e32 v47, v48, v74
	v_max_f32_e32 v48, 0, v102
	v_fmac_f32_e32 v47, v48, v79
	v_max_f32_e32 v48, 0, v103
	ds_read_b128 v[42:45], v152 offset:32256
	ds_read_b128 v[100:103], v152 offset:32320
	s_waitcnt lgkmcnt(1)
	v_mfma_f32_16x16x32_bf16 v[104:107], v[14:17], v[42:45], 0
	v_fmac_f32_e32 v47, v48, v78
	s_waitcnt lgkmcnt(0)
	v_mfma_f32_16x16x32_bf16 v[104:107], v[10:13], v[100:103], v[104:107]
	v_mfma_f32_16x16x32_bf16 v[42:45], v[2:5], v[42:45], 0
	v_mfma_f32_16x16x32_bf16 v[42:45], v[6:9], v[100:103], v[42:45]
	s_nop 5
	v_max_f32_e32 v49, 0, v104
	v_max_f32_e32 v48, 0, v105
	v_mul_f32_e32 v48, v48, v75
	v_fmac_f32_e32 v48, v49, v74
	v_max_f32_e32 v49, 0, v106
	v_fmac_f32_e32 v48, v49, v79
	v_max_f32_e32 v49, 0, v107
	ds_read_b128 v[100:103], v152 offset:34560
	ds_read_b128 v[104:107], v152 offset:34624
	s_waitcnt lgkmcnt(1)
	v_mfma_f32_16x16x32_bf16 v[14:17], v[14:17], v[100:103], 0
	v_fmac_f32_e32 v48, v49, v78
	s_nop 1
	v_permlane32_swap_b32_e32 v46, v48
	v_mfma_f32_16x16x32_bf16 v[2:5], v[2:5], v[100:103], 0
	s_waitcnt lgkmcnt(0)
	v_mfma_f32_16x16x32_bf16 v[10:13], v[10:13], v[104:107], v[14:17]
	v_mfma_f32_16x16x32_bf16 v[2:5], v[6:9], v[104:107], v[2:5]
	s_waitcnt vmcnt(0)
	v_add_f32_e32 v6, v90, v91
	v_fmamk_f32 v6, v6, 0x3c800000, v222
	s_nop 3
	v_cmp_gt_f32_e32 vcc, s18, v6
	v_mul_f32_e32 v7, 0x4b800000, v6
	v_max_f32_e32 v14, 0, v10
	v_cndmask_b32_e32 v6, v6, v7, vcc
	v_max_f32_e32 v10, 0, v11
	v_rsq_f32_e32 v6, v6
	v_mul_f32_e32 v10, v10, v75
	v_fmac_f32_e32 v10, v14, v74
	v_max_f32_e32 v11, 0, v12
	v_fmac_f32_e32 v10, v11, v79
	v_max_f32_e32 v11, 0, v13
	v_mul_f32_e32 v7, 0x45800000, v6
	v_fmac_f32_e32 v10, v11, v78
	v_cndmask_b32_e32 v8, v6, v7, vcc
	v_or_b32_e32 v6, 0x7c0, v124
	v_cmp_gt_u32_e32 vcc, s81, v6
	v_permlane32_swap_b32_e32 v47, v10
	v_mov_b32_e32 v7, 0xff800000
	v_mov_b32_e32 v6, 0xff800000
	s_and_saveexec_b64 s[4:5], vcc
	s_cbranch_execz .LBB0_741
	v_add_f32_e32 v6, v47, v10
	v_add_f32_e32 v9, v46, v48
	v_cndmask_b32_e64 v10, v9, v6, s[6:7]
	ds_bpermute_b32 v10, v130, v10
	v_cndmask_b32_e64 v6, v6, v9, s[6:7]
	s_waitcnt lgkmcnt(0)
	v_add_f32_e32 v6, v6, v10
	v_mul_f32_e32 v6, v8, v6
.LBB0_741:
	s_or_b64 exec, exec, s[4:5]
	v_max_f32_e32 v10, 0, v34
	v_max_f32_e32 v9, 0, v35
	v_mul_f32_e32 v9, v9, v77
	v_fmac_f32_e32 v9, v10, v76
	v_max_f32_e32 v10, 0, v36
	v_fmac_f32_e32 v9, v10, v81
	v_max_f32_e32 v10, 0, v37
	v_fmac_f32_e32 v9, v10, v80
	v_max_f32_e32 v11, 0, v38
	v_max_f32_e32 v10, 0, v39
	v_mul_f32_e32 v10, v10, v77
	v_fmac_f32_e32 v10, v11, v76
	v_max_f32_e32 v11, 0, v40
	v_fmac_f32_e32 v10, v11, v81
	v_max_f32_e32 v11, 0, v41
	v_fmac_f32_e32 v10, v11, v80
	v_max_f32_e32 v12, 0, v42
	v_max_f32_e32 v11, 0, v43
	v_mul_f32_e32 v11, v11, v77
	v_fmac_f32_e32 v11, v12, v76
	v_max_f32_e32 v12, 0, v44
	v_fmac_f32_e32 v11, v12, v81
	v_max_f32_e32 v12, 0, v45
	v_fmac_f32_e32 v11, v12, v80
	v_max_f32_e32 v12, 0, v2
	v_max_f32_e32 v2, 0, v3
	v_mul_f32_e32 v2, v2, v77
	v_fmac_f32_e32 v2, v12, v76
	v_max_f32_e32 v3, 0, v4
	v_fmac_f32_e32 v2, v3, v81
	v_max_f32_e32 v3, 0, v5
	v_fmac_f32_e32 v2, v3, v80
	v_permlane32_swap_b32_e32 v9, v11
	s_nop 0
	v_permlane32_swap_b32_e32 v10, v2
	s_and_saveexec_b64 s[4:5], vcc
	s_cbranch_execz .LBB0_743
	v_add_f32_e32 v2, v10, v2
	v_add_f32_e32 v3, v9, v11
	v_cndmask_b32_e64 v4, v3, v2, s[6:7]
	ds_bpermute_b32 v4, v130, v4
	v_cndmask_b32_e64 v2, v2, v3, s[6:7]
	s_waitcnt lgkmcnt(0)
	v_add_f32_e32 v2, v2, v4
	v_mul_f32_e32 v7, v8, v2

; template <class Epi, class Sched, bool ALIGN_EPI = false, bool SP2 = false>
; __device__ __forceinline__ void gemm_phase(PG8_LAS unsigned char* lds, const Gemm g, const Sched& S, const Epi& E) {
;     ...
;         const char* nA = has_next ? (const char*)g.A + (size_t)nxt.pm * tstep : cA; const char* nB = has_next ? (const char*)g.Bt + (size_t)nxt.pn * tstep : cB;
;         for (int t = 0; t < nt; t += 2) {
;             const bool last = (t == nt - 2);
;             const char* a1 = cA + (size_t)(t + 1) * kstep;
;             const char* a2 = last ? nA : cA + (size_t)(t + 2) * kstep; const char* b2 = last ? nB : cB + (size_t)(t + 2) * kstep;
;             const char* a3 = a2 + kstep; const char* b3 = b2 + kstep;
;     ...
; #pragma unroll
;         for (int a = 0; a < 2; ++a)
; #pragma unroll
;             for (int b = 0; b < 2; ++b)
; #pragma unroll
;                 for (int m = 0; m < 4; ++m)
; #pragma unroll
;                     for (int n = 0; n < 2; ++n) acc[a][b][m][n] = (f32x4){0.f, 0.f, 0.f, 0.f};
;         cur = nxt; cA = nA; cB = nB; ++ui;
.LBB0_1112:
	s_ashr_i32 s13, s12, 31
	s_lshl_b64 s[16:17], s[12:13], 20
	s_add_u32 s16, s28, s16
	s_addc_u32 s17, s29, s17
	s_and_b64 s[20:21], s[18:19], exec
	s_cselect_b32 s13, s17, s25
	s_cselect_b32 s43, s16, s24
	s_ashr_i32 s15, s14, 31
	s_lshl_b64 s[20:21], s[14:15], 20
	s_add_u32 s20, s30, s20
	s_addc_u32 s21, s31, s21
	s_and_b64 s[26:27], s[18:19], exec
	s_cselect_b32 s15, s21, s23
	s_cselect_b32 s44, s20, s22
	s_add_u32 s45, s22, 0x100
	s_addc_u32 s46, s23, 0
	s_add_u32 s22, s24, 0x80080
	v_mov_b32_e32 v2, 0
	s_addc_u32 s23, s25, 0
	s_mov_b32 s47, -2
	v_mov_b32_e32 v3, v2
	v_mov_b32_e32 v4, v2
	v_mov_b32_e32 v5, v2
	v_mov_b32_e32 v6, v2
	v_mov_b32_e32 v7, v2
	v_mov_b32_e32 v8, v2
	v_mov_b32_e32 v9, v2
	v_mov_b32_e32 v18, v2
	v_mov_b32_e32 v19, v2
	v_mov_b32_e32 v20, v2
	v_mov_b32_e32 v21, v2
	v_mov_b32_e32 v22, v2
	v_mov_b32_e32 v23, v2
	v_mov_b32_e32 v24, v2
	v_mov_b32_e32 v25, v2
	v_mov_b32_e32 v34, v2
	v_mov_b32_e32 v35, v2
	v_mov_b32_e32 v36, v2
	v_mov_b32_e32 v37, v2
	v_mov_b32_e32 v38, v2
	v_mov_b32_e32 v39, v2
	v_mov_b32_e32 v40, v2
	v_mov_b32_e32 v41, v2
	v_mov_b32_e32 v50, v2
	v_mov_b32_e32 v51, v2
	v_mov_b32_e32 v52, v2
	v_mov_b32_e32 v53, v2
	v_mov_b32_e32 v54, v2
	v_mov_b32_e32 v55, v2
	v_mov_b32_e32 v56, v2
	v_mov_b32_e32 v57, v2
	v_mov_b32_e32 v10, v2
	v_mov_b32_e32 v11, v2
	v_mov_b32_e32 v12, v2
	v_mov_b32_e32 v13, v2
	v_mov_b32_e32 v14, v2
	v_mov_b32_e32 v15, v2
	v_mov_b32_e32 v16, v2
	v_mov_b32_e32 v17, v2
	v_mov_b32_e32 v26, v2
	v_mov_b32_e32 v27, v2
	v_mov_b32_e32 v28, v2
	v_mov_b32_e32 v29, v2
	v_mov_b32_e32 v30, v2
	v_mov_b32_e32 v31, v2
	v_mov_b32_e32 v32, v2
	v_mov_b32_e32 v33, v2
	v_mov_b32_e32 v42, v2
	v_mov_b32_e32 v43, v2
	v_mov_b32_e32 v44, v2
	v_mov_b32_e32 v45, v2
	v_mov_b32_e32 v46, v2
	v_mov_b32_e32 v47, v2
	v_mov_b32_e32 v48, v2
	v_mov_b32_e32 v49, v2
	v_mov_b32_e32 v58, v2
	v_mov_b32_e32 v59, v2
	v_mov_b32_e32 v60, v2
	v_mov_b32_e32 v61, v2
	v_mov_b32_e32 v62, v2
	v_mov_b32_e32 v63, v2
	v_mov_b32_e32 v64, v2
	v_mov_b32_e32 v65, v2
	v_mov_b32_e32 v66, v2
	v_mov_b32_e32 v67, v2
	v_mov_b32_e32 v68, v2
	v_mov_b32_e32 v69, v2
	v_mov_b32_e32 v70, v2
	v_mov_b32_e32 v71, v2
	v_mov_b32_e32 v72, v2
	v_mov_b32_e32 v73, v2
	v_mov_b32_e32 v82, v2
	v_mov_b32_e32 v83, v2
	v_mov_b32_e32 v84, v2
	v_mov_b32_e32 v85, v2
	v_mov_b32_e32 v86, v2
	v_mov_b32_e32 v87, v2
	v_mov_b32_e32 v88, v2
	v_mov_b32_e32 v89, v2
	v_mov_b32_e32 v98, v2
	v_mov_b32_e32 v99, v2
	v_mov_b32_e32 v100, v2
	v_mov_b32_e32 v101, v2
	v_mov_b32_e32 v102, v2
	v_mov_b32_e32 v103, v2
	v_mov_b32_e32 v104, v2
	v_mov_b32_e32 v105, v2
	v_mov_b32_e32 v114, v2
	v_mov_b32_e32 v115, v2
	v_mov_b32_e32 v116, v2
	v_mov_b32_e32 v117, v2
	v_mov_b32_e32 v118, v2
	v_mov_b32_e32 v119, v2
	v_mov_b32_e32 v120, v2
	v_mov_b32_e32 v121, v2
	v_mov_b32_e32 v74, v2
	v_mov_b32_e32 v75, v2
	v_mov_b32_e32 v76, v2
	v_mov_b32_e32 v77, v2
	v_mov_b32_e32 v78, v2
	v_mov_b32_e32 v79, v2
	v_mov_b32_e32 v80, v2
	v_mov_b32_e32 v81, v2
	v_mov_b32_e32 v90, v2
	v_mov_b32_e32 v91, v2
	v_mov_b32_e32 v92, v2
	v_mov_b32_e32 v93, v2
	v_mov_b32_e32 v94, v2
	v_mov_b32_e32 v95, v2
	v_mov_b32_e32 v96, v2
	v_mov_b32_e32 v97, v2
	v_mov_b32_e32 v106, v2
	v_mov_b32_e32 v107, v2
	v_mov_b32_e32 v108, v2
	v_mov_b32_e32 v109, v2
	v_mov_b32_e32 v110, v2
	v_mov_b32_e32 v111, v2
	v_mov_b32_e32 v112, v2
	v_mov_b32_e32 v113, v2
	v_mov_b32_e32 v122, v2
	v_mov_b32_e32 v123, v2
	v_mov_b32_e32 v124, v2
	v_mov_b32_e32 v125, v2
	v_mov_b32_e32 v126, v2
	v_mov_b32_e32 v127, v2
	v_mov_b32_e32 v128, v2
	v_mov_b32_e32 v129, v2
	s_mov_b64 s[52:53], 0x80
	.p2align 8

; template <class Epi, class Sched, bool ALIGN_EPI = false, bool SP2 = false>
; __device__ __forceinline__ void gemm_phase(PG8_LAS unsigned char* lds, const Gemm g, const Sched& S, const Epi& E) {
;     ...
;         const char* nA = has_next ? (const char*)g.A + (size_t)nxt.pm * tstep : cA; const char* nB = has_next ? (const char*)g.Bt + (size_t)nxt.pn * tstep : cB;
;         for (int t = 0; t < nt; t += 2) {
;             const bool last = (t == nt - 2);
;             const char* a1 = cA + (size_t)(t + 1) * kstep;
;             const char* a2 = last ? nA : cA + (size_t)(t + 2) * kstep; const char* b2 = last ? nB : cB + (size_t)(t + 2) * kstep;
;             const char* a3 = a2 + kstep; const char* b3 = b2 + kstep;
;     ...
; #pragma unroll
;         for (int a = 0; a < 2; ++a)
; #pragma unroll
;             for (int b = 0; b < 2; ++b)
; #pragma unroll
;                 for (int m = 0; m < 4; ++m)
; #pragma unroll
;                     for (int n = 0; n < 2; ++n) acc[a][b][m][n] = (f32x4){0.f, 0.f, 0.f, 0.f};
;         cur = nxt; cA = nA; cB = nB; ++ui;
.LBB0_1181:
	s_ashr_i32 s21, s20, 31
	s_lshl_b64 s[22:23], s[20:21], 20
	s_add_u32 s22, s30, s22
	s_addc_u32 s23, s31, s23
	s_and_b64 s[24:25], s[2:3], exec
	s_cselect_b32 s21, s23, s27
	s_cselect_b32 s46, s22, s26
	s_ashr_i32 s19, s18, 31
	s_lshl_b64 s[24:25], s[18:19], 20
	s_add_u32 s24, s33, s24
	s_addc_u32 s25, s34, s25
	s_and_b64 s[28:29], s[2:3], exec
	s_cselect_b32 s19, s25, s5
	s_cselect_b32 s47, s24, s4
	s_add_u32 s48, s4, 0x100
	s_addc_u32 s49, s5, 0
	s_add_u32 s4, s26, 0x80080
	v_mov_b32_e32 v2, 0
	s_addc_u32 s5, s27, 0
	s_mov_b32 s50, -2
	v_mov_b32_e32 v3, v2
	v_mov_b32_e32 v4, v2
	v_mov_b32_e32 v5, v2
	v_mov_b32_e32 v6, v2
	v_mov_b32_e32 v7, v2
	v_mov_b32_e32 v8, v2
	v_mov_b32_e32 v9, v2
	v_mov_b32_e32 v18, v2
	v_mov_b32_e32 v19, v2
	v_mov_b32_e32 v20, v2
	v_mov_b32_e32 v21, v2
	v_mov_b32_e32 v22, v2
	v_mov_b32_e32 v23, v2
	v_mov_b32_e32 v24, v2
	v_mov_b32_e32 v25, v2
	v_mov_b32_e32 v34, v2
	v_mov_b32_e32 v35, v2
	v_mov_b32_e32 v36, v2
	v_mov_b32_e32 v37, v2
	v_mov_b32_e32 v38, v2
	v_mov_b32_e32 v39, v2
	v_mov_b32_e32 v40, v2
	v_mov_b32_e32 v41, v2
	v_mov_b32_e32 v50, v2
	v_mov_b32_e32 v51, v2
	v_mov_b32_e32 v52, v2
	v_mov_b32_e32 v53, v2
	v_mov_b32_e32 v54, v2
	v_mov_b32_e32 v55, v2
	v_mov_b32_e32 v56, v2
	v_mov_b32_e32 v57, v2
	v_mov_b32_e32 v10, v2
	v_mov_b32_e32 v11, v2
	v_mov_b32_e32 v12, v2
	v_mov_b32_e32 v13, v2
	v_mov_b32_e32 v14, v2
	v_mov_b32_e32 v15, v2
	v_mov_b32_e32 v16, v2
	v_mov_b32_e32 v17, v2
	v_mov_b32_e32 v26, v2
	v_mov_b32_e32 v27, v2
	v_mov_b32_e32 v28, v2
	v_mov_b32_e32 v29, v2
	v_mov_b32_e32 v30, v2
	v_mov_b32_e32 v31, v2
	v_mov_b32_e32 v32, v2
	v_mov_b32_e32 v33, v2
	v_mov_b32_e32 v42, v2
	v_mov_b32_e32 v43, v2
	v_mov_b32_e32 v44, v2
	v_mov_b32_e32 v45, v2
	v_mov_b32_e32 v46, v2
	v_mov_b32_e32 v47, v2
	v_mov_b32_e32 v48, v2
	v_mov_b32_e32 v49, v2
	v_mov_b32_e32 v58, v2
	v_mov_b32_e32 v59, v2
	v_mov_b32_e32 v60, v2
	v_mov_b32_e32 v61, v2
	v_mov_b32_e32 v62, v2
	v_mov_b32_e32 v63, v2
	v_mov_b32_e32 v64, v2
	v_mov_b32_e32 v65, v2
	v_mov_b32_e32 v66, v2
	v_mov_b32_e32 v67, v2
	v_mov_b32_e32 v68, v2
	v_mov_b32_e32 v69, v2
	v_mov_b32_e32 v70, v2
	v_mov_b32_e32 v71, v2
	v_mov_b32_e32 v72, v2
	v_mov_b32_e32 v73, v2
	v_mov_b32_e32 v82, v2
	v_mov_b32_e32 v83, v2
	v_mov_b32_e32 v84, v2
	v_mov_b32_e32 v85, v2
	v_mov_b32_e32 v86, v2
	v_mov_b32_e32 v87, v2
	v_mov_b32_e32 v88, v2
	v_mov_b32_e32 v89, v2
	v_mov_b32_e32 v98, v2
	v_mov_b32_e32 v99, v2
	v_mov_b32_e32 v100, v2
	v_mov_b32_e32 v101, v2
	v_mov_b32_e32 v102, v2
	v_mov_b32_e32 v103, v2
	v_mov_b32_e32 v104, v2
	v_mov_b32_e32 v105, v2
	v_mov_b32_e32 v114, v2
	v_mov_b32_e32 v115, v2
	v_mov_b32_e32 v116, v2
	v_mov_b32_e32 v117, v2
	v_mov_b32_e32 v118, v2
	v_mov_b32_e32 v119, v2
	v_mov_b32_e32 v120, v2
	v_mov_b32_e32 v121, v2
	v_mov_b32_e32 v74, v2
	v_mov_b32_e32 v75, v2
	v_mov_b32_e32 v76, v2
	v_mov_b32_e32 v77, v2
	v_mov_b32_e32 v78, v2
	v_mov_b32_e32 v79, v2
	v_mov_b32_e32 v80, v2
	v_mov_b32_e32 v81, v2
	v_mov_b32_e32 v90, v2
	v_mov_b32_e32 v91, v2
	v_mov_b32_e32 v92, v2
	v_mov_b32_e32 v93, v2
	v_mov_b32_e32 v94, v2
	v_mov_b32_e32 v95, v2
	v_mov_b32_e32 v96, v2
	v_mov_b32_e32 v97, v2
	v_mov_b32_e32 v106, v2
	v_mov_b32_e32 v107, v2
	v_mov_b32_e32 v108, v2
	v_mov_b32_e32 v109, v2
	v_mov_b32_e32 v110, v2
	v_mov_b32_e32 v111, v2
	v_mov_b32_e32 v112, v2
	v_mov_b32_e32 v113, v2
	v_mov_b32_e32 v130, v2
	v_mov_b32_e32 v131, v2
	v_mov_b32_e32 v132, v2
	v_mov_b32_e32 v133, v2
	v_mov_b32_e32 v134, v2
	v_mov_b32_e32 v135, v2
	v_mov_b32_e32 v136, v2
	v_mov_b32_e32 v137, v2
	s_mov_b64 s[56:57], 0x80
	.p2align 8
